# mid() rewritten (one-round-trip gate loads) + K-loop LDS-DMA in SGPR-base+VGPR-offset form
# speedup vs baseline: 1.0166x; 1.0166x over previous
; #define PG8_STAGE(bufoff, gbase, voff) do { _Pragma("unroll") for (int _i = 0; _i < 2; ++_i) \
;         __builtin_amdgcn_global_load_lds((const unsigned*)((const char*)(gbase) + (voff)[_i]), (LAS unsigned*)(lds + (bufoff) + ldsw + _i * 8192), 16, 0, 0); } while (0)
; #define PG8_LDA(dst, b, h) do { _Pragma("unroll") for (int m = 0; m < 4; ++m) _Pragma("unroll") for (int k = 0; k < 2; ++k) dst[m][k] = *(const LAS bf16x8*)(lds + PG8_SA(b, h) + aoff + m * 2048 + k * 1024); } while (0)
; #define PG8_WAIT_V(n) asm volatile("s_waitcnt vmcnt(" #n ")" ::: "memory")
; #define PG8_BAR __builtin_amdgcn_s_barrier()
; template <class Epi, class Sched>
; __device__ __forceinline__ void gemm_phase(LAS unsigned char* lds_in, const int lda, const int ldb, const Sched& S, const Epi& E, const int WID) {
;     ...
;         for (int t = tb; t < te; t += 2) {
;             const bool last = (t == nt - 2);
;             const char* a1 = cA + (size_t)(t + 1) * kstep;
;             const char* a2 = last ? nA : cA + (size_t)(t + 2) * kstep; const char* b2 = last ? nB : cB + (size_t)(t + 2) * kstep;
;             const char* a3 = a2 + kstep; const char* b3 = b2 + kstep;
;             PG8_LDB(B0, 0, 0); PG8_SCHED; PG8_LDA(At, 0, 0); PG8_STAGE(PG8_SA(1, 1), a1 + hstepA, voffA);
;             PG8_WAIT_L(8); PG8_BAR; PG8_WAIT_L(0); PG8_MMA(0, 0, At, B0); PG8_BAR; PG8_SCHED;
;             PG8_LDB(B1, 0, 1); PG8_STAGE(PG8_SB(0, 0), b2, voffB);
;             PG8_BAR; PG8_WAIT_L(0); PG8_MMA(0, 1, At, B1); PG8_BAR;
;             PG8_LDA(At, 0, 1); PG8_STAGE(PG8_SA(0, 0), a2, voffA);
;             PG8_BAR; PG8_WAIT_L(0); PG8_MMA(1, 0, At, B0); PG8_BAR; PG8_SCHED;
;             PG8_STAGE(PG8_SB(0, 1), b2 + hstepB, voffB);
;             PG8_WAIT_V(6); PG8_BAR; PG8_MMA(1, 1, At, B1); PG8_BAR;
;             PG8_LDB(B0, 1, 0); PG8_SCHED; PG8_LDA(At, 1, 0); PG8_STAGE(PG8_SA(0, 1), a2 + hstepA, voffA);
;             PG8_WAIT_L(8); PG8_BAR; PG8_WAIT_L(0); PG8_MMA(0, 0, At, B0); PG8_BAR; PG8_SCHED;
;             PG8_LDB(B1, 1, 1); PG8_STAGE(PG8_SB(1, 0), b3, voffB);
;             PG8_BAR; PG8_WAIT_L(0); PG8_MMA(0, 1, At, B1); PG8_BAR;
;             PG8_LDA(At, 1, 1); PG8_STAGE(PG8_SA(1, 0), a3, voffA);
;             PG8_BAR; PG8_WAIT_L(0); PG8_MMA(1, 0, At, B0); PG8_BAR; PG8_SCHED;
;             PG8_STAGE(PG8_SB(1, 1), b3 + hstepB, voffB);
;             PG8_WAIT_V(6); PG8_BAR; PG8_MMA(1, 1, At, B1); PG8_BAR;
.LBB0_151:
	ds_read_b128 v[66:69], v227
	ds_read_b128 v[70:73], v227 offset:1024
	ds_read_b128 v[82:85], v227 offset:2048
	ds_read_b128 v[94:97], v227 offset:3072
	s_add_u32 s20, s6, 0xffe00080
	s_addc_u32 s21, s7, -1
	s_cmpk_eq_i32 vcc_lo, 0x7c
	s_cselect_b32 s23, s17, s21
	s_cselect_b32 s22, s16, s20
	s_cselect_b32 s21, s19, s15
	s_cselect_b32 s20, s18, s5
	s_add_i32 m0, s50, 0xc000
	ds_read_b128 v[106:109], v228
	ds_read_b128 v[118:121], v228 offset:1024
	ds_read_b128 v[130:133], v228 offset:2048
	ds_read_b128 v[142:145], v228 offset:3072
	ds_read_b128 v[154:157], v228 offset:4096
	ds_read_b128 v[166:169], v228 offset:5120
	ds_read_b128 v[170:173], v228 offset:6144
	ds_read_b128 v[174:177], v228 offset:7168
	global_load_lds_dwordx4 v198, s[6:7]
	s_add_i32 m0, s50, 0xe000
	s_nop 0
	global_load_lds_dwordx4 v200, s[6:7]
	s_waitcnt lgkmcnt(8)
	s_barrier
	s_waitcnt lgkmcnt(0)
	s_setprio 1
	s_waitcnt lgkmcnt(0)
	v_mfma_f32_16x16x32_bf16 v[162:165], v[66:69], v[106:109], v[162:165]
	v_mfma_f32_16x16x32_bf16 v[158:161], v[82:85], v[106:109], v[158:161]
	v_mfma_f32_16x16x32_bf16 v[138:141], v[66:69], v[130:133], v[138:141]
	v_mfma_f32_16x16x32_bf16 v[134:137], v[82:85], v[130:133], v[134:137]
	v_mfma_f32_16x16x32_bf16 v[114:117], v[66:69], v[154:157], v[114:117]
	v_mfma_f32_16x16x32_bf16 v[110:113], v[82:85], v[154:157], v[110:113]
	v_mfma_f32_16x16x32_bf16 v[90:93], v[66:69], v[170:173], v[90:93]
	v_mfma_f32_16x16x32_bf16 v[86:89], v[82:85], v[170:173], v[86:89]
	v_mfma_f32_16x16x32_bf16 v[162:165], v[70:73], v[118:121], v[162:165]
	v_mfma_f32_16x16x32_bf16 v[158:161], v[94:97], v[118:121], v[158:161]
	v_mfma_f32_16x16x32_bf16 v[138:141], v[70:73], v[142:145], v[138:141]
	v_mfma_f32_16x16x32_bf16 v[134:137], v[94:97], v[142:145], v[134:137]
	v_mfma_f32_16x16x32_bf16 v[114:117], v[70:73], v[166:169], v[114:117]
	v_mfma_f32_16x16x32_bf16 v[110:113], v[94:97], v[166:169], v[110:113]
	v_mfma_f32_16x16x32_bf16 v[90:93], v[70:73], v[174:177], v[90:93]
	v_mfma_f32_16x16x32_bf16 v[86:89], v[94:97], v[174:177], v[86:89]
	s_setprio 0
	s_barrier
	s_mov_b32 m0, s48
	ds_read_b128 v[178:181], v229
	ds_read_b128 v[182:185], v229 offset:1024
	ds_read_b128 v[186:189], v229 offset:2048
	ds_read_b128 v[202:205], v229 offset:3072
	global_load_lds_dwordx4 v192, s[20:21]
	s_mov_b32 m0, s49
	s_nop 0
	global_load_lds_dwordx4 v196, s[20:21]
	s_barrier
	s_waitcnt lgkmcnt(0)
	s_setprio 1
	s_waitcnt lgkmcnt(0)
	v_mfma_f32_16x16x32_bf16 v[150:153], v[178:181], v[106:109], v[150:153]
	v_mfma_f32_16x16x32_bf16 v[106:109], v[186:189], v[106:109], v[146:149]
	v_mfma_f32_16x16x32_bf16 v[122:125], v[186:189], v[130:133], v[122:125]
	v_mfma_f32_16x16x32_bf16 v[102:105], v[178:181], v[154:157], v[102:105]
	v_mfma_f32_16x16x32_bf16 v[98:101], v[186:189], v[154:157], v[98:101]
	v_mfma_f32_16x16x32_bf16 v[78:81], v[178:181], v[170:173], v[78:81]
	v_mfma_f32_16x16x32_bf16 v[74:77], v[186:189], v[170:173], v[74:77]
	v_mfma_f32_16x16x32_bf16 v[150:153], v[182:185], v[118:121], v[150:153]
	v_mfma_f32_16x16x32_bf16 v[106:109], v[202:205], v[118:121], v[106:109]
	v_mfma_f32_16x16x32_bf16 v[118:121], v[178:181], v[130:133], v[126:129]
	v_mfma_f32_16x16x32_bf16 v[122:125], v[202:205], v[142:145], v[122:125]
	v_mfma_f32_16x16x32_bf16 v[102:105], v[182:185], v[166:169], v[102:105]
	v_mfma_f32_16x16x32_bf16 v[98:101], v[202:205], v[166:169], v[98:101]
	v_mfma_f32_16x16x32_bf16 v[78:81], v[182:185], v[174:177], v[78:81]
	v_mfma_f32_16x16x32_bf16 v[74:77], v[202:205], v[174:177], v[74:77]
	v_mfma_f32_16x16x32_bf16 v[118:121], v[182:185], v[142:145], v[118:121]
	s_setprio 0
	s_mov_b32 m0, s50
	s_barrier
	ds_read_b128 v[126:129], v228 offset:16384
	ds_read_b128 v[130:133], v228 offset:17408
	ds_read_b128 v[142:145], v228 offset:18432
	ds_read_b128 v[146:149], v228 offset:19456
	ds_read_b128 v[154:157], v228 offset:20480
	ds_read_b128 v[166:169], v228 offset:21504
	ds_read_b128 v[170:173], v228 offset:22528
	ds_read_b128 v[174:177], v228 offset:23552
	global_load_lds_dwordx4 v190, s[22:23]
	s_mov_b32 m0, s51
	s_nop 0
	global_load_lds_dwordx4 v194, s[22:23]
	s_barrier
	s_waitcnt lgkmcnt(0)
	s_setprio 1
	s_waitcnt lgkmcnt(0)
	v_mfma_f32_16x16x32_bf16 v[62:65], v[66:69], v[126:129], v[62:65]
	v_mfma_f32_16x16x32_bf16 v[58:61], v[82:85], v[126:129], v[58:61]
	v_mfma_f32_16x16x32_bf16 v[46:49], v[66:69], v[142:145], v[46:49]
	v_mfma_f32_16x16x32_bf16 v[42:45], v[82:85], v[142:145], v[42:45]
	v_mfma_f32_16x16x32_bf16 v[30:33], v[66:69], v[154:157], v[30:33]
	v_mfma_f32_16x16x32_bf16 v[26:29], v[82:85], v[154:157], v[26:29]
	v_mfma_f32_16x16x32_bf16 v[14:17], v[66:69], v[170:173], v[14:17]
	v_mfma_f32_16x16x32_bf16 v[10:13], v[82:85], v[170:173], v[10:13]
	v_mfma_f32_16x16x32_bf16 v[62:65], v[70:73], v[130:133], v[62:65]
	v_mfma_f32_16x16x32_bf16 v[58:61], v[94:97], v[130:133], v[58:61]
	v_mfma_f32_16x16x32_bf16 v[46:49], v[70:73], v[146:149], v[46:49]
	v_mfma_f32_16x16x32_bf16 v[42:45], v[94:97], v[146:149], v[42:45]
	v_mfma_f32_16x16x32_bf16 v[30:33], v[70:73], v[166:169], v[30:33]
	v_mfma_f32_16x16x32_bf16 v[26:29], v[94:97], v[166:169], v[26:29]
	v_mfma_f32_16x16x32_bf16 v[14:17], v[70:73], v[174:177], v[14:17]
	v_mfma_f32_16x16x32_bf16 v[10:13], v[94:97], v[174:177], v[10:13]
	s_setprio 0
	s_barrier
	s_add_u32 s66, s20, 0x200000
	s_addc_u32 s67, s21, 0
	s_mov_b32 m0, s65
	s_nop 0
	global_load_lds_dwordx4 v192, s[66:67]
	s_mov_b32 m0, s70
	s_nop 0
	global_load_lds_dwordx4 v196, s[66:67]
	s_waitcnt vmcnt(6)
	s_barrier
; #define PG8_STAGE(bufoff, gbase, voff) do { _Pragma("unroll") for (int _i = 0; _i < 2; ++_i) \
;         __builtin_amdgcn_global_load_lds((const unsigned*)((const char*)(gbase) + (voff)[_i]), (LAS unsigned*)(lds + (bufoff) + ldsw + _i * 8192), 16, 0, 0); } while (0)
; #define PG8_LDA(dst, b, h) do { _Pragma("unroll") for (int m = 0; m < 4; ++m) _Pragma("unroll") for (int k = 0; k < 2; ++k) dst[m][k] = *(const LAS bf16x8*)(lds + PG8_SA(b, h) + aoff + m * 2048 + k * 1024); } while (0)
; #define PG8_LDB(dst, b, h) do { _Pragma("unroll") for (int n = 0; n < 2; ++n) _Pragma("unroll") for (int k = 0; k < 2; ++k) dst[n][k] = *(const LAS bf16x8*)(lds + PG8_SB(b, h) + boff + n * 2048 + k * 1024); } while (0)
; #define PG8_MMA(ai, bj, At, Bt) do { __builtin_amdgcn_s_setprio(1); _Pragma("unroll") for (int m = 0; m < 4; ++m) _Pragma("unroll") for (int n = 0; n < 2; ++n) _Pragma("unroll") for (int k = 0; k < 2; ++k) \
;         acc[ai][bj][m][n] = __builtin_amdgcn_mfma_f32_16x16x32_bf16(Bt[n][k], At[m][k], acc[ai][bj][m][n], 0, 0, 0); __builtin_amdgcn_s_setprio(0); } while (0)
; #define PG8_WAIT_V(n) asm volatile("s_waitcnt vmcnt(" #n ")" ::: "memory")
; #define PG8_WAIT_L(n) asm volatile("s_waitcnt lgkmcnt(" #n ")" ::: "memory")
; #define PG8_BAR __builtin_amdgcn_s_barrier()
; #define PG8_SCHED __builtin_amdgcn_sched_barrier(0)
; template <class Epi, class Sched>
; __device__ __forceinline__ void gemm_phase(LAS unsigned char* lds_in, const int lda, const int ldb, const Sched& S, const Epi& E, const int WID) {
;     ...
;             PG8_LDB(B0, 1, 0); PG8_SCHED; PG8_LDA(At, 1, 0); PG8_STAGE(PG8_SA(0, 1), a2 + hstepA, voffA);
;             PG8_WAIT_L(8); PG8_BAR; PG8_WAIT_L(0); PG8_MMA(0, 0, At, B0); PG8_BAR; PG8_SCHED;
;             PG8_LDB(B1, 1, 1); PG8_STAGE(PG8_SB(1, 0), b3, voffB);
;             PG8_BAR; PG8_WAIT_L(0); PG8_MMA(0, 1, At, B1); PG8_BAR;
;             PG8_LDA(At, 1, 1); PG8_STAGE(PG8_SA(1, 0), a3, voffA);
;             PG8_BAR; PG8_WAIT_L(0); PG8_MMA(1, 0, At, B0); PG8_BAR; PG8_SCHED;
;             PG8_STAGE(PG8_SB(1, 1), b3 + hstepB, voffB);
;             PG8_WAIT_V(6); PG8_BAR; PG8_MMA(1, 1, At, B1); PG8_BAR;
	s_setprio 1
	v_mfma_f32_16x16x32_bf16 v[54:57], v[178:181], v[126:129], v[54:57]
	v_mfma_f32_16x16x32_bf16 v[50:53], v[186:189], v[126:129], v[50:53]
	v_mfma_f32_16x16x32_bf16 v[38:41], v[178:181], v[142:145], v[38:41]
	v_mfma_f32_16x16x32_bf16 v[34:37], v[186:189], v[142:145], v[34:37]
	v_mfma_f32_16x16x32_bf16 v[22:25], v[178:181], v[154:157], v[22:25]
	v_mfma_f32_16x16x32_bf16 v[18:21], v[186:189], v[154:157], v[18:21]
	v_mfma_f32_16x16x32_bf16 v[6:9], v[178:181], v[170:173], v[6:9]
	v_mfma_f32_16x16x32_bf16 v[2:5], v[186:189], v[170:173], v[2:5]
	v_mfma_f32_16x16x32_bf16 v[54:57], v[182:185], v[130:133], v[54:57]
	v_mfma_f32_16x16x32_bf16 v[50:53], v[202:205], v[130:133], v[50:53]
	v_mfma_f32_16x16x32_bf16 v[38:41], v[182:185], v[146:149], v[38:41]
	v_mfma_f32_16x16x32_bf16 v[34:37], v[202:205], v[146:149], v[34:37]
	v_mfma_f32_16x16x32_bf16 v[22:25], v[182:185], v[166:169], v[22:25]
	v_mfma_f32_16x16x32_bf16 v[18:21], v[202:205], v[166:169], v[18:21]
	v_mfma_f32_16x16x32_bf16 v[6:9], v[182:185], v[174:177], v[6:9]
	v_mfma_f32_16x16x32_bf16 v[2:5], v[202:205], v[174:177], v[2:5]
	s_setprio 0
	s_barrier
	ds_read_b128 v[66:69], v230
	ds_read_b128 v[70:73], v230 offset:1024
	ds_read_b128 v[82:85], v230 offset:2048
	ds_read_b128 v[94:97], v230 offset:3072
	s_add_u32 s22, s22, 0x200000
	s_addc_u32 s23, s23, 0
	s_mov_b32 m0, s78
	ds_read_b128 v[126:129], v228 offset:32768
	ds_read_b128 v[130:133], v228 offset:33792
	ds_read_b128 v[142:145], v228 offset:34816
	ds_read_b128 v[154:157], v228 offset:35840
	ds_read_b128 v[166:169], v228 offset:36864
	ds_read_b128 v[170:173], v228 offset:37888
	ds_read_b128 v[174:177], v228 offset:38912
	ds_read_b128 v[178:181], v228 offset:39936
	global_load_lds_dwordx4 v190, s[22:23]
	s_mov_b32 m0, s79
	s_nop 0
	global_load_lds_dwordx4 v194, s[22:23]
	s_waitcnt lgkmcnt(8)
	s_barrier
	s_waitcnt lgkmcnt(0)
	s_setprio 1
	s_waitcnt lgkmcnt(0)
	v_mfma_f32_16x16x32_bf16 v[146:149], v[66:69], v[126:129], v[162:165]
	v_mfma_f32_16x16x32_bf16 v[162:165], v[70:73], v[130:133], v[146:149]
	v_mfma_f32_16x16x32_bf16 v[146:149], v[82:85], v[126:129], v[158:161]
	v_mfma_f32_16x16x32_bf16 v[138:141], v[66:69], v[142:145], v[138:141]
	v_mfma_f32_16x16x32_bf16 v[134:137], v[82:85], v[142:145], v[134:137]
	v_mfma_f32_16x16x32_bf16 v[114:117], v[66:69], v[166:169], v[114:117]
	v_mfma_f32_16x16x32_bf16 v[110:113], v[82:85], v[166:169], v[110:113]
	v_mfma_f32_16x16x32_bf16 v[90:93], v[66:69], v[174:177], v[90:93]
	v_mfma_f32_16x16x32_bf16 v[86:89], v[82:85], v[174:177], v[86:89]
	v_mfma_f32_16x16x32_bf16 v[158:161], v[94:97], v[130:133], v[146:149]
	v_mfma_f32_16x16x32_bf16 v[138:141], v[70:73], v[154:157], v[138:141]
	v_mfma_f32_16x16x32_bf16 v[134:137], v[94:97], v[154:157], v[134:137]
	v_mfma_f32_16x16x32_bf16 v[114:117], v[70:73], v[170:173], v[114:117]
	v_mfma_f32_16x16x32_bf16 v[110:113], v[94:97], v[170:173], v[110:113]
	v_mfma_f32_16x16x32_bf16 v[90:93], v[70:73], v[178:181], v[90:93]
	v_mfma_f32_16x16x32_bf16 v[86:89], v[94:97], v[178:181], v[86:89]
	s_setprio 0
	s_barrier
	s_mov_b32 m0, s91
	s_add_u32 s100, s20, 0x80
	s_addc_u32 s101, s21, 0
	ds_read_b128 v[182:185], v231
	ds_read_b128 v[186:189], v231 offset:1024
	ds_read_b128 v[202:205], v231 offset:2048
	ds_read_b128 v[206:209], v231 offset:3072
	global_load_lds_dwordx4 v192, s[100:101]
	s_add_u32 s100, s20, 0x80
	s_addc_u32 s101, s21, 0
	s_mov_b32 m0, s92
	s_nop 0
	global_load_lds_dwordx4 v196, s[100:101]
	s_barrier
	s_waitcnt lgkmcnt(0)
	s_setprio 1
	s_waitcnt lgkmcnt(0)
	v_mfma_f32_16x16x32_bf16 v[146:149], v[182:185], v[126:129], v[150:153]
	v_mfma_f32_16x16x32_bf16 v[106:109], v[202:205], v[126:129], v[106:109]
	v_mfma_f32_16x16x32_bf16 v[150:153], v[186:189], v[130:133], v[146:149]
	v_mfma_f32_16x16x32_bf16 v[146:149], v[206:209], v[130:133], v[106:109]
	v_mfma_f32_16x16x32_bf16 v[106:109], v[182:185], v[142:145], v[118:121]
	v_mfma_f32_16x16x32_bf16 v[126:129], v[186:189], v[154:157], v[106:109]
	v_mfma_f32_16x16x32_bf16 v[106:109], v[202:205], v[142:145], v[122:125]
	v_mfma_f32_16x16x32_bf16 v[102:105], v[182:185], v[166:169], v[102:105]
	v_mfma_f32_16x16x32_bf16 v[98:101], v[202:205], v[166:169], v[98:101]
	v_mfma_f32_16x16x32_bf16 v[78:81], v[182:185], v[174:177], v[78:81]
	v_mfma_f32_16x16x32_bf16 v[74:77], v[202:205], v[174:177], v[74:77]
	v_mfma_f32_16x16x32_bf16 v[122:125], v[206:209], v[154:157], v[106:109]
	v_mfma_f32_16x16x32_bf16 v[102:105], v[186:189], v[170:173], v[102:105]
	v_mfma_f32_16x16x32_bf16 v[98:101], v[206:209], v[170:173], v[98:101]
	v_mfma_f32_16x16x32_bf16 v[78:81], v[186:189], v[178:181], v[78:81]
	v_mfma_f32_16x16x32_bf16 v[74:77], v[206:209], v[178:181], v[74:77]
	s_setprio 0
	s_mov_b32 m0, s93
	s_add_u32 s100, s22, 0xffe00080
	s_addc_u32 s101, s23, -1
	s_barrier
	ds_read_b128 v[106:109], v228 offset:49152
	ds_read_b128 v[118:121], v228 offset:50176
	ds_read_b128 v[130:133], v228 offset:51200
	ds_read_b128 v[142:145], v228 offset:52224
	ds_read_b128 v[154:157], v228 offset:53248
	ds_read_b128 v[166:169], v228 offset:54272
	ds_read_b128 v[170:173], v228 offset:55296
	ds_read_b128 v[174:177], v228 offset:56320
	global_load_lds_dwordx4 v190, s[100:101]
	s_add_u32 s100, s22, 0xffe00080
	s_addc_u32 s101, s23, -1
	s_mov_b32 m0, s94
	s_nop 0
	global_load_lds_dwordx4 v194, s[100:101]
	s_barrier
; __device__ __forceinline__ void unpack8(const u32x4 w, f32x4& a, f32x4& b) { a[0] = bf_lo(w.x); a[1] = bf_hi(w.x); a[2] = bf_lo(w.y); a[3] = bf_hi(w.y); b[0] = bf_lo(w.z); b[1] = bf_hi(w.z); b[2] = bf_lo(w.w); b[3] = bf_hi(w.w); }
; #define PG8_WAIT_V(n) asm volatile("s_waitcnt vmcnt(" #n ")" ::: "memory")
; #define PG8_BAR __builtin_amdgcn_s_barrier()
; template <class Epi, class Sched>
; __device__ __forceinline__ void gemm_phase(LAS unsigned char* lds_in, const int lda, const int ldb, const Sched& S, const Epi& E, const int WID) {
;     ...
;             PG8_WAIT_V(6); PG8_BAR; PG8_MMA(1, 1, At, B1); PG8_BAR;
;             PG8_LDB(B0, 1, 0); PG8_SCHED; PG8_LDA(At, 1, 0); PG8_STAGE(PG8_SA(0, 1), a2 + hstepA, voffA);
;             PG8_WAIT_L(8); PG8_BAR; PG8_WAIT_L(0); PG8_MMA(0, 0, At, B0); PG8_BAR; PG8_SCHED;
;             PG8_LDB(B1, 1, 1); PG8_STAGE(PG8_SB(1, 0), b3, voffB);
;             PG8_BAR; PG8_WAIT_L(0); PG8_MMA(0, 1, At, B1); PG8_BAR;
;             PG8_LDA(At, 1, 1); PG8_STAGE(PG8_SA(1, 0), a3, voffA);
;             PG8_BAR; PG8_WAIT_L(0); PG8_MMA(1, 0, At, B0); PG8_BAR; PG8_SCHED;
;             PG8_STAGE(PG8_SB(1, 1), b3 + hstepB, voffB);
;             PG8_WAIT_V(6); PG8_BAR; PG8_MMA(1, 1, At, B1); PG8_BAR;
;     __device__ __forceinline__ void operator()(const AccT& acc, const Unit& u, int wr, int wc, int fr, int fq) const {
;         int row0 = u.pm * 256 + wr * 64 + fr, col0 = u.pn * 256 + wc * 32 + 8 * fq;
;         asm volatile("" : "+v"(row0), "+v"(col0));
;         u32x4 bw[2][4][2];
; #pragma unroll
;         for (int ai = 0; ai < 2; ++ai)
; #pragma unroll
;             for (int m = 0; m < 4; ++m)
; #pragma unroll
;                 for (int bj = 0; bj < 2; ++bj) bw[ai][m][bj] = *(const u32x4*)(Hb + (size_t)(row0 + ai * 128 + m * 16) * 2048 + col0 + bj * 128);
; #pragma unroll
;         for (int ai = 0; ai < 2; ++ai) {
; #pragma unroll
;             for (int m = 0; m < 4; ++m) {
;                 const int row = row0 + ai * 128 + m * 16; const size_t off = (size_t)row * 2048 + col0; float ss = 0.f;
; #pragma unroll
;                 for (int bj = 0; bj < 2; ++bj) {
;                     f32x4 b0, b1; unpack8(bw[ai][m][bj], b0, b1);
;                     const f32x4 o0 = b0 + acc[ai][bj][m][0], o1 = b1 + acc[ai][bj][m][1];
;                     if (outF) { *(f32x4*)(outF + off + bj * 128) = o0; *(f32x4*)(outF + off + bj * 128 + 4) = o1; }
	s_waitcnt lgkmcnt(0)
	s_setprio 1
	s_waitcnt lgkmcnt(0)
	v_mfma_f32_16x16x32_bf16 v[62:65], v[66:69], v[106:109], v[62:65]
	v_mfma_f32_16x16x32_bf16 v[58:61], v[82:85], v[106:109], v[58:61]
	v_mfma_f32_16x16x32_bf16 v[46:49], v[66:69], v[130:133], v[46:49]
	v_mfma_f32_16x16x32_bf16 v[42:45], v[82:85], v[130:133], v[42:45]
	v_mfma_f32_16x16x32_bf16 v[30:33], v[66:69], v[154:157], v[30:33]
	v_mfma_f32_16x16x32_bf16 v[26:29], v[82:85], v[154:157], v[26:29]
	v_mfma_f32_16x16x32_bf16 v[14:17], v[66:69], v[170:173], v[14:17]
	v_mfma_f32_16x16x32_bf16 v[10:13], v[82:85], v[170:173], v[10:13]
	v_mfma_f32_16x16x32_bf16 v[62:65], v[70:73], v[118:121], v[62:65]
	v_mfma_f32_16x16x32_bf16 v[58:61], v[94:97], v[118:121], v[58:61]
	v_mfma_f32_16x16x32_bf16 v[46:49], v[70:73], v[142:145], v[46:49]
	v_mfma_f32_16x16x32_bf16 v[42:45], v[94:97], v[142:145], v[42:45]
	v_mfma_f32_16x16x32_bf16 v[30:33], v[70:73], v[166:169], v[30:33]
	v_mfma_f32_16x16x32_bf16 v[26:29], v[94:97], v[166:169], v[26:29]
	v_mfma_f32_16x16x32_bf16 v[14:17], v[70:73], v[174:177], v[14:17]
	v_mfma_f32_16x16x32_bf16 v[10:13], v[94:97], v[174:177], v[10:13]
	s_setprio 0
	s_barrier
	s_add_u32 s20, s20, 0x200080
	s_addc_u32 s21, s21, 0
	s_mov_b32 m0, s95
	s_nop 0
	global_load_lds_dwordx4 v192, s[20:21]
	s_mov_b32 m0, s96
	s_nop 0
	global_load_lds_dwordx4 v196, s[20:21]
	s_waitcnt vmcnt(6)
	s_barrier
	s_setprio 1
	v_mfma_f32_16x16x32_bf16 v[54:57], v[182:185], v[106:109], v[54:57]
	v_mfma_f32_16x16x32_bf16 v[50:53], v[202:205], v[106:109], v[50:53]
	v_mfma_f32_16x16x32_bf16 v[38:41], v[182:185], v[130:133], v[38:41]
	v_mfma_f32_16x16x32_bf16 v[34:37], v[202:205], v[130:133], v[34:37]
	v_mfma_f32_16x16x32_bf16 v[22:25], v[182:185], v[154:157], v[22:25]
	v_mfma_f32_16x16x32_bf16 v[18:21], v[202:205], v[154:157], v[18:21]
	v_mfma_f32_16x16x32_bf16 v[6:9], v[182:185], v[170:173], v[6:9]
	v_mfma_f32_16x16x32_bf16 v[2:5], v[202:205], v[170:173], v[2:5]
	v_mfma_f32_16x16x32_bf16 v[54:57], v[186:189], v[118:121], v[54:57]
	v_mfma_f32_16x16x32_bf16 v[50:53], v[206:209], v[118:121], v[50:53]
	v_mfma_f32_16x16x32_bf16 v[38:41], v[186:189], v[142:145], v[38:41]
	v_mfma_f32_16x16x32_bf16 v[34:37], v[206:209], v[142:145], v[34:37]
	v_mfma_f32_16x16x32_bf16 v[22:25], v[186:189], v[166:169], v[22:25]
	v_mfma_f32_16x16x32_bf16 v[18:21], v[206:209], v[166:169], v[18:21]
	v_mfma_f32_16x16x32_bf16 v[6:9], v[186:189], v[174:177], v[6:9]
	v_mfma_f32_16x16x32_bf16 v[2:5], v[206:209], v[174:177], v[2:5]
	s_setprio 0
	s_add_i32 vcc_lo, vcc_lo, 2
	s_add_u32 s6, s6, 0x100
	s_addc_u32 s7, s7, 0
	s_add_u32 s5, s5, 0x100
	s_addc_u32 s15, s15, 0
	s_cmpk_gt_u32 vcc_lo, 0x7d
	s_barrier
	s_cbranch_scc0 .LBB0_151
	v_lshl_add_u32 v220, s4, 8, v1
	v_lshl_or_b32 v206, s97, 8, v226
	v_cndmask_b32_e64 v222, 0, 1, s[10:11]
	v_ashrrev_i32_e32 v207, 31, v206
	v_ashrrev_i32_e32 v221, 31, v220
	v_lshl_add_u64 v[204:205], v[206:207], 1, s[28:29]
	v_lshlrev_b64 v[66:67], 12, v[220:221]
	v_add_u32_e32 v218, 16, v220
	v_lshl_add_u64 v[66:67], v[204:205], 0, v[66:67]
	v_ashrrev_i32_e32 v219, 31, v218
	global_load_dwordx4 v[232:235], v[66:67], off
	global_load_dwordx4 v[186:189], v[66:67], off offset:256
	v_lshlrev_b64 v[66:67], 12, v[218:219]
	v_add_u32_e32 v216, 32, v220
	v_lshl_add_u64 v[66:67], v[204:205], 0, v[66:67]
	v_ashrrev_i32_e32 v217, 31, v216
	global_load_dwordx4 v[182:185], v[66:67], off
	global_load_dwordx4 v[178:181], v[66:67], off offset:256
	v_lshlrev_b64 v[66:67], 12, v[216:217]
	v_add_u32_e32 v214, 48, v220
	v_lshl_add_u64 v[66:67], v[204:205], 0, v[66:67]
	v_ashrrev_i32_e32 v215, 31, v214
	global_load_dwordx4 v[174:177], v[66:67], off
	global_load_dwordx4 v[170:173], v[66:67], off offset:256
	v_lshlrev_b64 v[66:67], 12, v[214:215]
	v_add_u32_e32 v212, 0x80, v220
	v_lshl_add_u64 v[66:67], v[204:205], 0, v[66:67]
	v_ashrrev_i32_e32 v213, 31, v212
	global_load_dwordx4 v[166:169], v[66:67], off
	global_load_dwordx4 v[154:157], v[66:67], off offset:256
	v_lshlrev_b64 v[66:67], 12, v[212:213]
	v_add_u32_e32 v210, 0x90, v220
	v_lshl_add_u64 v[66:67], v[204:205], 0, v[66:67]
	v_ashrrev_i32_e32 v211, 31, v210
	global_load_dwordx4 v[142:145], v[66:67], off
	global_load_dwordx4 v[130:133], v[66:67], off offset:256
	v_lshlrev_b64 v[66:67], 12, v[210:211]
	v_add_u32_e32 v208, 0xa0, v220
	v_lshl_add_u64 v[66:67], v[204:205], 0, v[66:67]
	v_ashrrev_i32_e32 v209, 31, v208
	global_load_dwordx4 v[118:121], v[66:67], off
	global_load_dwordx4 v[106:109], v[66:67], off offset:256
	v_lshlrev_b64 v[66:67], 12, v[208:209]
	v_add_u32_e32 v202, 0xb0, v220
	v_lshl_add_u64 v[66:67], v[204:205], 0, v[66:67]
	v_ashrrev_i32_e32 v203, 31, v202
	global_load_dwordx4 v[94:97], v[66:67], off
	global_load_dwordx4 v[82:85], v[66:67], off offset:256
	v_lshlrev_b64 v[66:67], 12, v[202:203]
	v_lshl_add_u64 v[66:67], v[204:205], 0, v[66:67]
	global_load_dwordx4 v[70:73], v[66:67], off
	s_nop 0
	global_load_dwordx4 v[66:69], v[66:67], off offset:256
	v_cmp_ne_u32_e64 s[6:7], 1, v222
	v_lshlrev_b64 v[222:223], 11, v[220:221]
	v_lshl_add_u64 v[224:225], v[222:223], 0, v[206:207]
	s_mov_b64 s[4:5], -1
	s_andn2_b64 vcc, exec, s[10:11]
	v_lshl_add_u64 v[224:225], v[224:225], 2, s[2:3]
	s_waitcnt vmcnt(0)
	v_lshlrev_b32_e32 v236, 16, v232
	v_and_b32_e32 v237, 0xffff0000, v232
	v_lshlrev_b32_e32 v232, 16, v233
	v_and_b32_e32 v233, 0xffff0000, v233
	v_lshlrev_b32_e32 v238, 16, v234
	v_and_b32_e32 v239, 0xffff0000, v234
	v_lshlrev_b32_e32 v234, 16, v235
	v_and_b32_e32 v235, 0xffff0000, v235
	v_pk_add_f32 v[164:165], v[164:165], v[232:233]
	v_pk_add_f32 v[162:163], v[162:163], v[236:237]
	v_pk_add_f32 v[160:161], v[160:161], v[234:235]
	v_pk_add_f32 v[158:159], v[158:159], v[238:239]
	s_cbranch_vccnz .LBB0_154
	s_mov_b64 s[4:5], 0
	global_store_dwordx4 v[224:225], v[162:165], off
	global_store_dwordx4 v[224:225], v[158:161], off offset:16

; #define PG8_STAGE(bufoff, gbase, voff) do { _Pragma("unroll") for (int _i = 0; _i < 2; ++_i) \
;         __builtin_amdgcn_global_load_lds((const unsigned*)((const char*)(gbase) + (voff)[_i]), (LAS unsigned*)(lds + (bufoff) + ldsw + _i * 8192), 16, 0, 0); } while (0)
; #define PG8_LDA(dst, b, h) do { _Pragma("unroll") for (int m = 0; m < 4; ++m) _Pragma("unroll") for (int k = 0; k < 2; ++k) dst[m][k] = *(const LAS bf16x8*)(lds + PG8_SA(b, h) + aoff + m * 2048 + k * 1024); } while (0)
; #define PG8_WAIT_V(n) asm volatile("s_waitcnt vmcnt(" #n ")" ::: "memory")
; #define PG8_BAR __builtin_amdgcn_s_barrier()
; template <class Epi, class Sched>
; __device__ __forceinline__ void gemm_phase(LAS unsigned char* lds_in, const int lda, const int ldb, const Sched& S, const Epi& E, const int WID) {
;     ...
;         for (int t = tb; t < te; t += 2) {
;             const bool last = (t == nt - 2);
;             const char* a1 = cA + (size_t)(t + 1) * kstep;
;             const char* a2 = last ? nA : cA + (size_t)(t + 2) * kstep; const char* b2 = last ? nB : cB + (size_t)(t + 2) * kstep;
;             const char* a3 = a2 + kstep; const char* b3 = b2 + kstep;
;             PG8_LDB(B0, 0, 0); PG8_SCHED; PG8_LDA(At, 0, 0); PG8_STAGE(PG8_SA(1, 1), a1 + hstepA, voffA);
;             PG8_WAIT_L(8); PG8_BAR; PG8_WAIT_L(0); PG8_MMA(0, 0, At, B0); PG8_BAR; PG8_SCHED;
;             PG8_LDB(B1, 0, 1); PG8_STAGE(PG8_SB(0, 0), b2, voffB);
;             PG8_BAR; PG8_WAIT_L(0); PG8_MMA(0, 1, At, B1); PG8_BAR;
;             PG8_LDA(At, 0, 1); PG8_STAGE(PG8_SA(0, 0), a2, voffA);
;             PG8_BAR; PG8_WAIT_L(0); PG8_MMA(1, 0, At, B0); PG8_BAR; PG8_SCHED;
;             PG8_STAGE(PG8_SB(0, 1), b2 + hstepB, voffB);
;             PG8_WAIT_V(6); PG8_BAR; PG8_MMA(1, 1, At, B1); PG8_BAR;
;             PG8_LDB(B0, 1, 0); PG8_SCHED; PG8_LDA(At, 1, 0); PG8_STAGE(PG8_SA(0, 1), a2 + hstepA, voffA);
;             PG8_WAIT_L(8); PG8_BAR; PG8_WAIT_L(0); PG8_MMA(0, 0, At, B0); PG8_BAR; PG8_SCHED;
;             PG8_LDB(B1, 1, 1); PG8_STAGE(PG8_SB(1, 0), b3, voffB);
;             PG8_BAR; PG8_WAIT_L(0); PG8_MMA(0, 1, At, B1); PG8_BAR;
;             PG8_LDA(At, 1, 1); PG8_STAGE(PG8_SA(1, 0), a3, voffA);
;             PG8_BAR; PG8_WAIT_L(0); PG8_MMA(1, 0, At, B0); PG8_BAR; PG8_SCHED;
;             PG8_STAGE(PG8_SB(1, 1), b3 + hstepB, voffB);
;             PG8_WAIT_V(6); PG8_BAR; PG8_MMA(1, 1, At, B1); PG8_BAR;
.LBB0_267:
	v_add_u32_e32 v146, s9, v148
	ds_read_b128 v[142:145], v146
	ds_read_b128 v[152:155], v146 offset:1024
	ds_read_b128 v[156:159], v146 offset:2048
	ds_read_b128 v[160:163], v146 offset:3072
	s_add_u32 s12, s10, 0xfff80080
	s_addc_u32 s13, s11, -1
	s_cmp_eq_u32 s95, 28
	s_cselect_b32 s15, s5, s13
	s_cselect_b32 s14, s4, s12
	s_cselect_b32 s13, s7, s94
	s_cselect_b32 s12, s6, s3
	s_add_i32 m0, s21, 0xc000
	ds_read_b128 v[164:167], v150
	ds_read_b128 v[168:171], v150 offset:1024
	ds_read_b128 v[172:175], v150 offset:2048
	ds_read_b128 v[176:179], v150 offset:3072
	ds_read_b128 v[180:183], v150 offset:4096
	ds_read_b128 v[184:187], v150 offset:5120
	ds_read_b128 v[188:191], v150 offset:6144
	ds_read_b128 v[192:195], v150 offset:7168
	global_load_lds_dwordx4 v138, s[10:11]
	s_add_i32 m0, s21, 0xe000
	s_nop 0
	global_load_lds_dwordx4 v140, s[10:11]
	s_waitcnt lgkmcnt(8)
	s_barrier
	s_waitcnt lgkmcnt(0)
	s_setprio 1
	s_waitcnt lgkmcnt(0)
	v_mfma_f32_16x16x32_bf16 v[126:129], v[142:145], v[164:167], v[126:129]
	v_mfma_f32_16x16x32_bf16 v[122:125], v[156:159], v[164:167], v[122:125]
	v_mfma_f32_16x16x32_bf16 v[110:113], v[142:145], v[172:175], v[110:113]
	v_mfma_f32_16x16x32_bf16 v[106:109], v[156:159], v[172:175], v[106:109]
	v_mfma_f32_16x16x32_bf16 v[94:97], v[142:145], v[180:183], v[94:97]
	v_mfma_f32_16x16x32_bf16 v[90:93], v[156:159], v[180:183], v[90:93]
	v_mfma_f32_16x16x32_bf16 v[78:81], v[142:145], v[188:191], v[78:81]
	v_mfma_f32_16x16x32_bf16 v[74:77], v[156:159], v[188:191], v[74:77]
	v_mfma_f32_16x16x32_bf16 v[126:129], v[152:155], v[168:171], v[126:129]
	v_mfma_f32_16x16x32_bf16 v[122:125], v[160:163], v[168:171], v[122:125]
	v_mfma_f32_16x16x32_bf16 v[110:113], v[152:155], v[176:179], v[110:113]
	v_mfma_f32_16x16x32_bf16 v[106:109], v[160:163], v[176:179], v[106:109]
	v_mfma_f32_16x16x32_bf16 v[94:97], v[152:155], v[184:187], v[94:97]
	v_mfma_f32_16x16x32_bf16 v[90:93], v[160:163], v[184:187], v[90:93]
	v_mfma_f32_16x16x32_bf16 v[78:81], v[152:155], v[192:195], v[78:81]
	v_mfma_f32_16x16x32_bf16 v[74:77], v[160:163], v[192:195], v[74:77]
	s_setprio 0
	s_barrier
	v_add_u32_e32 v146, s23, v148
	s_mov_b32 m0, s19
	ds_read_b128 v[196:199], v146
	ds_read_b128 v[200:203], v146 offset:1024
	ds_read_b128 v[204:207], v146 offset:2048
	ds_read_b128 v[208:211], v146 offset:3072
	global_load_lds_dwordx4 v132, s[12:13]
	s_mov_b32 m0, s20
	s_nop 0
	global_load_lds_dwordx4 v136, s[12:13]
	s_barrier
	s_waitcnt lgkmcnt(0)
	s_setprio 1
	s_waitcnt lgkmcnt(0)
	v_mfma_f32_16x16x32_bf16 v[118:121], v[196:199], v[164:167], v[118:121]
	v_mfma_f32_16x16x32_bf16 v[114:117], v[204:207], v[164:167], v[114:117]
	v_mfma_f32_16x16x32_bf16 v[102:105], v[196:199], v[172:175], v[102:105]
	v_mfma_f32_16x16x32_bf16 v[98:101], v[204:207], v[172:175], v[98:101]
	v_mfma_f32_16x16x32_bf16 v[86:89], v[196:199], v[180:183], v[86:89]
	v_mfma_f32_16x16x32_bf16 v[82:85], v[204:207], v[180:183], v[82:85]
	v_mfma_f32_16x16x32_bf16 v[70:73], v[196:199], v[188:191], v[70:73]
	v_mfma_f32_16x16x32_bf16 v[66:69], v[204:207], v[188:191], v[66:69]
	v_mfma_f32_16x16x32_bf16 v[118:121], v[200:203], v[168:171], v[118:121]
	v_mfma_f32_16x16x32_bf16 v[114:117], v[208:211], v[168:171], v[114:117]
	v_mfma_f32_16x16x32_bf16 v[102:105], v[200:203], v[176:179], v[102:105]
	v_mfma_f32_16x16x32_bf16 v[98:101], v[208:211], v[176:179], v[98:101]
	v_mfma_f32_16x16x32_bf16 v[86:89], v[200:203], v[184:187], v[86:89]
	v_mfma_f32_16x16x32_bf16 v[82:85], v[208:211], v[184:187], v[82:85]
	v_mfma_f32_16x16x32_bf16 v[70:73], v[200:203], v[192:195], v[70:73]
	v_mfma_f32_16x16x32_bf16 v[66:69], v[208:211], v[192:195], v[66:69]
	s_setprio 0
	s_mov_b32 m0, s21
	s_barrier
	ds_read_b128 v[164:167], v150 offset:16384
	ds_read_b128 v[168:171], v150 offset:17408
	ds_read_b128 v[172:175], v150 offset:18432
	ds_read_b128 v[176:179], v150 offset:19456
	ds_read_b128 v[180:183], v150 offset:20480
	ds_read_b128 v[184:187], v150 offset:21504
	ds_read_b128 v[188:191], v150 offset:22528
	ds_read_b128 v[192:195], v150 offset:23552
	global_load_lds_dwordx4 v130, s[14:15]
	s_mov_b32 m0, s22
	s_nop 0
	global_load_lds_dwordx4 v134, s[14:15]
	s_barrier
	s_waitcnt lgkmcnt(0)
	s_setprio 1
	s_waitcnt lgkmcnt(0)
	v_mfma_f32_16x16x32_bf16 v[62:65], v[142:145], v[164:167], v[62:65]
	v_mfma_f32_16x16x32_bf16 v[58:61], v[156:159], v[164:167], v[58:61]
	v_mfma_f32_16x16x32_bf16 v[46:49], v[142:145], v[172:175], v[46:49]
	v_mfma_f32_16x16x32_bf16 v[42:45], v[156:159], v[172:175], v[42:45]
	v_mfma_f32_16x16x32_bf16 v[30:33], v[142:145], v[180:183], v[30:33]
	v_mfma_f32_16x16x32_bf16 v[26:29], v[156:159], v[180:183], v[26:29]
	v_mfma_f32_16x16x32_bf16 v[14:17], v[142:145], v[188:191], v[14:17]
	v_mfma_f32_16x16x32_bf16 v[10:13], v[156:159], v[188:191], v[10:13]
	v_mfma_f32_16x16x32_bf16 v[62:65], v[152:155], v[168:171], v[62:65]
	v_mfma_f32_16x16x32_bf16 v[58:61], v[160:163], v[168:171], v[58:61]
	v_mfma_f32_16x16x32_bf16 v[46:49], v[152:155], v[176:179], v[46:49]
	v_mfma_f32_16x16x32_bf16 v[42:45], v[160:163], v[176:179], v[42:45]
	v_mfma_f32_16x16x32_bf16 v[30:33], v[152:155], v[184:187], v[30:33]
	v_mfma_f32_16x16x32_bf16 v[26:29], v[160:163], v[184:187], v[26:29]
	v_mfma_f32_16x16x32_bf16 v[14:17], v[152:155], v[192:195], v[14:17]
	v_mfma_f32_16x16x32_bf16 v[10:13], v[160:163], v[192:195], v[10:13]
	s_setprio 0
	s_barrier
	s_add_u32 s66, s12, 0x80000
	s_addc_u32 s67, s13, 0
	s_mov_b32 m0, s35
	s_nop 0
	global_load_lds_dwordx4 v132, s[66:67]
	s_mov_b32 m0, s46
	s_nop 0
	global_load_lds_dwordx4 v136, s[66:67]
	s_waitcnt vmcnt(6)
	s_barrier
; #define PG8_STAGE(bufoff, gbase, voff) do { _Pragma("unroll") for (int _i = 0; _i < 2; ++_i) \
;         __builtin_amdgcn_global_load_lds((const unsigned*)((const char*)(gbase) + (voff)[_i]), (LAS unsigned*)(lds + (bufoff) + ldsw + _i * 8192), 16, 0, 0); } while (0)
; #define PG8_LDA(dst, b, h) do { _Pragma("unroll") for (int m = 0; m < 4; ++m) _Pragma("unroll") for (int k = 0; k < 2; ++k) dst[m][k] = *(const LAS bf16x8*)(lds + PG8_SA(b, h) + aoff + m * 2048 + k * 1024); } while (0)
; #define PG8_LDB(dst, b, h) do { _Pragma("unroll") for (int n = 0; n < 2; ++n) _Pragma("unroll") for (int k = 0; k < 2; ++k) dst[n][k] = *(const LAS bf16x8*)(lds + PG8_SB(b, h) + boff + n * 2048 + k * 1024); } while (0)
; #define PG8_MMA(ai, bj, At, Bt) do { __builtin_amdgcn_s_setprio(1); _Pragma("unroll") for (int m = 0; m < 4; ++m) _Pragma("unroll") for (int n = 0; n < 2; ++n) _Pragma("unroll") for (int k = 0; k < 2; ++k) \
;         acc[ai][bj][m][n] = __builtin_amdgcn_mfma_f32_16x16x32_bf16(Bt[n][k], At[m][k], acc[ai][bj][m][n], 0, 0, 0); __builtin_amdgcn_s_setprio(0); } while (0)
; #define PG8_WAIT_V(n) asm volatile("s_waitcnt vmcnt(" #n ")" ::: "memory")
; #define PG8_WAIT_L(n) asm volatile("s_waitcnt lgkmcnt(" #n ")" ::: "memory")
; #define PG8_BAR __builtin_amdgcn_s_barrier()
; #define PG8_SCHED __builtin_amdgcn_sched_barrier(0)
; template <class Epi, class Sched>
; __device__ __forceinline__ void gemm_phase(LAS unsigned char* lds_in, const int lda, const int ldb, const Sched& S, const Epi& E, const int WID) {
;     ...
;             PG8_LDB(B0, 1, 0); PG8_SCHED; PG8_LDA(At, 1, 0); PG8_STAGE(PG8_SA(0, 1), a2 + hstepA, voffA);
;             PG8_WAIT_L(8); PG8_BAR; PG8_WAIT_L(0); PG8_MMA(0, 0, At, B0); PG8_BAR; PG8_SCHED;
;             PG8_LDB(B1, 1, 1); PG8_STAGE(PG8_SB(1, 0), b3, voffB);
;             PG8_BAR; PG8_WAIT_L(0); PG8_MMA(0, 1, At, B1); PG8_BAR;
;             PG8_LDA(At, 1, 1); PG8_STAGE(PG8_SA(1, 0), a3, voffA);
;             PG8_BAR; PG8_WAIT_L(0); PG8_MMA(1, 0, At, B0); PG8_BAR; PG8_SCHED;
;             PG8_STAGE(PG8_SB(1, 1), b3 + hstepB, voffB);
;             PG8_WAIT_V(6); PG8_BAR; PG8_MMA(1, 1, At, B1); PG8_BAR;
	s_setprio 1
	v_mfma_f32_16x16x32_bf16 v[54:57], v[196:199], v[164:167], v[54:57]
	v_mfma_f32_16x16x32_bf16 v[50:53], v[204:207], v[164:167], v[50:53]
	v_mfma_f32_16x16x32_bf16 v[38:41], v[196:199], v[172:175], v[38:41]
	v_mfma_f32_16x16x32_bf16 v[34:37], v[204:207], v[172:175], v[34:37]
	v_mfma_f32_16x16x32_bf16 v[22:25], v[196:199], v[180:183], v[22:25]
	v_mfma_f32_16x16x32_bf16 v[18:21], v[204:207], v[180:183], v[18:21]
	v_mfma_f32_16x16x32_bf16 v[6:9], v[196:199], v[188:191], v[6:9]
	v_mfma_f32_16x16x32_bf16 v[2:5], v[204:207], v[188:191], v[2:5]
	v_mfma_f32_16x16x32_bf16 v[54:57], v[200:203], v[168:171], v[54:57]
	v_mfma_f32_16x16x32_bf16 v[50:53], v[208:211], v[168:171], v[50:53]
	v_mfma_f32_16x16x32_bf16 v[38:41], v[200:203], v[176:179], v[38:41]
	v_mfma_f32_16x16x32_bf16 v[34:37], v[208:211], v[176:179], v[34:37]
	v_mfma_f32_16x16x32_bf16 v[22:25], v[200:203], v[184:187], v[22:25]
	v_mfma_f32_16x16x32_bf16 v[18:21], v[208:211], v[184:187], v[18:21]
	v_mfma_f32_16x16x32_bf16 v[6:9], v[200:203], v[192:195], v[6:9]
	v_mfma_f32_16x16x32_bf16 v[2:5], v[208:211], v[192:195], v[2:5]
	s_setprio 0
	v_add_u32_e32 v151, s49, v148
	s_barrier
	ds_read_b128 v[142:145], v151
	ds_read_b128 v[152:155], v151 offset:1024
	ds_read_b128 v[156:159], v151 offset:2048
	ds_read_b128 v[160:163], v151 offset:3072
	s_add_u32 s14, s14, 0x80000
	s_addc_u32 s15, s15, 0
	s_mov_b32 m0, s47
	ds_read_b128 v[164:167], v150 offset:32768
	ds_read_b128 v[168:171], v150 offset:33792
	ds_read_b128 v[172:175], v150 offset:34816
	ds_read_b128 v[176:179], v150 offset:35840
	ds_read_b128 v[180:183], v150 offset:36864
	ds_read_b128 v[184:187], v150 offset:37888
	ds_read_b128 v[188:191], v150 offset:38912
	ds_read_b128 v[192:195], v150 offset:39936
	global_load_lds_dwordx4 v130, s[14:15]
	s_mov_b32 m0, s48
	s_nop 0
	global_load_lds_dwordx4 v134, s[14:15]
	s_waitcnt lgkmcnt(8)
	s_barrier
	s_waitcnt lgkmcnt(0)
	s_setprio 1
	s_waitcnt lgkmcnt(0)
	v_mfma_f32_16x16x32_bf16 v[126:129], v[142:145], v[164:167], v[126:129]
	v_mfma_f32_16x16x32_bf16 v[122:125], v[156:159], v[164:167], v[122:125]
	v_mfma_f32_16x16x32_bf16 v[110:113], v[142:145], v[172:175], v[110:113]
	v_mfma_f32_16x16x32_bf16 v[106:109], v[156:159], v[172:175], v[106:109]
	v_mfma_f32_16x16x32_bf16 v[94:97], v[142:145], v[180:183], v[94:97]
	v_mfma_f32_16x16x32_bf16 v[90:93], v[156:159], v[180:183], v[90:93]
	v_mfma_f32_16x16x32_bf16 v[78:81], v[142:145], v[188:191], v[78:81]
	v_mfma_f32_16x16x32_bf16 v[74:77], v[156:159], v[188:191], v[74:77]
	v_mfma_f32_16x16x32_bf16 v[126:129], v[152:155], v[168:171], v[126:129]
	v_mfma_f32_16x16x32_bf16 v[122:125], v[160:163], v[168:171], v[122:125]
	v_mfma_f32_16x16x32_bf16 v[110:113], v[152:155], v[176:179], v[110:113]
	v_mfma_f32_16x16x32_bf16 v[106:109], v[160:163], v[176:179], v[106:109]
	v_mfma_f32_16x16x32_bf16 v[94:97], v[152:155], v[184:187], v[94:97]
	v_mfma_f32_16x16x32_bf16 v[90:93], v[160:163], v[184:187], v[90:93]
	v_mfma_f32_16x16x32_bf16 v[78:81], v[152:155], v[192:195], v[78:81]
	v_mfma_f32_16x16x32_bf16 v[74:77], v[160:163], v[192:195], v[74:77]
	s_setprio 0
	s_barrier
	s_mov_b32 m0, s50
	v_add_u32_e32 v151, s78, v148
	s_add_u32 s100, s12, 0x80
	s_addc_u32 s101, s13, 0
	ds_read_b128 v[196:199], v151
	ds_read_b128 v[200:203], v151 offset:1024
	ds_read_b128 v[204:207], v151 offset:2048
	ds_read_b128 v[208:211], v151 offset:3072
	global_load_lds_dwordx4 v132, s[100:101]
	s_add_u32 s100, s12, 0x80
	s_addc_u32 s101, s13, 0
	s_mov_b32 m0, s51
	s_nop 0
	global_load_lds_dwordx4 v136, s[100:101]
	s_barrier
	s_waitcnt lgkmcnt(0)
	s_setprio 1
	s_waitcnt lgkmcnt(0)
	v_mfma_f32_16x16x32_bf16 v[118:121], v[196:199], v[164:167], v[118:121]
	v_mfma_f32_16x16x32_bf16 v[114:117], v[204:207], v[164:167], v[114:117]
	v_mfma_f32_16x16x32_bf16 v[102:105], v[196:199], v[172:175], v[102:105]
	v_mfma_f32_16x16x32_bf16 v[98:101], v[204:207], v[172:175], v[98:101]
	v_mfma_f32_16x16x32_bf16 v[86:89], v[196:199], v[180:183], v[86:89]
	v_mfma_f32_16x16x32_bf16 v[82:85], v[204:207], v[180:183], v[82:85]
	v_mfma_f32_16x16x32_bf16 v[70:73], v[196:199], v[188:191], v[70:73]
	v_mfma_f32_16x16x32_bf16 v[66:69], v[204:207], v[188:191], v[66:69]
	v_mfma_f32_16x16x32_bf16 v[118:121], v[200:203], v[168:171], v[118:121]
	v_mfma_f32_16x16x32_bf16 v[114:117], v[208:211], v[168:171], v[114:117]
	v_mfma_f32_16x16x32_bf16 v[102:105], v[200:203], v[176:179], v[102:105]
	v_mfma_f32_16x16x32_bf16 v[98:101], v[208:211], v[176:179], v[98:101]
	v_mfma_f32_16x16x32_bf16 v[86:89], v[200:203], v[184:187], v[86:89]
	v_mfma_f32_16x16x32_bf16 v[82:85], v[208:211], v[184:187], v[82:85]
	v_mfma_f32_16x16x32_bf16 v[70:73], v[200:203], v[192:195], v[70:73]
	v_mfma_f32_16x16x32_bf16 v[66:69], v[208:211], v[192:195], v[66:69]
	s_setprio 0
	s_mov_b32 m0, s65
	s_add_u32 s100, s14, 0xfff80080
	s_addc_u32 s101, s15, -1
	s_barrier
	ds_read_b128 v[164:167], v150 offset:49152
	ds_read_b128 v[168:171], v150 offset:50176
	ds_read_b128 v[172:175], v150 offset:51200
	ds_read_b128 v[176:179], v150 offset:52224
	ds_read_b128 v[180:183], v150 offset:53248
	ds_read_b128 v[184:187], v150 offset:54272
	ds_read_b128 v[188:191], v150 offset:55296
	ds_read_b128 v[192:195], v150 offset:56320
	global_load_lds_dwordx4 v130, s[100:101]
	s_add_u32 s100, s14, 0xfff80080
	s_addc_u32 s101, s15, -1
	s_mov_b32 m0, s70
	s_nop 0
	global_load_lds_dwordx4 v134, s[100:101]
	s_barrier
; __device__ __forceinline__ float rstd_of(float ss) { return rsqrtf(ss * (1.0f / DM) + EPS); }
; __device__ __forceinline__ u32x4 pack8(const f32x4 a, const f32x4 b) { u32x4 w; w.x = cvt_pk_bf16(a[0], a[1]); w.y = cvt_pk_bf16(a[2], a[3]); w.z = cvt_pk_bf16(b[0], b[1]); w.w = cvt_pk_bf16(b[2], b[3]); return w; }
; #define PG8_STAGE(bufoff, gbase, voff) do { _Pragma("unroll") for (int _i = 0; _i < 2; ++_i) \
;         __builtin_amdgcn_global_load_lds((const unsigned*)((const char*)(gbase) + (voff)[_i]), (LAS unsigned*)(lds + (bufoff) + ldsw + _i * 8192), 16, 0, 0); } while (0)
; #define PG8_MMA(ai, bj, At, Bt) do { __builtin_amdgcn_s_setprio(1); _Pragma("unroll") for (int m = 0; m < 4; ++m) _Pragma("unroll") for (int n = 0; n < 2; ++n) _Pragma("unroll") for (int k = 0; k < 2; ++k) \
;         acc[ai][bj][m][n] = __builtin_amdgcn_mfma_f32_16x16x32_bf16(Bt[n][k], At[m][k], acc[ai][bj][m][n], 0, 0, 0); __builtin_amdgcn_s_setprio(0); } while (0)
; #define PG8_BAR __builtin_amdgcn_s_barrier()
; template <class Epi, class Sched>
; __device__ __forceinline__ void gemm_phase(LAS unsigned char* lds_in, const int lda, const int ldb, const Sched& S, const Epi& E, const int WID) {
;     ...
;             PG8_BAR; PG8_WAIT_L(0); PG8_MMA(1, 0, At, B0); PG8_BAR; PG8_SCHED;
;             PG8_STAGE(PG8_SB(1, 1), b3 + hstepB, voffB);
;             PG8_WAIT_V(6); PG8_BAR; PG8_MMA(1, 1, At, B1); PG8_BAR;
;     __device__ __forceinline__ void operator()(const AccT& acc, const Unit& u, int wr, int wc, int fr, int fq) const {
;         const int row0 = u.pm * 256 + wr * 64 + fr, col0 = u.pn * 256 + wc * 32 + 8 * fq;
;         float rsv[2][4];
; #pragma unroll
;         for (int ai = 0; ai < 2; ++ai)
; #pragma unroll
;             for (int m = 0; m < 4; ++m) rsv[ai][m] = SS[row0 + ai * 128 + m * 16];
; #pragma unroll
;         for (int ai = 0; ai < 2; ++ai)
; #pragma unroll
;             for (int m = 0; m < 4; ++m) {
;                 const float rs = rstd_of(rsv[ai][m]);
; #pragma unroll
;                 for (int bj = 0; bj < 2; ++bj) {
;                     f32x4 v0 = acc[ai][bj][m][0] * rs, v1 = acc[ai][bj][m][1] * rs;
; #pragma unroll
;                     for (int j = 0; j < 4; ++j) { const float a = fmaxf(v0[j], 0.f), b = fmaxf(v1[j], 0.f); v0[j] = a * a; v1[j] = b * b; }
;                     *(u32x4*)(Hd + (size_t)(row0 + ai * 128 + m * 16) * DFF + col0 + bj * 128) = pack8(v0, v1);
	s_waitcnt lgkmcnt(0)
	s_setprio 1
	s_waitcnt lgkmcnt(0)
	v_mfma_f32_16x16x32_bf16 v[62:65], v[142:145], v[164:167], v[62:65]
	v_mfma_f32_16x16x32_bf16 v[58:61], v[156:159], v[164:167], v[58:61]
	v_mfma_f32_16x16x32_bf16 v[46:49], v[142:145], v[172:175], v[46:49]
	v_mfma_f32_16x16x32_bf16 v[42:45], v[156:159], v[172:175], v[42:45]
	v_mfma_f32_16x16x32_bf16 v[30:33], v[142:145], v[180:183], v[30:33]
	v_mfma_f32_16x16x32_bf16 v[26:29], v[156:159], v[180:183], v[26:29]
	v_mfma_f32_16x16x32_bf16 v[14:17], v[142:145], v[188:191], v[14:17]
	v_mfma_f32_16x16x32_bf16 v[10:13], v[156:159], v[188:191], v[10:13]
	v_mfma_f32_16x16x32_bf16 v[62:65], v[152:155], v[168:171], v[62:65]
	v_mfma_f32_16x16x32_bf16 v[58:61], v[160:163], v[168:171], v[58:61]
	v_mfma_f32_16x16x32_bf16 v[46:49], v[152:155], v[176:179], v[46:49]
	v_mfma_f32_16x16x32_bf16 v[42:45], v[160:163], v[176:179], v[42:45]
	v_mfma_f32_16x16x32_bf16 v[30:33], v[152:155], v[184:187], v[30:33]
	v_mfma_f32_16x16x32_bf16 v[26:29], v[160:163], v[184:187], v[26:29]
	v_mfma_f32_16x16x32_bf16 v[14:17], v[152:155], v[192:195], v[14:17]
	v_mfma_f32_16x16x32_bf16 v[10:13], v[160:163], v[192:195], v[10:13]
	s_setprio 0
	s_barrier
	s_add_u32 s12, s12, 0x80080
	s_addc_u32 s13, s13, 0
	s_mov_b32 m0, s79
	s_nop 0
	global_load_lds_dwordx4 v132, s[12:13]
	s_mov_b32 m0, s90
	s_nop 0
	global_load_lds_dwordx4 v136, s[12:13]
	s_waitcnt vmcnt(6)
	s_barrier
	s_setprio 1
	v_mfma_f32_16x16x32_bf16 v[54:57], v[196:199], v[164:167], v[54:57]
	v_mfma_f32_16x16x32_bf16 v[50:53], v[204:207], v[164:167], v[50:53]
	v_mfma_f32_16x16x32_bf16 v[38:41], v[196:199], v[172:175], v[38:41]
	v_mfma_f32_16x16x32_bf16 v[34:37], v[204:207], v[172:175], v[34:37]
	v_mfma_f32_16x16x32_bf16 v[22:25], v[196:199], v[180:183], v[22:25]
	v_mfma_f32_16x16x32_bf16 v[18:21], v[204:207], v[180:183], v[18:21]
	v_mfma_f32_16x16x32_bf16 v[6:9], v[196:199], v[188:191], v[6:9]
	v_mfma_f32_16x16x32_bf16 v[2:5], v[204:207], v[188:191], v[2:5]
	v_mfma_f32_16x16x32_bf16 v[54:57], v[200:203], v[168:171], v[54:57]
	v_mfma_f32_16x16x32_bf16 v[50:53], v[208:211], v[168:171], v[50:53]
	v_mfma_f32_16x16x32_bf16 v[38:41], v[200:203], v[176:179], v[38:41]
	v_mfma_f32_16x16x32_bf16 v[34:37], v[208:211], v[176:179], v[34:37]
	v_mfma_f32_16x16x32_bf16 v[22:25], v[200:203], v[184:187], v[22:25]
	v_mfma_f32_16x16x32_bf16 v[18:21], v[208:211], v[184:187], v[18:21]
	v_mfma_f32_16x16x32_bf16 v[6:9], v[200:203], v[192:195], v[6:9]
	v_mfma_f32_16x16x32_bf16 v[2:5], v[208:211], v[192:195], v[2:5]
	s_setprio 0
	s_add_i32 s95, s95, 2
	s_add_u32 s10, s10, 0x100
	s_addc_u32 s11, s11, 0
	s_add_u32 s3, s3, 0x100
	s_addc_u32 s94, s94, 0
	s_cmp_gt_u32 s95, 29
	s_barrier
	s_cbranch_scc0 .LBB0_267
	v_lshl_add_u32 v158, s8, 8, v1
	v_readlane_b32 s10, v254, 42
	v_ashrrev_i32_e32 v159, 31, v158
	v_readlane_b32 s11, v254, 43
	v_or_b32_e32 v146, 16, v158
	v_ashrrev_i32_e32 v147, 31, v146
	v_lshl_add_u64 v[160:161], v[158:159], 2, s[10:11]
	global_load_dword v157, v[160:161], off
	v_lshl_add_u64 v[142:143], v[146:147], 2, s[10:11]
	global_load_dword v163, v[142:143], off
	v_or_b32_e32 v144, 32, v158
	v_ashrrev_i32_e32 v145, 31, v144
	v_lshl_add_u64 v[142:143], v[144:145], 2, s[10:11]
	global_load_dword v156, v[142:143], off
	v_or_b32_e32 v142, 48, v158
	v_ashrrev_i32_e32 v143, 31, v142
	v_lshl_add_u64 v[152:153], v[142:143], 2, s[10:11]
	global_load_dword v155, v[152:153], off
	global_load_dword v154, v[160:161], off offset:512
	s_nop 0
	global_load_dword v153, v[160:161], off offset:576
	global_load_dword v152, v[160:161], off offset:640
	global_load_dword v151, v[160:161], off offset:704
	v_lshl_or_b32 v160, s93, 8, v149
	v_ashrrev_i32_e32 v161, 31, v160
	v_lshlrev_b64 v[158:159], 14, v[158:159]
	s_mov_b64 s[10:11], 0x200000
	s_mov_b32 s3, 0x2c0000
	s_mov_b32 s93, s92
	s_mov_b32 s8, s2
	s_mov_b64 s[12:13], s[6:7]
	s_waitcnt vmcnt(0)
	v_fmamk_f32 v157, v157, 0x3a000000, v251
	v_cmp_gt_f32_e32 vcc, s38, v157
	v_mul_f32_e32 v162, 0x4b800000, v157
	s_nop 0
	v_cndmask_b32_e32 v157, v157, v162, vcc
	v_rsq_f32_e32 v157, v157
	s_nop 0
	v_mul_f32_e32 v162, 0x45800000, v157
	v_cndmask_b32_e32 v162, v157, v162, vcc
	v_pk_mul_f32 v[128:129], v[128:129], v[162:163] op_sel_hi:[1,0]
	v_pk_mul_f32 v[126:127], v[126:127], v[162:163] op_sel_hi:[1,0]
	v_pk_mul_f32 v[124:125], v[124:125], v[162:163] op_sel_hi:[1,0]
	v_pk_mul_f32 v[122:123], v[122:123], v[162:163] op_sel_hi:[1,0]
	v_max_f32_e32 v126, 0, v126
	v_max_f32_e32 v122, 0, v122
	v_max_f32_e32 v127, 0, v127
	v_max_f32_e32 v123, 0, v123
	v_max_f32_e32 v128, 0, v128
	v_max_f32_e32 v124, 0, v124
	v_max_f32_e32 v129, 0, v129
	v_max_f32_e32 v125, 0, v125
	v_mul_f32_e32 v126, v126, v126
	v_mul_f32_e32 v122, v122, v122
	v_mul_f32_e32 v127, v127, v127
	v_mul_f32_e32 v123, v123, v123
	v_mul_f32_e32 v128, v128, v128
	v_mul_f32_e32 v124, v124, v124
	v_mul_f32_e32 v129, v129, v129
	v_mul_f32_e32 v125, v125, v125
	v_cvt_pk_bf16_f32 v126, v126, v127
	v_cvt_pk_bf16_f32 v127, v128, v129
	v_cvt_pk_bf16_f32 v128, v122, v123
	v_cvt_pk_bf16_f32 v129, v124, v125
	v_lshl_add_u64 v[122:123], s[30:31], 0, v[158:159]
	v_lshlrev_b64 v[124:125], 1, v[160:161]
	v_pk_mul_f32 v[114:115], v[114:115], v[162:163] op_sel_hi:[1,0]
	v_lshl_add_u64 v[122:123], v[122:123], 0, v[124:125]
	v_pk_mul_f32 v[118:119], v[118:119], v[162:163] op_sel_hi:[1,0]
	v_pk_mul_f32 v[116:117], v[116:117], v[162:163] op_sel_hi:[1,0]
	v_max_f32_e32 v114, 0, v114
	global_store_dwordx4 v[122:123], v[126:129], off
	v_pk_mul_f32 v[120:121], v[120:121], v[162:163] op_sel_hi:[1,0]
	v_max_f32_e32 v115, 0, v115
	v_mul_f32_e32 v126, v114, v114
	v_max_f32_e32 v114, 0, v119
	v_max_f32_e32 v116, 0, v116
; __device__ __forceinline__ float rstd_of(float ss) { return rsqrtf(ss * (1.0f / DM) + EPS); }
; __device__ __forceinline__ u32x4 pack8(const f32x4 a, const f32x4 b) { u32x4 w; w.x = cvt_pk_bf16(a[0], a[1]); w.y = cvt_pk_bf16(a[2], a[3]); w.z = cvt_pk_bf16(b[0], b[1]); w.w = cvt_pk_bf16(b[2], b[3]); return w; }
;     __device__ __forceinline__ void operator()(const AccT& acc, const Unit& u, int wr, int wc, int fr, int fq) const {
;         const int row0 = u.pm * 256 + wr * 64 + fr, col0 = u.pn * 256 + wc * 32 + 8 * fq;
;         float rsv[2][4];
; #pragma unroll
;         for (int ai = 0; ai < 2; ++ai)
; #pragma unroll
;             for (int m = 0; m < 4; ++m) rsv[ai][m] = SS[row0 + ai * 128 + m * 16];
; #pragma unroll
;         for (int ai = 0; ai < 2; ++ai)
; #pragma unroll
;             for (int m = 0; m < 4; ++m) {
;                 const float rs = rstd_of(rsv[ai][m]);
; #pragma unroll
;                 for (int bj = 0; bj < 2; ++bj) {
;                     f32x4 v0 = acc[ai][bj][m][0] * rs, v1 = acc[ai][bj][m][1] * rs;
; #pragma unroll
;                     for (int j = 0; j < 4; ++j) { const float a = fmaxf(v0[j], 0.f), b = fmaxf(v1[j], 0.f); v0[j] = a * a; v1[j] = b * b; }
;                     *(u32x4*)(Hd + (size_t)(row0 + ai * 128 + m * 16) * DFF + col0 + bj * 128) = pack8(v0, v1);
;                 }
;             }
;     }
	v_max_f32_e32 v118, 0, v118
	v_mul_f32_e32 v114, v114, v114
	v_mul_f32_e32 v119, v115, v115
	v_max_f32_e32 v115, 0, v120
	v_mul_f32_e32 v120, v116, v116
	v_max_f32_e32 v116, 0, v121
	v_max_f32_e32 v117, 0, v117
	v_mul_f32_e32 v118, v118, v118
	v_mul_f32_e32 v115, v115, v115
	v_mul_f32_e32 v116, v116, v116
	v_mul_f32_e32 v117, v117, v117
	v_cvt_pk_bf16_f32 v114, v118, v114
	v_cvt_pk_bf16_f32 v115, v115, v116
	v_cvt_pk_bf16_f32 v116, v126, v119
	v_cvt_pk_bf16_f32 v117, v120, v117
	global_store_dwordx4 v[122:123], v[114:117], off offset:256
	s_nop 1
	v_fmamk_f32 v114, v163, 0x3a000000, v251
	v_cmp_gt_f32_e32 vcc, s38, v114
	v_mul_f32_e32 v115, 0x4b800000, v114
	v_lshlrev_b64 v[116:117], 14, v[146:147]
	v_cndmask_b32_e32 v114, v114, v115, vcc
	v_rsq_f32_e32 v114, v114
	s_nop 0
	v_mul_f32_e32 v115, 0x45800000, v114
	v_cndmask_b32_e32 v114, v114, v115, vcc
	v_pk_mul_f32 v[108:109], v[108:109], v[114:115] op_sel_hi:[1,0]
	v_pk_mul_f32 v[106:107], v[106:107], v[114:115] op_sel_hi:[1,0]
	v_pk_mul_f32 v[112:113], v[112:113], v[114:115] op_sel_hi:[1,0]
	v_pk_mul_f32 v[110:111], v[110:111], v[114:115] op_sel_hi:[1,0]
	v_max_f32_e32 v106, 0, v106
	v_max_f32_e32 v107, 0, v107
	v_max_f32_e32 v108, 0, v108
	v_max_f32_e32 v110, 0, v110
	v_mul_f32_e32 v115, v106, v106
	v_max_f32_e32 v106, 0, v111
	v_mul_f32_e32 v111, v107, v107
	v_max_f32_e32 v107, 0, v112
	v_mul_f32_e32 v112, v108, v108
	v_max_f32_e32 v108, 0, v113
	v_mul_f32_e32 v110, v110, v110
	v_mul_f32_e32 v106, v106, v106
	v_mul_f32_e32 v107, v107, v107
	v_mul_f32_e32 v108, v108, v108
	v_max_f32_e32 v109, 0, v109
	v_cvt_pk_bf16_f32 v106, v110, v106
	v_cvt_pk_bf16_f32 v107, v107, v108
	v_cvt_pk_bf16_f32 v108, v115, v111
	v_lshl_add_u64 v[110:111], s[30:31], 0, v[116:117]
	v_pk_mul_f32 v[98:99], v[98:99], v[114:115] op_sel_hi:[1,0]
	v_mul_f32_e32 v109, v109, v109
	v_lshl_add_u64 v[110:111], v[110:111], 0, v[124:125]
	v_pk_mul_f32 v[102:103], v[102:103], v[114:115] op_sel_hi:[1,0]
	v_pk_mul_f32 v[100:101], v[100:101], v[114:115] op_sel_hi:[1,0]
	v_max_f32_e32 v98, 0, v98
	v_cvt_pk_bf16_f32 v109, v112, v109
	global_store_dwordx4 v[110:111], v[106:109], off
	v_pk_mul_f32 v[104:105], v[104:105], v[114:115] op_sel_hi:[1,0]
	v_max_f32_e32 v99, 0, v99
	v_mul_f32_e32 v106, v98, v98
	v_max_f32_e32 v98, 0, v103
	v_max_f32_e32 v100, 0, v100
	v_max_f32_e32 v102, 0, v102
	v_mul_f32_e32 v98, v98, v98
	v_mul_f32_e32 v103, v99, v99
	v_max_f32_e32 v99, 0, v104
	v_mul_f32_e32 v104, v100, v100
	v_max_f32_e32 v100, 0, v105
	v_max_f32_e32 v101, 0, v101
	v_mul_f32_e32 v102, v102, v102
	v_mul_f32_e32 v99, v99, v99
	v_mul_f32_e32 v100, v100, v100
	v_mul_f32_e32 v101, v101, v101
	v_cvt_pk_bf16_f32 v98, v102, v98
	v_cvt_pk_bf16_f32 v99, v99, v100
	v_cvt_pk_bf16_f32 v100, v106, v103
	v_cvt_pk_bf16_f32 v101, v104, v101
	global_store_dwordx4 v[110:111], v[98:101], off offset:256
	s_nop 1
	v_fmamk_f32 v98, v156, 0x3a000000, v251
	v_cmp_gt_f32_e32 vcc, s38, v98
	v_mul_f32_e32 v99, 0x4b800000, v98
	v_lshlrev_b64 v[100:101], 14, v[144:145]
	v_cndmask_b32_e32 v98, v98, v99, vcc
	v_rsq_f32_e32 v98, v98
	s_nop 0
	v_mul_f32_e32 v99, 0x45800000, v98
	v_cndmask_b32_e32 v98, v98, v99, vcc
	v_pk_mul_f32 v[92:93], v[92:93], v[98:99] op_sel_hi:[1,0]
	v_pk_mul_f32 v[90:91], v[90:91], v[98:99] op_sel_hi:[1,0]
	v_pk_mul_f32 v[96:97], v[96:97], v[98:99] op_sel_hi:[1,0]
	v_pk_mul_f32 v[94:95], v[94:95], v[98:99] op_sel_hi:[1,0]
	v_max_f32_e32 v90, 0, v90
	v_max_f32_e32 v91, 0, v91
	v_max_f32_e32 v92, 0, v92
	v_max_f32_e32 v94, 0, v94
	v_mul_f32_e32 v99, v90, v90
	v_max_f32_e32 v90, 0, v95
	v_mul_f32_e32 v95, v91, v91
	v_max_f32_e32 v91, 0, v96
	v_mul_f32_e32 v96, v92, v92
	v_max_f32_e32 v92, 0, v97
	v_mul_f32_e32 v94, v94, v94
	v_mul_f32_e32 v90, v90, v90
	v_mul_f32_e32 v91, v91, v91
	v_mul_f32_e32 v92, v92, v92
	v_max_f32_e32 v93, 0, v93
	v_cvt_pk_bf16_f32 v90, v94, v90
	v_cvt_pk_bf16_f32 v91, v91, v92
	v_cvt_pk_bf16_f32 v92, v99, v95
	v_lshl_add_u64 v[94:95], s[30:31], 0, v[100:101]
	v_pk_mul_f32 v[82:83], v[82:83], v[98:99] op_sel_hi:[1,0]
	v_mul_f32_e32 v93, v93, v93
	v_lshl_add_u64 v[94:95], v[94:95], 0, v[124:125]
	v_pk_mul_f32 v[86:87], v[86:87], v[98:99] op_sel_hi:[1,0]
	v_pk_mul_f32 v[84:85], v[84:85], v[98:99] op_sel_hi:[1,0]
	v_max_f32_e32 v82, 0, v82
	v_cvt_pk_bf16_f32 v93, v96, v93
	global_store_dwordx4 v[94:95], v[90:93], off
	v_pk_mul_f32 v[88:89], v[88:89], v[98:99] op_sel_hi:[1,0]
	v_max_f32_e32 v83, 0, v83
	v_mul_f32_e32 v90, v82, v82
	v_max_f32_e32 v82, 0, v87
	v_max_f32_e32 v84, 0, v84
	v_max_f32_e32 v86, 0, v86
	v_mul_f32_e32 v82, v82, v82
	v_mul_f32_e32 v87, v83, v83
	v_max_f32_e32 v83, 0, v88
	v_mul_f32_e32 v88, v84, v84
	v_max_f32_e32 v84, 0, v89
	v_max_f32_e32 v85, 0, v85
	v_mul_f32_e32 v86, v86, v86
	v_mul_f32_e32 v83, v83, v83
	v_mul_f32_e32 v84, v84, v84
	v_mul_f32_e32 v85, v85, v85
	v_cvt_pk_bf16_f32 v82, v86, v82
	v_cvt_pk_bf16_f32 v83, v83, v84
	v_cvt_pk_bf16_f32 v84, v90, v87
	v_cvt_pk_bf16_f32 v85, v88, v85
	global_store_dwordx4 v[94:95], v[82:85], off offset:256
	s_nop 1
	v_fmamk_f32 v82, v155, 0x3a000000, v251
	v_cmp_gt_f32_e32 vcc, s38, v82
	v_mul_f32_e32 v83, 0x4b800000, v82
	v_lshlrev_b64 v[84:85], 14, v[142:143]
	v_cndmask_b32_e32 v82, v82, v83, vcc
	v_rsq_f32_e32 v82, v82
	s_nop 0
	v_mul_f32_e32 v83, 0x45800000, v82
	v_cndmask_b32_e32 v82, v82, v83, vcc
	v_pk_mul_f32 v[76:77], v[76:77], v[82:83] op_sel_hi:[1,0]
	v_pk_mul_f32 v[74:75], v[74:75], v[82:83] op_sel_hi:[1,0]
	v_pk_mul_f32 v[80:81], v[80:81], v[82:83] op_sel_hi:[1,0]
	v_pk_mul_f32 v[78:79], v[78:79], v[82:83] op_sel_hi:[1,0]
	v_max_f32_e32 v74, 0, v74
	v_max_f32_e32 v75, 0, v75
	v_max_f32_e32 v76, 0, v76
	v_max_f32_e32 v78, 0, v78
; __device__ __forceinline__ float rstd_of(float ss) { return rsqrtf(ss * (1.0f / DM) + EPS); }
; __device__ __forceinline__ u32x4 pack8(const f32x4 a, const f32x4 b) { u32x4 w; w.x = cvt_pk_bf16(a[0], a[1]); w.y = cvt_pk_bf16(a[2], a[3]); w.z = cvt_pk_bf16(b[0], b[1]); w.w = cvt_pk_bf16(b[2], b[3]); return w; }
;     __device__ __forceinline__ void operator()(const AccT& acc, const Unit& u, int wr, int wc, int fr, int fq) const {
;         const int row0 = u.pm * 256 + wr * 64 + fr, col0 = u.pn * 256 + wc * 32 + 8 * fq;
;         float rsv[2][4];
; #pragma unroll
;         for (int ai = 0; ai < 2; ++ai)
; #pragma unroll
;             for (int m = 0; m < 4; ++m) rsv[ai][m] = SS[row0 + ai * 128 + m * 16];
; #pragma unroll
;         for (int ai = 0; ai < 2; ++ai)
; #pragma unroll
;             for (int m = 0; m < 4; ++m) {
;                 const float rs = rstd_of(rsv[ai][m]);
; #pragma unroll
;                 for (int bj = 0; bj < 2; ++bj) {
;                     f32x4 v0 = acc[ai][bj][m][0] * rs, v1 = acc[ai][bj][m][1] * rs;
; #pragma unroll
;                     for (int j = 0; j < 4; ++j) { const float a = fmaxf(v0[j], 0.f), b = fmaxf(v1[j], 0.f); v0[j] = a * a; v1[j] = b * b; }
;                     *(u32x4*)(Hd + (size_t)(row0 + ai * 128 + m * 16) * DFF + col0 + bj * 128) = pack8(v0, v1);
;                 }
;             }
;     }
	v_mul_f32_e32 v83, v74, v74
	v_max_f32_e32 v74, 0, v79
	v_mul_f32_e32 v79, v75, v75
	v_max_f32_e32 v75, 0, v80
	v_mul_f32_e32 v80, v76, v76
	v_max_f32_e32 v76, 0, v81
	v_mul_f32_e32 v78, v78, v78
	v_mul_f32_e32 v74, v74, v74
	v_mul_f32_e32 v75, v75, v75
	v_mul_f32_e32 v76, v76, v76
	v_max_f32_e32 v77, 0, v77
	v_cvt_pk_bf16_f32 v74, v78, v74
	v_cvt_pk_bf16_f32 v75, v75, v76
	v_cvt_pk_bf16_f32 v76, v83, v79
	v_lshl_add_u64 v[78:79], s[30:31], 0, v[84:85]
	v_pk_mul_f32 v[66:67], v[66:67], v[82:83] op_sel_hi:[1,0]
	v_mul_f32_e32 v77, v77, v77
	v_lshl_add_u64 v[78:79], v[78:79], 0, v[124:125]
	v_pk_mul_f32 v[70:71], v[70:71], v[82:83] op_sel_hi:[1,0]
	v_pk_mul_f32 v[68:69], v[68:69], v[82:83] op_sel_hi:[1,0]
	v_max_f32_e32 v66, 0, v66
	v_cvt_pk_bf16_f32 v77, v80, v77
	global_store_dwordx4 v[78:79], v[74:77], off
	v_pk_mul_f32 v[72:73], v[72:73], v[82:83] op_sel_hi:[1,0]
	v_max_f32_e32 v67, 0, v67
	v_mul_f32_e32 v74, v66, v66
	v_max_f32_e32 v66, 0, v71
	v_max_f32_e32 v68, 0, v68
	v_max_f32_e32 v70, 0, v70
	v_mul_f32_e32 v66, v66, v66
	v_mul_f32_e32 v71, v67, v67
	v_max_f32_e32 v67, 0, v72
	v_mul_f32_e32 v72, v68, v68
	v_max_f32_e32 v68, 0, v73
	v_max_f32_e32 v69, 0, v69
	v_mul_f32_e32 v70, v70, v70
	v_mul_f32_e32 v67, v67, v67
	v_mul_f32_e32 v68, v68, v68
	v_mul_f32_e32 v69, v69, v69
	v_cvt_pk_bf16_f32 v66, v70, v66
	v_cvt_pk_bf16_f32 v67, v67, v68
	v_cvt_pk_bf16_f32 v68, v74, v71
	v_cvt_pk_bf16_f32 v69, v72, v69
	global_store_dwordx4 v[78:79], v[66:69], off offset:256
	s_nop 1
	v_fmamk_f32 v66, v154, 0x3a000000, v251
	v_cmp_gt_f32_e32 vcc, s38, v66
	v_mul_f32_e32 v67, 0x4b800000, v66
	s_nop 0
	v_cndmask_b32_e32 v66, v66, v67, vcc
	v_rsq_f32_e32 v66, v66
	s_nop 0
	v_mul_f32_e32 v67, 0x45800000, v66
	v_cndmask_b32_e32 v66, v66, v67, vcc
	v_pk_mul_f32 v[60:61], v[60:61], v[66:67] op_sel_hi:[1,0]
	v_pk_mul_f32 v[58:59], v[58:59], v[66:67] op_sel_hi:[1,0]
	v_pk_mul_f32 v[64:65], v[64:65], v[66:67] op_sel_hi:[1,0]
	v_pk_mul_f32 v[62:63], v[62:63], v[66:67] op_sel_hi:[1,0]
	v_max_f32_e32 v58, 0, v58
	v_max_f32_e32 v59, 0, v59
	v_max_f32_e32 v60, 0, v60
	v_max_f32_e32 v61, 0, v61
	v_mul_f32_e32 v67, v58, v58
	v_max_f32_e32 v58, 0, v63
	v_mul_f32_e32 v63, v59, v59
	v_max_f32_e32 v59, 0, v64
	v_mul_f32_e32 v64, v60, v60
	v_mul_f32_e32 v61, v61, v61
	v_max_f32_e32 v62, 0, v62
	v_mul_f32_e32 v58, v58, v58
	v_max_f32_e32 v60, 0, v65
	v_cvt_pk_bf16_f32 v61, v64, v61
	v_add_co_u32_e32 v64, vcc, s39, v122
	v_pk_mul_f32 v[50:51], v[50:51], v[66:67] op_sel_hi:[1,0]
	v_mul_f32_e32 v62, v62, v62
	v_mul_f32_e32 v59, v59, v59
	v_mul_f32_e32 v60, v60, v60
	v_cvt_pk_bf16_f32 v58, v62, v58
	v_addc_co_u32_e32 v65, vcc, 0, v123, vcc
	v_pk_mul_f32 v[54:55], v[54:55], v[66:67] op_sel_hi:[1,0]
	v_pk_mul_f32 v[52:53], v[52:53], v[66:67] op_sel_hi:[1,0]
	v_max_f32_e32 v50, 0, v50
	v_cvt_pk_bf16_f32 v59, v59, v60
	v_cvt_pk_bf16_f32 v60, v67, v63
	global_store_dwordx4 v[64:65], v[58:61], off
	v_pk_mul_f32 v[56:57], v[56:57], v[66:67] op_sel_hi:[1,0]
	v_max_f32_e32 v51, 0, v51
	v_mul_f32_e32 v58, v50, v50
	v_max_f32_e32 v50, 0, v55
	v_max_f32_e32 v52, 0, v52
	v_max_f32_e32 v54, 0, v54
	v_mul_f32_e32 v50, v50, v50
	v_mul_f32_e32 v55, v51, v51
	v_max_f32_e32 v51, 0, v56
	v_mul_f32_e32 v56, v52, v52
	v_max_f32_e32 v52, 0, v57
	v_max_f32_e32 v53, 0, v53
	v_lshl_add_u64 v[62:63], v[122:123], 0, s[10:11]
	v_mul_f32_e32 v54, v54, v54
	v_mul_f32_e32 v51, v51, v51
	v_mul_f32_e32 v52, v52, v52
	v_mul_f32_e32 v53, v53, v53
	v_cvt_pk_bf16_f32 v50, v54, v50
	v_cvt_pk_bf16_f32 v51, v51, v52
	v_cvt_pk_bf16_f32 v52, v58, v55
	v_cvt_pk_bf16_f32 v53, v56, v53
	global_store_dwordx4 v[62:63], v[50:53], off offset:256
	s_mov_b64 s[10:11], 0x280000
	s_nop 0
	v_fmamk_f32 v50, v153, 0x3a000000, v251
	v_cmp_gt_f32_e32 vcc, s38, v50
	v_mul_f32_e32 v51, 0x4b800000, v50
	s_nop 0
	v_cndmask_b32_e32 v50, v50, v51, vcc
	v_rsq_f32_e32 v50, v50
	s_nop 0
	v_mul_f32_e32 v51, 0x45800000, v50
	v_cndmask_b32_e32 v50, v50, v51, vcc
	v_pk_mul_f32 v[44:45], v[44:45], v[50:51] op_sel_hi:[1,0]
	v_pk_mul_f32 v[42:43], v[42:43], v[50:51] op_sel_hi:[1,0]
	v_pk_mul_f32 v[48:49], v[48:49], v[50:51] op_sel_hi:[1,0]
	v_pk_mul_f32 v[46:47], v[46:47], v[50:51] op_sel_hi:[1,0]
	v_max_f32_e32 v42, 0, v42
	v_max_f32_e32 v43, 0, v43
	v_max_f32_e32 v44, 0, v44
	v_max_f32_e32 v45, 0, v45
	v_mul_f32_e32 v51, v42, v42
	v_max_f32_e32 v42, 0, v47
	v_mul_f32_e32 v47, v43, v43
	v_max_f32_e32 v43, 0, v48
	v_mul_f32_e32 v48, v44, v44
	v_mul_f32_e32 v45, v45, v45
	v_max_f32_e32 v46, 0, v46
	v_mul_f32_e32 v42, v42, v42
	v_max_f32_e32 v44, 0, v49
	v_cvt_pk_bf16_f32 v45, v48, v45
	v_add_co_u32_e32 v48, vcc, s63, v122
	v_pk_mul_f32 v[34:35], v[34:35], v[50:51] op_sel_hi:[1,0]
	v_mul_f32_e32 v46, v46, v46
	v_mul_f32_e32 v43, v43, v43
	v_mul_f32_e32 v44, v44, v44
	v_cvt_pk_bf16_f32 v42, v46, v42
	v_addc_co_u32_e32 v49, vcc, 0, v123, vcc
	v_pk_mul_f32 v[38:39], v[38:39], v[50:51] op_sel_hi:[1,0]
	v_pk_mul_f32 v[36:37], v[36:37], v[50:51] op_sel_hi:[1,0]
	v_max_f32_e32 v34, 0, v34
	v_cvt_pk_bf16_f32 v43, v43, v44
	v_cvt_pk_bf16_f32 v44, v51, v47
	global_store_dwordx4 v[48:49], v[42:45], off
; __device__ __forceinline__ float rstd_of(float ss) { return rsqrtf(ss * (1.0f / DM) + EPS); }
; __device__ __forceinline__ u32x4 pack8(const f32x4 a, const f32x4 b) { u32x4 w; w.x = cvt_pk_bf16(a[0], a[1]); w.y = cvt_pk_bf16(a[2], a[3]); w.z = cvt_pk_bf16(b[0], b[1]); w.w = cvt_pk_bf16(b[2], b[3]); return w; }
; #define PG8_WAIT_V(n) asm volatile("s_waitcnt vmcnt(" #n ")" ::: "memory")
; #define PG8_BAR __builtin_amdgcn_s_barrier()
; template <class Epi, class Sched>
; __device__ __forceinline__ void gemm_phase(LAS unsigned char* lds_in, const int lda, const int ldb, const Sched& S, const Epi& E, const int WID) {
;     ...
;         E(acc, cur, wr, wc, fr, fq);
;         if (!has_next) break;
; #pragma unroll
;         for (int a = 0; a < 2; ++a)
; #pragma unroll
;             for (int b = 0; b < 2; ++b)
; #pragma unroll
;                 for (int m = 0; m < 4; ++m)
; #pragma unroll
;                     for (int n = 0; n < 2; ++n) acc[a][b][m][n] = (f32x4){0.f, 0.f, 0.f, 0.f};
;         cur = nxt; cA = nA; cB = nB; ++ui;
;     }
;     PG8_WAIT_V(0);
;     if (wr == 0) PG8_BAR;
;     PG8_BAR;
;     __device__ __forceinline__ void operator()(const AccT& acc, const Unit& u, int wr, int wc, int fr, int fq) const {
;         const int row0 = u.pm * 256 + wr * 64 + fr, col0 = u.pn * 256 + wc * 32 + 8 * fq;
;         float rsv[2][4];
; #pragma unroll
;         for (int ai = 0; ai < 2; ++ai)
; #pragma unroll
;             for (int m = 0; m < 4; ++m) rsv[ai][m] = SS[row0 + ai * 128 + m * 16];
; #pragma unroll
;         for (int ai = 0; ai < 2; ++ai)
; #pragma unroll
;             for (int m = 0; m < 4; ++m) {
;                 const float rs = rstd_of(rsv[ai][m]);
; #pragma unroll
;                 for (int bj = 0; bj < 2; ++bj) {
;                     f32x4 v0 = acc[ai][bj][m][0] * rs, v1 = acc[ai][bj][m][1] * rs;
; #pragma unroll
;                     for (int j = 0; j < 4; ++j) { const float a = fmaxf(v0[j], 0.f), b = fmaxf(v1[j], 0.f); v0[j] = a * a; v1[j] = b * b; }
;                     *(u32x4*)(Hd + (size_t)(row0 + ai * 128 + m * 16) * DFF + col0 + bj * 128) = pack8(v0, v1);
;                 }
;             }
;     }
	v_pk_mul_f32 v[40:41], v[40:41], v[50:51] op_sel_hi:[1,0]
	v_max_f32_e32 v35, 0, v35
	v_mul_f32_e32 v42, v34, v34
	v_max_f32_e32 v34, 0, v39
	v_max_f32_e32 v36, 0, v36
	v_max_f32_e32 v38, 0, v38
	v_mul_f32_e32 v34, v34, v34
	v_mul_f32_e32 v39, v35, v35
	v_max_f32_e32 v35, 0, v40
	v_mul_f32_e32 v40, v36, v36
	v_max_f32_e32 v36, 0, v41
	v_max_f32_e32 v37, 0, v37
	v_lshl_add_u64 v[46:47], v[122:123], 0, s[52:53]
	v_mul_f32_e32 v38, v38, v38
	v_mul_f32_e32 v35, v35, v35
	v_mul_f32_e32 v36, v36, v36
	v_mul_f32_e32 v37, v37, v37
	v_cvt_pk_bf16_f32 v34, v38, v34
	v_cvt_pk_bf16_f32 v35, v35, v36
	v_cvt_pk_bf16_f32 v36, v42, v39
	v_cvt_pk_bf16_f32 v37, v40, v37
	global_store_dwordx4 v[46:47], v[34:37], off offset:256
	s_nop 1
	v_fmamk_f32 v34, v152, 0x3a000000, v251
	v_cmp_gt_f32_e32 vcc, s38, v34
	v_mul_f32_e32 v35, 0x4b800000, v34
	s_nop 0
	v_cndmask_b32_e32 v34, v34, v35, vcc
	v_rsq_f32_e32 v34, v34
	s_nop 0
	v_mul_f32_e32 v35, 0x45800000, v34
	v_cndmask_b32_e32 v34, v34, v35, vcc
	v_pk_mul_f32 v[28:29], v[28:29], v[34:35] op_sel_hi:[1,0]
	v_pk_mul_f32 v[26:27], v[26:27], v[34:35] op_sel_hi:[1,0]
	v_pk_mul_f32 v[32:33], v[32:33], v[34:35] op_sel_hi:[1,0]
	v_pk_mul_f32 v[30:31], v[30:31], v[34:35] op_sel_hi:[1,0]
	v_max_f32_e32 v26, 0, v26
	v_max_f32_e32 v27, 0, v27
	v_max_f32_e32 v28, 0, v28
	v_max_f32_e32 v29, 0, v29
	v_mul_f32_e32 v35, v26, v26
	v_max_f32_e32 v26, 0, v31
	v_mul_f32_e32 v31, v27, v27
	v_max_f32_e32 v27, 0, v32
	v_mul_f32_e32 v32, v28, v28
	v_mul_f32_e32 v29, v29, v29
	v_max_f32_e32 v30, 0, v30
	v_mul_f32_e32 v26, v26, v26
	v_max_f32_e32 v28, 0, v33
	v_cvt_pk_bf16_f32 v29, v32, v29
	v_add_co_u32_e32 v32, vcc, s36, v122
	v_pk_mul_f32 v[18:19], v[18:19], v[34:35] op_sel_hi:[1,0]
	v_mul_f32_e32 v30, v30, v30
	v_mul_f32_e32 v27, v27, v27
	v_mul_f32_e32 v28, v28, v28
	v_cvt_pk_bf16_f32 v26, v30, v26
	v_addc_co_u32_e32 v33, vcc, 0, v123, vcc
	v_pk_mul_f32 v[22:23], v[22:23], v[34:35] op_sel_hi:[1,0]
	v_pk_mul_f32 v[20:21], v[20:21], v[34:35] op_sel_hi:[1,0]
	v_max_f32_e32 v18, 0, v18
	v_cvt_pk_bf16_f32 v27, v27, v28
	v_cvt_pk_bf16_f32 v28, v35, v31
	global_store_dwordx4 v[32:33], v[26:29], off
	v_pk_mul_f32 v[24:25], v[24:25], v[34:35] op_sel_hi:[1,0]
	v_max_f32_e32 v19, 0, v19
	v_mul_f32_e32 v26, v18, v18
	v_max_f32_e32 v18, 0, v23
	v_max_f32_e32 v20, 0, v20
	v_max_f32_e32 v22, 0, v22
	v_mul_f32_e32 v18, v18, v18
	v_mul_f32_e32 v23, v19, v19
	v_max_f32_e32 v19, 0, v24
	v_mul_f32_e32 v24, v20, v20
	v_max_f32_e32 v20, 0, v25
	v_max_f32_e32 v21, 0, v21
	v_lshl_add_u64 v[30:31], v[122:123], 0, s[10:11]
	v_mul_f32_e32 v22, v22, v22
	v_mul_f32_e32 v19, v19, v19
	v_mul_f32_e32 v20, v20, v20
	v_mul_f32_e32 v21, v21, v21
	v_cvt_pk_bf16_f32 v18, v22, v18
	v_cvt_pk_bf16_f32 v19, v19, v20
	v_cvt_pk_bf16_f32 v20, v26, v23
	v_cvt_pk_bf16_f32 v21, v24, v21
	global_store_dwordx4 v[30:31], v[18:21], off offset:256
	s_mov_b64 s[10:11], 0x2c0000
	s_nop 0
	v_fmamk_f32 v18, v151, 0x3a000000, v251
	v_cmp_gt_f32_e32 vcc, s38, v18
	v_mul_f32_e32 v19, 0x4b800000, v18
	s_nop 0
	v_cndmask_b32_e32 v18, v18, v19, vcc
	v_rsq_f32_e32 v18, v18
	s_nop 0
	v_mul_f32_e32 v19, 0x45800000, v18
	v_cndmask_b32_e32 v18, v18, v19, vcc
	v_pk_mul_f32 v[12:13], v[12:13], v[18:19] op_sel_hi:[1,0]
	v_pk_mul_f32 v[10:11], v[10:11], v[18:19] op_sel_hi:[1,0]
	v_pk_mul_f32 v[16:17], v[16:17], v[18:19] op_sel_hi:[1,0]
	v_pk_mul_f32 v[14:15], v[14:15], v[18:19] op_sel_hi:[1,0]
	v_max_f32_e32 v10, 0, v10
	v_max_f32_e32 v11, 0, v11
	v_max_f32_e32 v12, 0, v12
	v_max_f32_e32 v13, 0, v13
	v_mul_f32_e32 v19, v10, v10
	v_max_f32_e32 v10, 0, v15
	v_mul_f32_e32 v15, v11, v11
	v_max_f32_e32 v11, 0, v16
	v_mul_f32_e32 v16, v12, v12
	v_mul_f32_e32 v13, v13, v13
	v_max_f32_e32 v14, 0, v14
	v_mul_f32_e32 v10, v10, v10
	v_max_f32_e32 v12, 0, v17
	v_cvt_pk_bf16_f32 v13, v16, v13
	v_add_co_u32_e32 v16, vcc, s3, v122
	v_pk_mul_f32 v[4:5], v[4:5], v[18:19] op_sel_hi:[1,0]
	v_pk_mul_f32 v[2:3], v[2:3], v[18:19] op_sel_hi:[1,0]
	v_mul_f32_e32 v14, v14, v14
	v_mul_f32_e32 v11, v11, v11
	v_mul_f32_e32 v12, v12, v12
	v_cvt_pk_bf16_f32 v10, v14, v10
	v_addc_co_u32_e32 v17, vcc, 0, v123, vcc
	v_pk_mul_f32 v[8:9], v[8:9], v[18:19] op_sel_hi:[1,0]
	v_pk_mul_f32 v[6:7], v[6:7], v[18:19] op_sel_hi:[1,0]
	v_max_f32_e32 v2, 0, v2
	v_max_f32_e32 v3, 0, v3
	v_max_f32_e32 v4, 0, v4
	v_cvt_pk_bf16_f32 v11, v11, v12
	v_cvt_pk_bf16_f32 v12, v19, v15
	global_store_dwordx4 v[16:17], v[10:13], off
	v_max_f32_e32 v5, 0, v5
	v_lshl_add_u64 v[14:15], v[122:123], 0, s[10:11]
	v_mul_f32_e32 v10, v2, v2
	v_max_f32_e32 v2, 0, v7
	v_mul_f32_e32 v7, v3, v3
	v_max_f32_e32 v3, 0, v8
	v_mul_f32_e32 v8, v4, v4
	v_max_f32_e32 v4, 0, v9
	v_max_f32_e32 v6, 0, v6
	v_mul_f32_e32 v2, v2, v2
	v_mul_f32_e32 v3, v3, v3
	v_mul_f32_e32 v4, v4, v4
	v_mul_f32_e32 v5, v5, v5
	s_and_b64 vcc, exec, s[0:1]
	s_mov_b64 s[10:11], s[4:5]
	v_mul_f32_e32 v6, v6, v6
	v_cvt_pk_bf16_f32 v2, v6, v2
	v_cvt_pk_bf16_f32 v3, v3, v4
	v_cvt_pk_bf16_f32 v4, v10, v7
	v_cvt_pk_bf16_f32 v5, v8, v5
	global_store_dwordx4 v[14:15], v[2:5], off offset:256
	s_cbranch_vccz .LBB0_260
	s_waitcnt vmcnt(0)
	s_cmpk_gt_u32 s16, 0xff
	s_cbranch_scc1 .LBB0_271
	s_barrier

; #define PG8_STAGE(bufoff, gbase, voff) do { _Pragma("unroll") for (int _i = 0; _i < 2; ++_i) \
;         __builtin_amdgcn_global_load_lds((const unsigned*)((const char*)(gbase) + (voff)[_i]), (LAS unsigned*)(lds + (bufoff) + ldsw + _i * 8192), 16, 0, 0); } while (0)
; #define PG8_LDA(dst, b, h) do { _Pragma("unroll") for (int m = 0; m < 4; ++m) _Pragma("unroll") for (int k = 0; k < 2; ++k) dst[m][k] = *(const LAS bf16x8*)(lds + PG8_SA(b, h) + aoff + m * 2048 + k * 1024); } while (0)
; #define PG8_WAIT_V(n) asm volatile("s_waitcnt vmcnt(" #n ")" ::: "memory")
; #define PG8_BAR __builtin_amdgcn_s_barrier()
; template <class Epi, class Sched>
; __device__ __forceinline__ void gemm_phase(LAS unsigned char* lds_in, const int lda, const int ldb, const Sched& S, const Epi& E, const int WID) {
;     ...
;         for (int t = tb; t < te; t += 2) {
;             const bool last = (t == nt - 2);
;             const char* a1 = cA + (size_t)(t + 1) * kstep;
;             const char* a2 = last ? nA : cA + (size_t)(t + 2) * kstep; const char* b2 = last ? nB : cB + (size_t)(t + 2) * kstep;
;             const char* a3 = a2 + kstep; const char* b3 = b2 + kstep;
;             PG8_LDB(B0, 0, 0); PG8_SCHED; PG8_LDA(At, 0, 0); PG8_STAGE(PG8_SA(1, 1), a1 + hstepA, voffA);
;             PG8_WAIT_L(8); PG8_BAR; PG8_WAIT_L(0); PG8_MMA(0, 0, At, B0); PG8_BAR; PG8_SCHED;
;             PG8_LDB(B1, 0, 1); PG8_STAGE(PG8_SB(0, 0), b2, voffB);
;             PG8_BAR; PG8_WAIT_L(0); PG8_MMA(0, 1, At, B1); PG8_BAR;
;             PG8_LDA(At, 0, 1); PG8_STAGE(PG8_SA(0, 0), a2, voffA);
;             PG8_BAR; PG8_WAIT_L(0); PG8_MMA(1, 0, At, B0); PG8_BAR; PG8_SCHED;
;             PG8_STAGE(PG8_SB(0, 1), b2 + hstepB, voffB);
;             PG8_WAIT_V(6); PG8_BAR; PG8_MMA(1, 1, At, B1); PG8_BAR;
;             PG8_LDB(B0, 1, 0); PG8_SCHED; PG8_LDA(At, 1, 0); PG8_STAGE(PG8_SA(0, 1), a2 + hstepA, voffA);
;             PG8_WAIT_L(8); PG8_BAR; PG8_WAIT_L(0); PG8_MMA(0, 0, At, B0); PG8_BAR; PG8_SCHED;
;             PG8_LDB(B1, 1, 1); PG8_STAGE(PG8_SB(1, 0), b3, voffB);
;             PG8_BAR; PG8_WAIT_L(0); PG8_MMA(0, 1, At, B1); PG8_BAR;
;             PG8_LDA(At, 1, 1); PG8_STAGE(PG8_SA(1, 0), a3, voffA);
;             PG8_BAR; PG8_WAIT_L(0); PG8_MMA(1, 0, At, B0); PG8_BAR; PG8_SCHED;
;             PG8_STAGE(PG8_SB(1, 1), b3 + hstepB, voffB);
;             PG8_WAIT_V(6); PG8_BAR; PG8_MMA(1, 1, At, B1); PG8_BAR;
.LBB0_301:
	v_add_u32_e32 v134, s21, v251
	ds_read_b128 v[114:117], v134
	ds_read_b128 v[118:121], v134 offset:1024
	ds_read_b128 v[130:133], v134 offset:2048
	ds_read_b128 v[134:137], v134 offset:3072
	s_add_u32 s14, s12, 0xfff80080
	s_addc_u32 s15, s13, -1
	s_cmp_eq_u32 s97, 28
	s_cselect_b32 s17, s7, s15
	s_cselect_b32 s16, s6, s14
	s_cselect_b32 s15, s9, s11
	s_cselect_b32 s14, s8, s5
	s_add_i32 m0, s35, 0xc000
	ds_read_b128 v[138:141], v253
	ds_read_b128 v[142:145], v253 offset:1024
	ds_read_b128 v[146:149], v253 offset:2048
	ds_read_b128 v[158:161], v253 offset:3072
	ds_read_b128 v[162:165], v253 offset:4096
	ds_read_b128 v[166:169], v253 offset:5120
	ds_read_b128 v[170:173], v253 offset:6144
	ds_read_b128 v[174:177], v253 offset:7168
	global_load_lds_dwordx4 v202, s[12:13]
	s_add_i32 m0, s35, 0xe000
	s_nop 0
	global_load_lds_dwordx4 v204, s[12:13]
	s_waitcnt lgkmcnt(8)
	s_barrier
	s_waitcnt lgkmcnt(0)
	s_setprio 1
	s_waitcnt lgkmcnt(0)
	v_mfma_f32_16x16x32_bf16 v[154:157], v[114:117], v[138:141], v[154:157]
	v_mfma_f32_16x16x32_bf16 v[150:153], v[130:133], v[138:141], v[150:153]
	v_mfma_f32_16x16x32_bf16 v[110:113], v[114:117], v[146:149], v[110:113]
	v_mfma_f32_16x16x32_bf16 v[106:109], v[130:133], v[146:149], v[106:109]
	v_mfma_f32_16x16x32_bf16 v[94:97], v[114:117], v[162:165], v[94:97]
	v_mfma_f32_16x16x32_bf16 v[90:93], v[130:133], v[162:165], v[90:93]
	v_mfma_f32_16x16x32_bf16 v[78:81], v[114:117], v[170:173], v[78:81]
	v_mfma_f32_16x16x32_bf16 v[74:77], v[130:133], v[170:173], v[74:77]
	v_mfma_f32_16x16x32_bf16 v[154:157], v[118:121], v[142:145], v[154:157]
	v_mfma_f32_16x16x32_bf16 v[150:153], v[134:137], v[142:145], v[150:153]
	v_mfma_f32_16x16x32_bf16 v[110:113], v[118:121], v[158:161], v[110:113]
	v_mfma_f32_16x16x32_bf16 v[106:109], v[134:137], v[158:161], v[106:109]
	v_mfma_f32_16x16x32_bf16 v[94:97], v[118:121], v[166:169], v[94:97]
	v_mfma_f32_16x16x32_bf16 v[90:93], v[134:137], v[166:169], v[90:93]
	v_mfma_f32_16x16x32_bf16 v[78:81], v[118:121], v[174:177], v[78:81]
	v_mfma_f32_16x16x32_bf16 v[74:77], v[134:137], v[174:177], v[74:77]
	s_setprio 0
	s_barrier
	s_mov_b32 m0, s22
	v_add_u32_e32 v190, s47, v251
	ds_read_b128 v[178:181], v190
	ds_read_b128 v[182:185], v190 offset:1024
	ds_read_b128 v[186:189], v190 offset:2048
	ds_read_b128 v[190:193], v190 offset:3072
	global_load_lds_dwordx4 v196, s[14:15]
	s_mov_b32 m0, s23
	s_nop 0
	global_load_lds_dwordx4 v200, s[14:15]
	s_barrier
	s_waitcnt lgkmcnt(0)
	s_setprio 1
	s_waitcnt lgkmcnt(0)
	v_mfma_f32_16x16x32_bf16 v[126:129], v[178:181], v[138:141], v[126:129]
	v_mfma_f32_16x16x32_bf16 v[122:125], v[186:189], v[138:141], v[122:125]
	v_mfma_f32_16x16x32_bf16 v[102:105], v[178:181], v[146:149], v[102:105]
	v_mfma_f32_16x16x32_bf16 v[98:101], v[186:189], v[146:149], v[98:101]
	v_mfma_f32_16x16x32_bf16 v[86:89], v[178:181], v[162:165], v[86:89]
	v_mfma_f32_16x16x32_bf16 v[82:85], v[186:189], v[162:165], v[82:85]
	v_mfma_f32_16x16x32_bf16 v[70:73], v[178:181], v[170:173], v[70:73]
	v_mfma_f32_16x16x32_bf16 v[66:69], v[186:189], v[170:173], v[66:69]
	v_mfma_f32_16x16x32_bf16 v[126:129], v[182:185], v[142:145], v[126:129]
	v_mfma_f32_16x16x32_bf16 v[122:125], v[190:193], v[142:145], v[122:125]
	v_mfma_f32_16x16x32_bf16 v[102:105], v[182:185], v[158:161], v[102:105]
	v_mfma_f32_16x16x32_bf16 v[98:101], v[190:193], v[158:161], v[98:101]
	v_mfma_f32_16x16x32_bf16 v[86:89], v[182:185], v[166:169], v[86:89]
	v_mfma_f32_16x16x32_bf16 v[82:85], v[190:193], v[166:169], v[82:85]
	v_mfma_f32_16x16x32_bf16 v[70:73], v[182:185], v[174:177], v[70:73]
	v_mfma_f32_16x16x32_bf16 v[66:69], v[190:193], v[174:177], v[66:69]
	s_setprio 0
	s_mov_b32 m0, s35
	s_barrier
	ds_read_b128 v[138:141], v253 offset:16384
	ds_read_b128 v[142:145], v253 offset:17408
	ds_read_b128 v[146:149], v253 offset:18432
	ds_read_b128 v[158:161], v253 offset:19456
	ds_read_b128 v[162:165], v253 offset:20480
	ds_read_b128 v[166:169], v253 offset:21504
	ds_read_b128 v[170:173], v253 offset:22528
	ds_read_b128 v[174:177], v253 offset:23552
	global_load_lds_dwordx4 v194, s[16:17]
	s_mov_b32 m0, s46
	s_nop 0
	global_load_lds_dwordx4 v198, s[16:17]
	s_barrier
	s_waitcnt lgkmcnt(0)
	s_setprio 1
	s_waitcnt lgkmcnt(0)
	v_mfma_f32_16x16x32_bf16 v[62:65], v[114:117], v[138:141], v[62:65]
	v_mfma_f32_16x16x32_bf16 v[58:61], v[130:133], v[138:141], v[58:61]
	v_mfma_f32_16x16x32_bf16 v[46:49], v[114:117], v[146:149], v[46:49]
	v_mfma_f32_16x16x32_bf16 v[42:45], v[130:133], v[146:149], v[42:45]
	v_mfma_f32_16x16x32_bf16 v[30:33], v[114:117], v[162:165], v[30:33]
	v_mfma_f32_16x16x32_bf16 v[26:29], v[130:133], v[162:165], v[26:29]
	v_mfma_f32_16x16x32_bf16 v[14:17], v[114:117], v[170:173], v[14:17]
	v_mfma_f32_16x16x32_bf16 v[10:13], v[130:133], v[170:173], v[10:13]
	v_mfma_f32_16x16x32_bf16 v[62:65], v[118:121], v[142:145], v[62:65]
	v_mfma_f32_16x16x32_bf16 v[58:61], v[134:137], v[142:145], v[58:61]
	v_mfma_f32_16x16x32_bf16 v[46:49], v[118:121], v[158:161], v[46:49]
	v_mfma_f32_16x16x32_bf16 v[42:45], v[134:137], v[158:161], v[42:45]
	v_mfma_f32_16x16x32_bf16 v[30:33], v[118:121], v[166:169], v[30:33]
	v_mfma_f32_16x16x32_bf16 v[26:29], v[134:137], v[166:169], v[26:29]
	v_mfma_f32_16x16x32_bf16 v[14:17], v[118:121], v[174:177], v[14:17]
	v_mfma_f32_16x16x32_bf16 v[10:13], v[134:137], v[174:177], v[10:13]
	s_setprio 0
	s_barrier
	s_add_u32 s66, s14, 0x80000
	s_addc_u32 s67, s15, 0
	s_mov_b32 m0, s48
	s_nop 0
	global_load_lds_dwordx4 v196, s[66:67]
	s_mov_b32 m0, s49
	s_nop 0
	global_load_lds_dwordx4 v200, s[66:67]
	s_waitcnt vmcnt(6)
	s_barrier
; #define PG8_STAGE(bufoff, gbase, voff) do { _Pragma("unroll") for (int _i = 0; _i < 2; ++_i) \
;         __builtin_amdgcn_global_load_lds((const unsigned*)((const char*)(gbase) + (voff)[_i]), (LAS unsigned*)(lds + (bufoff) + ldsw + _i * 8192), 16, 0, 0); } while (0)
; #define PG8_LDA(dst, b, h) do { _Pragma("unroll") for (int m = 0; m < 4; ++m) _Pragma("unroll") for (int k = 0; k < 2; ++k) dst[m][k] = *(const LAS bf16x8*)(lds + PG8_SA(b, h) + aoff + m * 2048 + k * 1024); } while (0)
; #define PG8_LDB(dst, b, h) do { _Pragma("unroll") for (int n = 0; n < 2; ++n) _Pragma("unroll") for (int k = 0; k < 2; ++k) dst[n][k] = *(const LAS bf16x8*)(lds + PG8_SB(b, h) + boff + n * 2048 + k * 1024); } while (0)
; #define PG8_MMA(ai, bj, At, Bt) do { __builtin_amdgcn_s_setprio(1); _Pragma("unroll") for (int m = 0; m < 4; ++m) _Pragma("unroll") for (int n = 0; n < 2; ++n) _Pragma("unroll") for (int k = 0; k < 2; ++k) \
;         acc[ai][bj][m][n] = __builtin_amdgcn_mfma_f32_16x16x32_bf16(Bt[n][k], At[m][k], acc[ai][bj][m][n], 0, 0, 0); __builtin_amdgcn_s_setprio(0); } while (0)
; #define PG8_WAIT_V(n) asm volatile("s_waitcnt vmcnt(" #n ")" ::: "memory")
; #define PG8_WAIT_L(n) asm volatile("s_waitcnt lgkmcnt(" #n ")" ::: "memory")
; #define PG8_BAR __builtin_amdgcn_s_barrier()
; #define PG8_SCHED __builtin_amdgcn_sched_barrier(0)
; template <class Epi, class Sched>
; __device__ __forceinline__ void gemm_phase(LAS unsigned char* lds_in, const int lda, const int ldb, const Sched& S, const Epi& E, const int WID) {
;     ...
;             PG8_LDB(B0, 1, 0); PG8_SCHED; PG8_LDA(At, 1, 0); PG8_STAGE(PG8_SA(0, 1), a2 + hstepA, voffA);
;             PG8_WAIT_L(8); PG8_BAR; PG8_WAIT_L(0); PG8_MMA(0, 0, At, B0); PG8_BAR; PG8_SCHED;
;             PG8_LDB(B1, 1, 1); PG8_STAGE(PG8_SB(1, 0), b3, voffB);
;             PG8_BAR; PG8_WAIT_L(0); PG8_MMA(0, 1, At, B1); PG8_BAR;
;             PG8_LDA(At, 1, 1); PG8_STAGE(PG8_SA(1, 0), a3, voffA);
;             PG8_BAR; PG8_WAIT_L(0); PG8_MMA(1, 0, At, B0); PG8_BAR; PG8_SCHED;
;             PG8_STAGE(PG8_SB(1, 1), b3 + hstepB, voffB);
;             PG8_WAIT_V(6); PG8_BAR; PG8_MMA(1, 1, At, B1); PG8_BAR;
	s_setprio 1
	v_mfma_f32_16x16x32_bf16 v[54:57], v[178:181], v[138:141], v[54:57]
	v_mfma_f32_16x16x32_bf16 v[50:53], v[186:189], v[138:141], v[50:53]
	v_mfma_f32_16x16x32_bf16 v[38:41], v[178:181], v[146:149], v[38:41]
	v_mfma_f32_16x16x32_bf16 v[34:37], v[186:189], v[146:149], v[34:37]
	v_mfma_f32_16x16x32_bf16 v[22:25], v[178:181], v[162:165], v[22:25]
	v_mfma_f32_16x16x32_bf16 v[18:21], v[186:189], v[162:165], v[18:21]
	v_mfma_f32_16x16x32_bf16 v[6:9], v[178:181], v[170:173], v[6:9]
	v_mfma_f32_16x16x32_bf16 v[2:5], v[186:189], v[170:173], v[2:5]
	v_mfma_f32_16x16x32_bf16 v[54:57], v[182:185], v[142:145], v[54:57]
	v_mfma_f32_16x16x32_bf16 v[50:53], v[190:193], v[142:145], v[50:53]
	v_mfma_f32_16x16x32_bf16 v[38:41], v[182:185], v[158:161], v[38:41]
	v_mfma_f32_16x16x32_bf16 v[34:37], v[190:193], v[158:161], v[34:37]
	v_mfma_f32_16x16x32_bf16 v[22:25], v[182:185], v[166:169], v[22:25]
	v_mfma_f32_16x16x32_bf16 v[18:21], v[190:193], v[166:169], v[18:21]
	v_mfma_f32_16x16x32_bf16 v[6:9], v[182:185], v[174:177], v[6:9]
	v_mfma_f32_16x16x32_bf16 v[2:5], v[190:193], v[174:177], v[2:5]
	s_setprio 0
	v_add_u32_e32 v134, s65, v251
	s_barrier
	ds_read_b128 v[114:117], v134
	ds_read_b128 v[118:121], v134 offset:1024
	ds_read_b128 v[130:133], v134 offset:2048
	ds_read_b128 v[134:137], v134 offset:3072
	s_add_u32 s16, s16, 0x80000
	s_addc_u32 s17, s17, 0
	s_mov_b32 m0, s50
	ds_read_b128 v[138:141], v253 offset:32768
	ds_read_b128 v[142:145], v253 offset:33792
	ds_read_b128 v[146:149], v253 offset:34816
	ds_read_b128 v[158:161], v253 offset:35840
	ds_read_b128 v[162:165], v253 offset:36864
	ds_read_b128 v[166:169], v253 offset:37888
	ds_read_b128 v[170:173], v253 offset:38912
	ds_read_b128 v[174:177], v253 offset:39936
	global_load_lds_dwordx4 v194, s[16:17]
	s_mov_b32 m0, s51
	s_nop 0
	global_load_lds_dwordx4 v198, s[16:17]
	s_waitcnt lgkmcnt(8)
	s_barrier
	s_waitcnt lgkmcnt(0)
	s_setprio 1
	s_waitcnt lgkmcnt(0)
	v_mfma_f32_16x16x32_bf16 v[154:157], v[114:117], v[138:141], v[154:157]
	v_mfma_f32_16x16x32_bf16 v[150:153], v[130:133], v[138:141], v[150:153]
	v_mfma_f32_16x16x32_bf16 v[110:113], v[114:117], v[146:149], v[110:113]
	v_mfma_f32_16x16x32_bf16 v[106:109], v[130:133], v[146:149], v[106:109]
	v_mfma_f32_16x16x32_bf16 v[94:97], v[114:117], v[162:165], v[94:97]
	v_mfma_f32_16x16x32_bf16 v[90:93], v[130:133], v[162:165], v[90:93]
	v_mfma_f32_16x16x32_bf16 v[78:81], v[114:117], v[170:173], v[78:81]
	v_mfma_f32_16x16x32_bf16 v[74:77], v[130:133], v[170:173], v[74:77]
	v_mfma_f32_16x16x32_bf16 v[154:157], v[118:121], v[142:145], v[154:157]
	v_mfma_f32_16x16x32_bf16 v[150:153], v[134:137], v[142:145], v[150:153]
	v_mfma_f32_16x16x32_bf16 v[110:113], v[118:121], v[158:161], v[110:113]
	v_mfma_f32_16x16x32_bf16 v[106:109], v[134:137], v[158:161], v[106:109]
	v_mfma_f32_16x16x32_bf16 v[94:97], v[118:121], v[166:169], v[94:97]
	v_mfma_f32_16x16x32_bf16 v[90:93], v[134:137], v[166:169], v[90:93]
	v_mfma_f32_16x16x32_bf16 v[78:81], v[118:121], v[174:177], v[78:81]
	v_mfma_f32_16x16x32_bf16 v[74:77], v[134:137], v[174:177], v[74:77]
	s_setprio 0
	s_barrier
	s_mov_b32 m0, s70
	v_add_u32_e32 v190, s91, v251
	s_add_u32 s100, s14, 0x80
	s_addc_u32 s101, s15, 0
	ds_read_b128 v[178:181], v190
	ds_read_b128 v[182:185], v190 offset:1024
	ds_read_b128 v[186:189], v190 offset:2048
	ds_read_b128 v[190:193], v190 offset:3072
	global_load_lds_dwordx4 v196, s[100:101]
	s_add_u32 s100, s14, 0x80
	s_addc_u32 s101, s15, 0
	s_mov_b32 m0, s78
	s_nop 0
	global_load_lds_dwordx4 v200, s[100:101]
	s_barrier
	s_waitcnt lgkmcnt(0)
	s_setprio 1
	s_waitcnt lgkmcnt(0)
	v_mfma_f32_16x16x32_bf16 v[126:129], v[178:181], v[138:141], v[126:129]
	v_mfma_f32_16x16x32_bf16 v[122:125], v[186:189], v[138:141], v[122:125]
	v_mfma_f32_16x16x32_bf16 v[102:105], v[178:181], v[146:149], v[102:105]
	v_mfma_f32_16x16x32_bf16 v[98:101], v[186:189], v[146:149], v[98:101]
	v_mfma_f32_16x16x32_bf16 v[86:89], v[178:181], v[162:165], v[86:89]
	v_mfma_f32_16x16x32_bf16 v[82:85], v[186:189], v[162:165], v[82:85]
	v_mfma_f32_16x16x32_bf16 v[70:73], v[178:181], v[170:173], v[70:73]
	v_mfma_f32_16x16x32_bf16 v[66:69], v[186:189], v[170:173], v[66:69]
	v_mfma_f32_16x16x32_bf16 v[126:129], v[182:185], v[142:145], v[126:129]
	v_mfma_f32_16x16x32_bf16 v[122:125], v[190:193], v[142:145], v[122:125]
	v_mfma_f32_16x16x32_bf16 v[102:105], v[182:185], v[158:161], v[102:105]
	v_mfma_f32_16x16x32_bf16 v[98:101], v[190:193], v[158:161], v[98:101]
	v_mfma_f32_16x16x32_bf16 v[86:89], v[182:185], v[166:169], v[86:89]
	v_mfma_f32_16x16x32_bf16 v[82:85], v[190:193], v[166:169], v[82:85]
	v_mfma_f32_16x16x32_bf16 v[70:73], v[182:185], v[174:177], v[70:73]
	v_mfma_f32_16x16x32_bf16 v[66:69], v[190:193], v[174:177], v[66:69]
	s_setprio 0
	s_mov_b32 m0, s79
	s_add_u32 s100, s16, 0xfff80080
	s_addc_u32 s101, s17, -1
	s_barrier
	ds_read_b128 v[138:141], v253 offset:49152
	ds_read_b128 v[142:145], v253 offset:50176
	ds_read_b128 v[146:149], v253 offset:51200
	ds_read_b128 v[158:161], v253 offset:52224
	ds_read_b128 v[162:165], v253 offset:53248
	ds_read_b128 v[166:169], v253 offset:54272
	ds_read_b128 v[170:173], v253 offset:55296
	ds_read_b128 v[174:177], v253 offset:56320
	global_load_lds_dwordx4 v194, s[100:101]
	s_add_u32 s100, s16, 0xfff80080
	s_addc_u32 s101, s17, -1
	s_mov_b32 m0, s90
	s_nop 0
	global_load_lds_dwordx4 v198, s[100:101]
	s_barrier
; #define PG8_STAGE(bufoff, gbase, voff) do { _Pragma("unroll") for (int _i = 0; _i < 2; ++_i) \
;         __builtin_amdgcn_global_load_lds((const unsigned*)((const char*)(gbase) + (voff)[_i]), (LAS unsigned*)(lds + (bufoff) + ldsw + _i * 8192), 16, 0, 0); } while (0)
; #define PG8_LDA(dst, b, h) do { _Pragma("unroll") for (int m = 0; m < 4; ++m) _Pragma("unroll") for (int k = 0; k < 2; ++k) dst[m][k] = *(const LAS bf16x8*)(lds + PG8_SA(b, h) + aoff + m * 2048 + k * 1024); } while (0)
; #define PG8_LDB(dst, b, h) do { _Pragma("unroll") for (int n = 0; n < 2; ++n) _Pragma("unroll") for (int k = 0; k < 2; ++k) dst[n][k] = *(const LAS bf16x8*)(lds + PG8_SB(b, h) + boff + n * 2048 + k * 1024); } while (0)
; #define PG8_MMA(ai, bj, At, Bt) do { __builtin_amdgcn_s_setprio(1); _Pragma("unroll") for (int m = 0; m < 4; ++m) _Pragma("unroll") for (int n = 0; n < 2; ++n) _Pragma("unroll") for (int k = 0; k < 2; ++k) \
;         acc[ai][bj][m][n] = __builtin_amdgcn_mfma_f32_16x16x32_bf16(Bt[n][k], At[m][k], acc[ai][bj][m][n], 0, 0, 0); __builtin_amdgcn_s_setprio(0); } while (0)
; #define PG8_WAIT_V(n) asm volatile("s_waitcnt vmcnt(" #n ")" ::: "memory")
; #define PG8_WAIT_L(n) asm volatile("s_waitcnt lgkmcnt(" #n ")" ::: "memory")
; #define PG8_BAR __builtin_amdgcn_s_barrier()
; #define PG8_SCHED __builtin_amdgcn_sched_barrier(0)
; template <class Epi, class Sched>
; __device__ __forceinline__ void gemm_phase(LAS unsigned char* lds_in, const int lda, const int ldb, const Sched& S, const Epi& E, const int WID) {
;     ...
;             PG8_WAIT_V(6); PG8_BAR; PG8_MMA(1, 1, At, B1); PG8_BAR;
;             PG8_LDB(B0, 1, 0); PG8_SCHED; PG8_LDA(At, 1, 0); PG8_STAGE(PG8_SA(0, 1), a2 + hstepA, voffA);
;             PG8_WAIT_L(8); PG8_BAR; PG8_WAIT_L(0); PG8_MMA(0, 0, At, B0); PG8_BAR; PG8_SCHED;
;             PG8_LDB(B1, 1, 1); PG8_STAGE(PG8_SB(1, 0), b3, voffB);
;             PG8_BAR; PG8_WAIT_L(0); PG8_MMA(0, 1, At, B1); PG8_BAR;
;             PG8_LDA(At, 1, 1); PG8_STAGE(PG8_SA(1, 0), a3, voffA);
;             PG8_BAR; PG8_WAIT_L(0); PG8_MMA(1, 0, At, B0); PG8_BAR; PG8_SCHED;
;             PG8_STAGE(PG8_SB(1, 1), b3 + hstepB, voffB);
;             PG8_WAIT_V(6); PG8_BAR; PG8_MMA(1, 1, At, B1); PG8_BAR;
	s_waitcnt lgkmcnt(0)
	s_setprio 1
	s_waitcnt lgkmcnt(0)
	v_mfma_f32_16x16x32_bf16 v[62:65], v[114:117], v[138:141], v[62:65]
	v_mfma_f32_16x16x32_bf16 v[58:61], v[130:133], v[138:141], v[58:61]
	v_mfma_f32_16x16x32_bf16 v[46:49], v[114:117], v[146:149], v[46:49]
	v_mfma_f32_16x16x32_bf16 v[42:45], v[130:133], v[146:149], v[42:45]
	v_mfma_f32_16x16x32_bf16 v[30:33], v[114:117], v[162:165], v[30:33]
	v_mfma_f32_16x16x32_bf16 v[26:29], v[130:133], v[162:165], v[26:29]
	v_mfma_f32_16x16x32_bf16 v[14:17], v[114:117], v[170:173], v[14:17]
	v_mfma_f32_16x16x32_bf16 v[10:13], v[130:133], v[170:173], v[10:13]
	v_mfma_f32_16x16x32_bf16 v[62:65], v[118:121], v[142:145], v[62:65]
	v_mfma_f32_16x16x32_bf16 v[58:61], v[134:137], v[142:145], v[58:61]
	v_mfma_f32_16x16x32_bf16 v[46:49], v[118:121], v[158:161], v[46:49]
	v_mfma_f32_16x16x32_bf16 v[42:45], v[134:137], v[158:161], v[42:45]
	v_mfma_f32_16x16x32_bf16 v[30:33], v[118:121], v[166:169], v[30:33]
	v_mfma_f32_16x16x32_bf16 v[26:29], v[134:137], v[166:169], v[26:29]
	v_mfma_f32_16x16x32_bf16 v[14:17], v[118:121], v[174:177], v[14:17]
	v_mfma_f32_16x16x32_bf16 v[10:13], v[134:137], v[174:177], v[10:13]
	s_setprio 0
	s_barrier
	s_add_u32 s14, s14, 0x80080
	s_addc_u32 s15, s15, 0
	s_mov_b32 m0, s92
	s_nop 0
	global_load_lds_dwordx4 v196, s[14:15]
	s_mov_b32 m0, s93
	s_nop 0
	global_load_lds_dwordx4 v200, s[14:15]
	s_waitcnt vmcnt(6)
	s_barrier
	s_setprio 1
	v_mfma_f32_16x16x32_bf16 v[54:57], v[178:181], v[138:141], v[54:57]
	v_mfma_f32_16x16x32_bf16 v[50:53], v[186:189], v[138:141], v[50:53]
	v_mfma_f32_16x16x32_bf16 v[38:41], v[178:181], v[146:149], v[38:41]
	v_mfma_f32_16x16x32_bf16 v[34:37], v[186:189], v[146:149], v[34:37]
	v_mfma_f32_16x16x32_bf16 v[22:25], v[178:181], v[162:165], v[22:25]
	v_mfma_f32_16x16x32_bf16 v[18:21], v[186:189], v[162:165], v[18:21]
	v_mfma_f32_16x16x32_bf16 v[6:9], v[178:181], v[170:173], v[6:9]
	v_mfma_f32_16x16x32_bf16 v[2:5], v[186:189], v[170:173], v[2:5]
	v_mfma_f32_16x16x32_bf16 v[54:57], v[182:185], v[142:145], v[54:57]
	v_mfma_f32_16x16x32_bf16 v[50:53], v[190:193], v[142:145], v[50:53]
	v_mfma_f32_16x16x32_bf16 v[38:41], v[182:185], v[158:161], v[38:41]
	v_mfma_f32_16x16x32_bf16 v[34:37], v[190:193], v[158:161], v[34:37]
	v_mfma_f32_16x16x32_bf16 v[22:25], v[182:185], v[166:169], v[22:25]
	v_mfma_f32_16x16x32_bf16 v[18:21], v[190:193], v[166:169], v[18:21]
	v_mfma_f32_16x16x32_bf16 v[6:9], v[182:185], v[174:177], v[6:9]
	v_mfma_f32_16x16x32_bf16 v[2:5], v[190:193], v[174:177], v[2:5]
	s_setprio 0
	s_add_i32 s97, s97, 2
	s_add_u32 s12, s12, 0x100
	s_addc_u32 s13, s13, 0
	s_add_u32 s5, s5, 0x100
	s_addc_u32 s11, s11, 0
	s_cmp_gt_u32 s97, 29
	s_barrier
	s_cbranch_scc0 .LBB0_301
; __device__ __forceinline__ u32x4 pack8(const f32x4 a, const f32x4 b) { u32x4 w; w.x = cvt_pk_bf16(a[0], a[1]); w.y = cvt_pk_bf16(a[2], a[3]); w.z = cvt_pk_bf16(b[0], b[1]); w.w = cvt_pk_bf16(b[2], b[3]); return w; }
; __device__ __forceinline__ void unpack8(const u32x4 w, f32x4& a, f32x4& b) { a[0] = bf_lo(w.x); a[1] = bf_hi(w.x); a[2] = bf_lo(w.y); a[3] = bf_hi(w.y); b[0] = bf_lo(w.z); b[1] = bf_hi(w.z); b[2] = bf_lo(w.w); b[3] = bf_hi(w.w); }
;     __device__ __forceinline__ void operator()(const AccT& acc, const Unit& u, int wr, int wc, int fr, int fq) const {
;         int row0 = u.pm * 256 + wr * 64 + fr, col0 = u.pn * 256 + wc * 32 + 8 * fq;
;         asm volatile("" : "+v"(row0), "+v"(col0));
;         u32x4 bw[2][4][2];
; #pragma unroll
;         for (int ai = 0; ai < 2; ++ai)
; #pragma unroll
;             for (int m = 0; m < 4; ++m)
; #pragma unroll
;                 for (int bj = 0; bj < 2; ++bj) bw[ai][m][bj] = *(const u32x4*)(Hb + (size_t)(row0 + ai * 128 + m * 16) * 2048 + col0 + bj * 128);
; #pragma unroll
;         for (int ai = 0; ai < 2; ++ai) {
; #pragma unroll
;             for (int m = 0; m < 4; ++m) {
;                 const int row = row0 + ai * 128 + m * 16; const size_t off = (size_t)row * 2048 + col0; float ss = 0.f;
; #pragma unroll
;                 for (int bj = 0; bj < 2; ++bj) {
;                     f32x4 b0, b1; unpack8(bw[ai][m][bj], b0, b1);
;                     const f32x4 o0 = b0 + acc[ai][bj][m][0], o1 = b1 + acc[ai][bj][m][1];
;                     if (outF) { *(f32x4*)(outF + off + bj * 128) = o0; *(f32x4*)(outF + off + bj * 128 + 4) = o1; }
;                     else { *(u32x4*)(Hb + off + bj * 128) = pack8(o0, o1);
;                         ss += (o0[0] * o0[0] + o0[1] * o0[1]) + (o0[2] * o0[2] + o0[3] * o0[3]) + (o1[0] * o1[0] + o1[1] * o1[1]) + (o1[2] * o1[2] + o1[3] * o1[3]); }
;                 }
;                 if (!outF) { ss += __shfl_xor(ss, 16); ss += __shfl_xor(ss, 32); if (fq == 0) atomicAdd(SS + row, ss); }
;             }
	v_lshl_add_u32 v236, s10, 8, v1
	v_lshl_or_b32 v206, s96, 8, v252
	s_nop 0
	v_ashrrev_i32_e32 v207, 31, v206
	v_lshlrev_b64 v[238:239], 1, v[206:207]
	v_ashrrev_i32_e32 v237, 31, v236
	v_lshl_add_u64 v[118:119], s[28:29], 0, v[238:239]
	v_lshlrev_b64 v[240:241], 12, v[236:237]
	v_lshl_add_u64 v[114:115], v[118:119], 0, v[240:241]
	global_load_dwordx4 v[190:193], v[114:115], off
	global_load_dwordx4 v[186:189], v[114:115], off offset:256
	v_add_u32_e32 v232, 16, v236
	v_ashrrev_i32_e32 v233, 31, v232
	v_add_u32_e32 v228, 32, v236
	v_lshlrev_b64 v[234:235], 12, v[232:233]
	v_ashrrev_i32_e32 v229, 31, v228
	v_add_u32_e32 v224, 48, v236
	v_lshl_add_u64 v[114:115], v[118:119], 0, v[234:235]
	v_lshlrev_b64 v[230:231], 12, v[228:229]
	v_ashrrev_i32_e32 v225, 31, v224
	v_add_u32_e32 v220, 0x80, v236
	global_load_dwordx4 v[182:185], v[114:115], off
	global_load_dwordx4 v[178:181], v[114:115], off offset:256
	v_lshl_add_u64 v[114:115], v[118:119], 0, v[230:231]
	v_lshlrev_b64 v[226:227], 12, v[224:225]
	v_ashrrev_i32_e32 v221, 31, v220
	v_add_u32_e32 v216, 0x90, v236
	global_load_dwordx4 v[174:177], v[114:115], off
	global_load_dwordx4 v[170:173], v[114:115], off offset:256
	v_lshl_add_u64 v[114:115], v[118:119], 0, v[226:227]
	v_lshlrev_b64 v[222:223], 12, v[220:221]
	v_ashrrev_i32_e32 v217, 31, v216
	v_add_u32_e32 v212, 0xa0, v236
	v_add_u32_e32 v208, 0xb0, v236
	global_load_dwordx4 v[166:169], v[114:115], off
	global_load_dwordx4 v[162:165], v[114:115], off offset:256
	v_lshl_add_u64 v[114:115], v[118:119], 0, v[222:223]
	v_lshlrev_b64 v[218:219], 12, v[216:217]
	v_ashrrev_i32_e32 v213, 31, v212
	v_ashrrev_i32_e32 v209, 31, v208
	global_load_dwordx4 v[158:161], v[114:115], off
	global_load_dwordx4 v[146:149], v[114:115], off offset:256
	v_lshl_add_u64 v[114:115], v[118:119], 0, v[218:219]
	v_lshlrev_b64 v[214:215], 12, v[212:213]
	v_lshlrev_b64 v[210:211], 12, v[208:209]
	global_load_dwordx4 v[142:145], v[114:115], off
	global_load_dwordx4 v[138:141], v[114:115], off offset:256
	v_lshl_add_u64 v[114:115], v[118:119], 0, v[214:215]
	v_lshl_add_u64 v[118:119], v[118:119], 0, v[210:211]
	global_load_dwordx4 v[130:133], v[114:115], off
	s_nop 0
	global_load_dwordx4 v[114:117], v[114:115], off offset:256
	s_nop 0
	global_load_dwordx4 v[134:137], v[118:119], off
	s_nop 0
	global_load_dwordx4 v[118:121], v[118:119], off offset:256
	v_lshl_add_u64 v[240:241], s[28:29], 0, v[240:241]
	v_lshl_add_u64 v[238:239], v[240:241], 0, v[238:239]
	s_waitcnt vmcnt(0)
	v_lshlrev_b32_e32 v244, 16, v190
	v_and_b32_e32 v245, 0xffff0000, v190
	v_lshlrev_b32_e32 v190, 16, v191
	v_and_b32_e32 v191, 0xffff0000, v191
	v_lshlrev_b32_e32 v246, 16, v192
	v_and_b32_e32 v247, 0xffff0000, v192
	v_lshlrev_b32_e32 v192, 16, v193
	v_and_b32_e32 v193, 0xffff0000, v193
	v_pk_add_f32 v[156:157], v[156:157], v[190:191]
	v_pk_add_f32 v[154:155], v[154:155], v[244:245]
	v_pk_add_f32 v[190:191], v[152:153], v[192:193]
	v_pk_add_f32 v[192:193], v[150:151], v[246:247]
	v_cvt_pk_bf16_f32 v150, v154, v155
	v_cvt_pk_bf16_f32 v151, v156, v157
	v_cvt_pk_bf16_f32 v153, v190, v191
	s_nop 0
	v_cvt_pk_bf16_f32 v152, v192, v193
	global_store_dwordx4 v[238:239], v[150:153], off
	s_nop 1
	v_mul_f32_e32 v150, v155, v155
	v_mul_f32_e32 v151, v157, v157
	v_fmac_f32_e32 v150, v154, v154
	v_fmac_f32_e32 v151, v156, v156
	v_add_f32_e32 v150, v150, v151
	v_mul_f32_e32 v151, v193, v193
	v_fmac_f32_e32 v151, v192, v192
	v_add_f32_e32 v150, v151, v150
	v_mul_f32_e32 v151, v191, v191
	v_fmac_f32_e32 v151, v190, v190
	v_add_f32_e32 v190, v151, v150
	v_lshlrev_b32_e32 v150, 16, v186
	v_and_b32_e32 v151, 0xffff0000, v186
	v_lshlrev_b32_e32 v152, 16, v187
	v_and_b32_e32 v153, 0xffff0000, v187
	v_lshlrev_b32_e32 v154, 16, v188
	v_and_b32_e32 v155, 0xffff0000, v188
	v_lshlrev_b32_e32 v156, 16, v189
	v_and_b32_e32 v157, 0xffff0000, v189
	v_pk_add_f32 v[128:129], v[128:129], v[152:153]
	v_pk_add_f32 v[126:127], v[126:127], v[150:151]
	v_pk_add_f32 v[152:153], v[122:123], v[154:155]
	v_cvt_pk_bf16_f32 v122, v126, v127
	v_cvt_pk_bf16_f32 v123, v128, v129
	v_pk_add_f32 v[150:151], v[124:125], v[156:157]
	v_cvt_pk_bf16_f32 v124, v152, v153
	s_nop 0
	v_cvt_pk_bf16_f32 v125, v150, v151
	global_store_dwordx4 v[238:239], v[122:125], off offset:256
	s_nop 1
	v_mul_f32_e32 v122, v127, v127
	v_mul_f32_e32 v123, v129, v129
	v_fmac_f32_e32 v122, v126, v126
	v_fmac_f32_e32 v123, v128, v128
	v_add_f32_e32 v122, v122, v123
	v_mul_f32_e32 v123, v153, v153
	v_fmac_f32_e32 v123, v152, v152
	v_add_f32_e32 v122, v123, v122
	v_mul_f32_e32 v123, v151, v151
	v_fmac_f32_e32 v123, v150, v150
	v_add_f32_e32 v122, v123, v122
	v_and_b32_e32 v124, 64, v248
	v_add_f32_e32 v123, v190, v122
	v_xor_b32_e32 v122, 16, v248
	v_add_u32_e32 v125, 64, v124
	v_cmp_lt_i32_e32 vcc, v122, v125
	s_nop 1
	v_cndmask_b32_e32 v122, v248, v122, vcc
	v_lshlrev_b32_e32 v122, 2, v122
	ds_bpermute_b32 v124, v122, v123
	s_waitcnt lgkmcnt(0)
	v_add_f32_e32 v124, v123, v124
	v_xor_b32_e32 v123, 32, v248
	v_cmp_lt_i32_e32 vcc, v123, v125
	s_nop 1
	v_cndmask_b32_e32 v123, v248, v123, vcc
	v_lshlrev_b32_e32 v123, 2, v123
	ds_bpermute_b32 v125, v123, v124
	s_and_saveexec_b64 s[10:11], s[0:1]
	s_cbranch_execz .LBB0_304
	v_readlane_b32 s12, v254, 42
	v_readlane_b32 s13, v254, 43
	s_waitcnt lgkmcnt(0)
	v_add_f32_e32 v124, v124, v125
	v_lshl_add_u64 v[126:127], v[236:237], 2, s[12:13]
	global_atomic_add_f32 v[126:127], v124, off

; __device__ __forceinline__ void unpack8(const u32x4 w, f32x4& a, f32x4& b) { a[0] = bf_lo(w.x); a[1] = bf_hi(w.x); a[2] = bf_lo(w.y); a[3] = bf_hi(w.y); b[0] = bf_lo(w.z); b[1] = bf_hi(w.z); b[2] = bf_lo(w.w); b[3] = bf_hi(w.w); }
;     __device__ __forceinline__ void mid(AccT& acc, const Unit& u, int t, int wr, int wc, int fr, int fq) const {
;         int row0 = u.pm * 256 + wr * 64 + fr, col0 = u.pn * 256 + wc * 32 + 8 * fq; const int seg = (t == 16) ? 0 : 1;
;         asm volatile("" : "+v"(row0), "+v"(col0));
; #pragma unroll
;         for (int ai = 0; ai < 2; ++ai) {
;             u32x4 ga[4][2], gb[4][2];
; #pragma unroll
;             for (int m = 0; m < 4; ++m)
; #pragma unroll
;                 for (int bj = 0; bj < 2; ++bj) { const bf16_t* gp = Z + (size_t)(row0 + ai * 128 + m * 16) * ZW + ZG + seg * 2048 + col0 + bj * 128; ga[m][bj] = *(const u32x4*)gp; gb[m][bj] = *(const u32x4*)(gp + 2048); }
; #pragma unroll
;             for (int m = 0; m < 4; ++m)
; #pragma unroll
;                 for (int bj = 0; bj < 2; ++bj) {
;                     f32x4 a0, a1, b0, b1; unpack8(ga[m][bj], a0, a1); unpack8(gb[m][bj], b0, b1);
; #pragma unroll
;                     for (int j = 0; j < 4; ++j) { a0[j] = fmaxf(a0[j], 1e-20f) * __builtin_amdgcn_rcpf(fmaxf(b0[j], 1e-20f)); a1[j] = fmaxf(a1[j], 1e-20f) * __builtin_amdgcn_rcpf(fmaxf(b1[j], 1e-20f)); }
;                     acc[ai][bj][m][0] *= a0; acc[ai][bj][m][1] *= a1;
;                 }
;             asm volatile("" ::: "memory");
;         }
.LBB0_340:
	s_cmp_eq_u32 s97, 0
	s_cselect_b64 s[10:11], -1, 0
	s_cmp_eq_u32 s97, 1
	s_cselect_b64 s[12:13], -1, 0
	s_and_b64 vcc, exec, s[10:11]
	s_cbranch_vccnz .LBB0_342
	s_and_b64 s[14:15], s[12:13], exec
	s_cselect_b32 s70, 0, 0x1000
	s_addk_i32 s70, 0x2000
	v_mov_b64_e32 v[208:209], s[30:31]
	v_lshl_add_u32 v2, v180, 1, s70
	v_mov_b32_e32 v3, 0
	v_mad_i64_i32 v[208:209], s[14:15], v196, s68, v[208:209]
	s_mov_b64 s[16:17], 0x48000
	s_mov_b64 s[18:19], 0x168000
	v_lshl_add_u64 v[208:209], v[208:209], 0, v[2:3]
	global_load_dwordx4 v[132:135], v[208:209], off offset:-2048
	global_load_dwordx4 v[136:139], v[208:209], off offset:2048
	global_load_dwordx4 v[140:143], v[208:209], off offset:-1792
	global_load_dwordx4 v[144:147], v[208:209], off offset:2304
	v_lshl_add_u64 v[208:209], v[208:209], 0, s[16:17]
	global_load_dwordx4 v[148:151], v[208:209], off offset:-2048
	global_load_dwordx4 v[152:155], v[208:209], off offset:2048
	global_load_dwordx4 v[156:159], v[208:209], off offset:-1792
	global_load_dwordx4 v[160:163], v[208:209], off offset:2304
	v_lshl_add_u64 v[208:209], v[208:209], 0, s[16:17]
	global_load_dwordx4 v[164:167], v[208:209], off offset:-2048
	global_load_dwordx4 v[168:171], v[208:209], off offset:2048
	global_load_dwordx4 v[172:175], v[208:209], off offset:-1792
	global_load_dwordx4 v[176:179], v[208:209], off offset:2304
	v_lshl_add_u64 v[208:209], v[208:209], 0, s[16:17]
	global_load_dwordx4 v[200:203], v[208:209], off offset:-2048
	global_load_dwordx4 v[204:207], v[208:209], off offset:2048
	global_load_dwordx4 v[214:217], v[208:209], off offset:-1792
	global_load_dwordx4 v[218:221], v[208:209], off offset:2304
	v_lshl_add_u64 v[208:209], v[208:209], 0, s[18:19]
	global_load_dwordx4 v[222:225], v[208:209], off offset:-2048
	global_load_dwordx4 v[226:229], v[208:209], off offset:2048
	global_load_dwordx4 v[230:233], v[208:209], off offset:-1792
	global_load_dwordx4 v[234:237], v[208:209], off offset:2304
	v_lshl_add_u64 v[208:209], v[208:209], 0, s[16:17]
	s_waitcnt vmcnt(18)
	v_lshlrev_b32_e32 v238, 16, v132
	v_and_b32_e32 v239, 0xffff0000, v132
	v_lshlrev_b32_e32 v240, 16, v136
	v_and_b32_e32 v241, 0xffff0000, v136
	v_max_f32_e32 v240, 0x1e3ce508, v240
	v_max_f32_e32 v241, 0x1e3ce508, v241
	v_rcp_f32_e32 v240, v240
	v_rcp_f32_e32 v241, v241
	v_max_f32_e32 v238, 0x1e3ce508, v238
	v_max_f32_e32 v239, 0x1e3ce508, v239
	v_lshlrev_b32_e32 v244, 16, v133
	v_and_b32_e32 v245, 0xffff0000, v133
	v_lshlrev_b32_e32 v246, 16, v137
	v_and_b32_e32 v247, 0xffff0000, v137
	v_max_f32_e32 v246, 0x1e3ce508, v246
	v_max_f32_e32 v247, 0x1e3ce508, v247
	v_rcp_f32_e32 v246, v246
	v_rcp_f32_e32 v247, v247
	v_pk_mul_f32 v[238:239], v[238:239], v[240:241]
	v_pk_mul_f32 v[128:129], v[128:129], v[238:239]
	v_max_f32_e32 v244, 0x1e3ce508, v244
	v_max_f32_e32 v245, 0x1e3ce508, v245
	v_lshlrev_b32_e32 v238, 16, v134
	v_and_b32_e32 v239, 0xffff0000, v134
	v_lshlrev_b32_e32 v240, 16, v138
	v_and_b32_e32 v241, 0xffff0000, v138
	v_max_f32_e32 v240, 0x1e3ce508, v240
	v_max_f32_e32 v241, 0x1e3ce508, v241
	v_rcp_f32_e32 v240, v240
	v_rcp_f32_e32 v241, v241
	v_pk_mul_f32 v[244:245], v[244:245], v[246:247]
	v_pk_mul_f32 v[130:131], v[130:131], v[244:245]
	v_max_f32_e32 v238, 0x1e3ce508, v238
	v_max_f32_e32 v239, 0x1e3ce508, v239
	v_lshlrev_b32_e32 v244, 16, v135
	v_and_b32_e32 v245, 0xffff0000, v135
	v_lshlrev_b32_e32 v246, 16, v139
	v_and_b32_e32 v247, 0xffff0000, v139
	v_max_f32_e32 v246, 0x1e3ce508, v246
	v_max_f32_e32 v247, 0x1e3ce508, v247
	v_rcp_f32_e32 v246, v246
	v_rcp_f32_e32 v247, v247
	v_pk_mul_f32 v[238:239], v[238:239], v[240:241]
	v_pk_mul_f32 v[124:125], v[124:125], v[238:239]
	v_max_f32_e32 v244, 0x1e3ce508, v244
	v_max_f32_e32 v245, 0x1e3ce508, v245
	v_pk_mul_f32 v[244:245], v[244:245], v[246:247]
	v_pk_mul_f32 v[126:127], v[126:127], v[244:245]
	s_waitcnt vmcnt(16)
	v_lshlrev_b32_e32 v238, 16, v140
	v_and_b32_e32 v239, 0xffff0000, v140
	v_lshlrev_b32_e32 v240, 16, v144
	v_and_b32_e32 v241, 0xffff0000, v144
	v_max_f32_e32 v240, 0x1e3ce508, v240
	v_max_f32_e32 v241, 0x1e3ce508, v241
	v_rcp_f32_e32 v240, v240
	v_rcp_f32_e32 v241, v241
	v_max_f32_e32 v238, 0x1e3ce508, v238
	v_max_f32_e32 v239, 0x1e3ce508, v239
	v_lshlrev_b32_e32 v244, 16, v141
	v_and_b32_e32 v245, 0xffff0000, v141
	v_lshlrev_b32_e32 v246, 16, v145
	v_and_b32_e32 v247, 0xffff0000, v145
	v_max_f32_e32 v246, 0x1e3ce508, v246
	v_max_f32_e32 v247, 0x1e3ce508, v247
	v_rcp_f32_e32 v246, v246
	v_rcp_f32_e32 v247, v247
	v_pk_mul_f32 v[238:239], v[238:239], v[240:241]
	v_pk_mul_f32 v[120:121], v[120:121], v[238:239]
	v_max_f32_e32 v244, 0x1e3ce508, v244
	v_max_f32_e32 v245, 0x1e3ce508, v245
	v_lshlrev_b32_e32 v238, 16, v142
	v_and_b32_e32 v239, 0xffff0000, v142
	v_lshlrev_b32_e32 v240, 16, v146
	v_and_b32_e32 v241, 0xffff0000, v146
	v_max_f32_e32 v240, 0x1e3ce508, v240
	v_max_f32_e32 v241, 0x1e3ce508, v241
	v_rcp_f32_e32 v240, v240
	v_rcp_f32_e32 v241, v241
	v_pk_mul_f32 v[244:245], v[244:245], v[246:247]
	v_pk_mul_f32 v[122:123], v[122:123], v[244:245]
	v_max_f32_e32 v238, 0x1e3ce508, v238
	v_max_f32_e32 v239, 0x1e3ce508, v239
	v_lshlrev_b32_e32 v244, 16, v143
	v_and_b32_e32 v245, 0xffff0000, v143
	v_lshlrev_b32_e32 v246, 16, v147
	v_and_b32_e32 v247, 0xffff0000, v147
	v_max_f32_e32 v246, 0x1e3ce508, v246
	v_max_f32_e32 v247, 0x1e3ce508, v247
	v_rcp_f32_e32 v246, v246
	v_rcp_f32_e32 v247, v247
	v_pk_mul_f32 v[238:239], v[238:239], v[240:241]
	v_pk_mul_f32 v[116:117], v[116:117], v[238:239]
	v_max_f32_e32 v244, 0x1e3ce508, v244
	v_max_f32_e32 v245, 0x1e3ce508, v245
	v_pk_mul_f32 v[244:245], v[244:245], v[246:247]
	v_pk_mul_f32 v[118:119], v[118:119], v[244:245]
	global_load_dwordx4 v[132:135], v[208:209], off offset:-2048
	global_load_dwordx4 v[136:139], v[208:209], off offset:2048
	global_load_dwordx4 v[140:143], v[208:209], off offset:-1792
	global_load_dwordx4 v[144:147], v[208:209], off offset:2304
	v_lshl_add_u64 v[208:209], v[208:209], 0, s[16:17]
	s_waitcnt vmcnt(18)
; __device__ __forceinline__ void unpack8(const u32x4 w, f32x4& a, f32x4& b) { a[0] = bf_lo(w.x); a[1] = bf_hi(w.x); a[2] = bf_lo(w.y); a[3] = bf_hi(w.y); b[0] = bf_lo(w.z); b[1] = bf_hi(w.z); b[2] = bf_lo(w.w); b[3] = bf_hi(w.w); }
;     __device__ __forceinline__ void mid(AccT& acc, const Unit& u, int t, int wr, int wc, int fr, int fq) const {
;     ...
;                 for (int bj = 0; bj < 2; ++bj) { const bf16_t* gp = Z + (size_t)(row0 + ai * 128 + m * 16) * ZW + ZG + seg * 2048 + col0 + bj * 128; ga[m][bj] = *(const u32x4*)gp; gb[m][bj] = *(const u32x4*)(gp + 2048); }
; #pragma unroll
;             for (int m = 0; m < 4; ++m)
; #pragma unroll
;                 for (int bj = 0; bj < 2; ++bj) {
;                     f32x4 a0, a1, b0, b1; unpack8(ga[m][bj], a0, a1); unpack8(gb[m][bj], b0, b1);
; #pragma unroll
;                     for (int j = 0; j < 4; ++j) { a0[j] = fmaxf(a0[j], 1e-20f) * __builtin_amdgcn_rcpf(fmaxf(b0[j], 1e-20f)); a1[j] = fmaxf(a1[j], 1e-20f) * __builtin_amdgcn_rcpf(fmaxf(b1[j], 1e-20f)); }
;                     acc[ai][bj][m][0] *= a0; acc[ai][bj][m][1] *= a1;
;                 }
	v_lshlrev_b32_e32 v238, 16, v148
	v_and_b32_e32 v239, 0xffff0000, v148
	v_lshlrev_b32_e32 v240, 16, v152
	v_and_b32_e32 v241, 0xffff0000, v152
	v_max_f32_e32 v240, 0x1e3ce508, v240
	v_max_f32_e32 v241, 0x1e3ce508, v241
	v_rcp_f32_e32 v240, v240
	v_rcp_f32_e32 v241, v241
	v_max_f32_e32 v238, 0x1e3ce508, v238
	v_max_f32_e32 v239, 0x1e3ce508, v239
	v_lshlrev_b32_e32 v244, 16, v149
	v_and_b32_e32 v245, 0xffff0000, v149
	v_lshlrev_b32_e32 v246, 16, v153
	v_and_b32_e32 v247, 0xffff0000, v153
	v_max_f32_e32 v246, 0x1e3ce508, v246
	v_max_f32_e32 v247, 0x1e3ce508, v247
	v_rcp_f32_e32 v246, v246
	v_rcp_f32_e32 v247, v247
	v_pk_mul_f32 v[238:239], v[238:239], v[240:241]
	v_pk_mul_f32 v[112:113], v[112:113], v[238:239]
	v_max_f32_e32 v244, 0x1e3ce508, v244
	v_max_f32_e32 v245, 0x1e3ce508, v245
	v_lshlrev_b32_e32 v238, 16, v150
	v_and_b32_e32 v239, 0xffff0000, v150
	v_lshlrev_b32_e32 v240, 16, v154
	v_and_b32_e32 v241, 0xffff0000, v154
	v_max_f32_e32 v240, 0x1e3ce508, v240
	v_max_f32_e32 v241, 0x1e3ce508, v241
	v_rcp_f32_e32 v240, v240
	v_rcp_f32_e32 v241, v241
	v_pk_mul_f32 v[244:245], v[244:245], v[246:247]
	v_pk_mul_f32 v[114:115], v[114:115], v[244:245]
	v_max_f32_e32 v238, 0x1e3ce508, v238
	v_max_f32_e32 v239, 0x1e3ce508, v239
	v_lshlrev_b32_e32 v244, 16, v151
	v_and_b32_e32 v245, 0xffff0000, v151
	v_lshlrev_b32_e32 v246, 16, v155
	v_and_b32_e32 v247, 0xffff0000, v155
	v_max_f32_e32 v246, 0x1e3ce508, v246
	v_max_f32_e32 v247, 0x1e3ce508, v247
	v_rcp_f32_e32 v246, v246
	v_rcp_f32_e32 v247, v247
	v_pk_mul_f32 v[238:239], v[238:239], v[240:241]
	v_pk_mul_f32 v[108:109], v[108:109], v[238:239]
	v_max_f32_e32 v244, 0x1e3ce508, v244
	v_max_f32_e32 v245, 0x1e3ce508, v245
	v_pk_mul_f32 v[244:245], v[244:245], v[246:247]
	v_pk_mul_f32 v[110:111], v[110:111], v[244:245]
	s_waitcnt vmcnt(16)
	v_lshlrev_b32_e32 v238, 16, v156
	v_and_b32_e32 v239, 0xffff0000, v156
	v_lshlrev_b32_e32 v240, 16, v160
	v_and_b32_e32 v241, 0xffff0000, v160
	v_max_f32_e32 v240, 0x1e3ce508, v240
	v_max_f32_e32 v241, 0x1e3ce508, v241
	v_rcp_f32_e32 v240, v240
	v_rcp_f32_e32 v241, v241
	v_max_f32_e32 v238, 0x1e3ce508, v238
	v_max_f32_e32 v239, 0x1e3ce508, v239
	v_lshlrev_b32_e32 v244, 16, v157
	v_and_b32_e32 v245, 0xffff0000, v157
	v_lshlrev_b32_e32 v246, 16, v161
	v_and_b32_e32 v247, 0xffff0000, v161
	v_max_f32_e32 v246, 0x1e3ce508, v246
	v_max_f32_e32 v247, 0x1e3ce508, v247
	v_rcp_f32_e32 v246, v246
	v_rcp_f32_e32 v247, v247
	v_pk_mul_f32 v[238:239], v[238:239], v[240:241]
	v_pk_mul_f32 v[104:105], v[104:105], v[238:239]
	v_max_f32_e32 v244, 0x1e3ce508, v244
	v_max_f32_e32 v245, 0x1e3ce508, v245
	v_lshlrev_b32_e32 v238, 16, v158
	v_and_b32_e32 v239, 0xffff0000, v158
	v_lshlrev_b32_e32 v240, 16, v162
	v_and_b32_e32 v241, 0xffff0000, v162
	v_max_f32_e32 v240, 0x1e3ce508, v240
	v_max_f32_e32 v241, 0x1e3ce508, v241
	v_rcp_f32_e32 v240, v240
	v_rcp_f32_e32 v241, v241
	v_pk_mul_f32 v[244:245], v[244:245], v[246:247]
	v_pk_mul_f32 v[106:107], v[106:107], v[244:245]
	v_max_f32_e32 v238, 0x1e3ce508, v238
	v_max_f32_e32 v239, 0x1e3ce508, v239
	v_lshlrev_b32_e32 v244, 16, v159
	v_and_b32_e32 v245, 0xffff0000, v159
	v_lshlrev_b32_e32 v246, 16, v163
	v_and_b32_e32 v247, 0xffff0000, v163
	v_max_f32_e32 v246, 0x1e3ce508, v246
	v_max_f32_e32 v247, 0x1e3ce508, v247
	v_rcp_f32_e32 v246, v246
	v_rcp_f32_e32 v247, v247
	v_pk_mul_f32 v[238:239], v[238:239], v[240:241]
	v_pk_mul_f32 v[100:101], v[100:101], v[238:239]
	v_max_f32_e32 v244, 0x1e3ce508, v244
	v_max_f32_e32 v245, 0x1e3ce508, v245
	v_pk_mul_f32 v[244:245], v[244:245], v[246:247]
	v_pk_mul_f32 v[102:103], v[102:103], v[244:245]
	global_load_dwordx4 v[148:151], v[208:209], off offset:-2048
	global_load_dwordx4 v[152:155], v[208:209], off offset:2048
	global_load_dwordx4 v[156:159], v[208:209], off offset:-1792
	global_load_dwordx4 v[160:163], v[208:209], off offset:2304
	v_lshl_add_u64 v[208:209], v[208:209], 0, s[16:17]
	s_waitcnt vmcnt(18)
	v_lshlrev_b32_e32 v238, 16, v164
	v_and_b32_e32 v239, 0xffff0000, v164
	v_lshlrev_b32_e32 v240, 16, v168
	v_and_b32_e32 v241, 0xffff0000, v168
	v_max_f32_e32 v240, 0x1e3ce508, v240
	v_max_f32_e32 v241, 0x1e3ce508, v241
	v_rcp_f32_e32 v240, v240
	v_rcp_f32_e32 v241, v241
	v_max_f32_e32 v238, 0x1e3ce508, v238
	v_max_f32_e32 v239, 0x1e3ce508, v239
	v_lshlrev_b32_e32 v244, 16, v165
	v_and_b32_e32 v245, 0xffff0000, v165
	v_lshlrev_b32_e32 v246, 16, v169
	v_and_b32_e32 v247, 0xffff0000, v169
	v_max_f32_e32 v246, 0x1e3ce508, v246
	v_max_f32_e32 v247, 0x1e3ce508, v247
	v_rcp_f32_e32 v246, v246
	v_rcp_f32_e32 v247, v247
	v_pk_mul_f32 v[238:239], v[238:239], v[240:241]
	v_pk_mul_f32 v[96:97], v[96:97], v[238:239]
	v_max_f32_e32 v244, 0x1e3ce508, v244
	v_max_f32_e32 v245, 0x1e3ce508, v245
	v_lshlrev_b32_e32 v238, 16, v166
	v_and_b32_e32 v239, 0xffff0000, v166
	v_lshlrev_b32_e32 v240, 16, v170
	v_and_b32_e32 v241, 0xffff0000, v170
	v_max_f32_e32 v240, 0x1e3ce508, v240
	v_max_f32_e32 v241, 0x1e3ce508, v241
	v_rcp_f32_e32 v240, v240
	v_rcp_f32_e32 v241, v241
	v_pk_mul_f32 v[244:245], v[244:245], v[246:247]
	v_pk_mul_f32 v[98:99], v[98:99], v[244:245]
	v_max_f32_e32 v238, 0x1e3ce508, v238
	v_max_f32_e32 v239, 0x1e3ce508, v239
	v_lshlrev_b32_e32 v244, 16, v167
	v_and_b32_e32 v245, 0xffff0000, v167
	v_lshlrev_b32_e32 v246, 16, v171
	v_and_b32_e32 v247, 0xffff0000, v171
	v_max_f32_e32 v246, 0x1e3ce508, v246
	v_max_f32_e32 v247, 0x1e3ce508, v247
	v_rcp_f32_e32 v246, v246
	v_rcp_f32_e32 v247, v247
	v_pk_mul_f32 v[238:239], v[238:239], v[240:241]
	v_pk_mul_f32 v[92:93], v[92:93], v[238:239]
	v_max_f32_e32 v244, 0x1e3ce508, v244
	v_max_f32_e32 v245, 0x1e3ce508, v245
	v_pk_mul_f32 v[244:245], v[244:245], v[246:247]
	v_pk_mul_f32 v[94:95], v[94:95], v[244:245]
	s_waitcnt vmcnt(16)
; __device__ __forceinline__ void unpack8(const u32x4 w, f32x4& a, f32x4& b) { a[0] = bf_lo(w.x); a[1] = bf_hi(w.x); a[2] = bf_lo(w.y); a[3] = bf_hi(w.y); b[0] = bf_lo(w.z); b[1] = bf_hi(w.z); b[2] = bf_lo(w.w); b[3] = bf_hi(w.w); }
;     __device__ __forceinline__ void mid(AccT& acc, const Unit& u, int t, int wr, int wc, int fr, int fq) const {
;     ...
;                 for (int bj = 0; bj < 2; ++bj) { const bf16_t* gp = Z + (size_t)(row0 + ai * 128 + m * 16) * ZW + ZG + seg * 2048 + col0 + bj * 128; ga[m][bj] = *(const u32x4*)gp; gb[m][bj] = *(const u32x4*)(gp + 2048); }
; #pragma unroll
;             for (int m = 0; m < 4; ++m)
; #pragma unroll
;                 for (int bj = 0; bj < 2; ++bj) {
;                     f32x4 a0, a1, b0, b1; unpack8(ga[m][bj], a0, a1); unpack8(gb[m][bj], b0, b1);
; #pragma unroll
;                     for (int j = 0; j < 4; ++j) { a0[j] = fmaxf(a0[j], 1e-20f) * __builtin_amdgcn_rcpf(fmaxf(b0[j], 1e-20f)); a1[j] = fmaxf(a1[j], 1e-20f) * __builtin_amdgcn_rcpf(fmaxf(b1[j], 1e-20f)); }
;                     acc[ai][bj][m][0] *= a0; acc[ai][bj][m][1] *= a1;
;                 }
	v_lshlrev_b32_e32 v238, 16, v172
	v_and_b32_e32 v239, 0xffff0000, v172
	v_lshlrev_b32_e32 v240, 16, v176
	v_and_b32_e32 v241, 0xffff0000, v176
	v_max_f32_e32 v240, 0x1e3ce508, v240
	v_max_f32_e32 v241, 0x1e3ce508, v241
	v_rcp_f32_e32 v240, v240
	v_rcp_f32_e32 v241, v241
	v_max_f32_e32 v238, 0x1e3ce508, v238
	v_max_f32_e32 v239, 0x1e3ce508, v239
	v_lshlrev_b32_e32 v244, 16, v173
	v_and_b32_e32 v245, 0xffff0000, v173
	v_lshlrev_b32_e32 v246, 16, v177
	v_and_b32_e32 v247, 0xffff0000, v177
	v_max_f32_e32 v246, 0x1e3ce508, v246
	v_max_f32_e32 v247, 0x1e3ce508, v247
	v_rcp_f32_e32 v246, v246
	v_rcp_f32_e32 v247, v247
	v_pk_mul_f32 v[238:239], v[238:239], v[240:241]
	v_pk_mul_f32 v[88:89], v[88:89], v[238:239]
	v_max_f32_e32 v244, 0x1e3ce508, v244
	v_max_f32_e32 v245, 0x1e3ce508, v245
	v_lshlrev_b32_e32 v238, 16, v174
	v_and_b32_e32 v239, 0xffff0000, v174
	v_lshlrev_b32_e32 v240, 16, v178
	v_and_b32_e32 v241, 0xffff0000, v178
	v_max_f32_e32 v240, 0x1e3ce508, v240
	v_max_f32_e32 v241, 0x1e3ce508, v241
	v_rcp_f32_e32 v240, v240
	v_rcp_f32_e32 v241, v241
	v_pk_mul_f32 v[244:245], v[244:245], v[246:247]
	v_pk_mul_f32 v[90:91], v[90:91], v[244:245]
	v_max_f32_e32 v238, 0x1e3ce508, v238
	v_max_f32_e32 v239, 0x1e3ce508, v239
	v_lshlrev_b32_e32 v244, 16, v175
	v_and_b32_e32 v245, 0xffff0000, v175
	v_lshlrev_b32_e32 v246, 16, v179
	v_and_b32_e32 v247, 0xffff0000, v179
	v_max_f32_e32 v246, 0x1e3ce508, v246
	v_max_f32_e32 v247, 0x1e3ce508, v247
	v_rcp_f32_e32 v246, v246
	v_rcp_f32_e32 v247, v247
	v_pk_mul_f32 v[238:239], v[238:239], v[240:241]
	v_pk_mul_f32 v[84:85], v[84:85], v[238:239]
	v_max_f32_e32 v244, 0x1e3ce508, v244
	v_max_f32_e32 v245, 0x1e3ce508, v245
	v_pk_mul_f32 v[244:245], v[244:245], v[246:247]
	v_pk_mul_f32 v[86:87], v[86:87], v[244:245]
	global_load_dwordx4 v[164:167], v[208:209], off offset:-2048
	global_load_dwordx4 v[168:171], v[208:209], off offset:2048
	global_load_dwordx4 v[172:175], v[208:209], off offset:-1792
	global_load_dwordx4 v[176:179], v[208:209], off offset:2304
	s_waitcnt vmcnt(18)
	v_lshlrev_b32_e32 v238, 16, v200
	v_and_b32_e32 v239, 0xffff0000, v200
	v_lshlrev_b32_e32 v240, 16, v204
	v_and_b32_e32 v241, 0xffff0000, v204
	v_max_f32_e32 v240, 0x1e3ce508, v240
	v_max_f32_e32 v241, 0x1e3ce508, v241
	v_rcp_f32_e32 v240, v240
	v_rcp_f32_e32 v241, v241
	v_max_f32_e32 v238, 0x1e3ce508, v238
	v_max_f32_e32 v239, 0x1e3ce508, v239
	v_lshlrev_b32_e32 v244, 16, v201
	v_and_b32_e32 v245, 0xffff0000, v201
	v_lshlrev_b32_e32 v246, 16, v205
	v_and_b32_e32 v247, 0xffff0000, v205
	v_max_f32_e32 v246, 0x1e3ce508, v246
	v_max_f32_e32 v247, 0x1e3ce508, v247
	v_rcp_f32_e32 v246, v246
	v_rcp_f32_e32 v247, v247
	v_pk_mul_f32 v[238:239], v[238:239], v[240:241]
	v_pk_mul_f32 v[80:81], v[80:81], v[238:239]
	v_max_f32_e32 v244, 0x1e3ce508, v244
	v_max_f32_e32 v245, 0x1e3ce508, v245
	v_lshlrev_b32_e32 v238, 16, v202
	v_and_b32_e32 v239, 0xffff0000, v202
	v_lshlrev_b32_e32 v240, 16, v206
	v_and_b32_e32 v241, 0xffff0000, v206
	v_max_f32_e32 v240, 0x1e3ce508, v240
	v_max_f32_e32 v241, 0x1e3ce508, v241
	v_rcp_f32_e32 v240, v240
	v_rcp_f32_e32 v241, v241
	v_pk_mul_f32 v[244:245], v[244:245], v[246:247]
	v_pk_mul_f32 v[82:83], v[82:83], v[244:245]
	v_max_f32_e32 v238, 0x1e3ce508, v238
	v_max_f32_e32 v239, 0x1e3ce508, v239
	v_lshlrev_b32_e32 v244, 16, v203
	v_and_b32_e32 v245, 0xffff0000, v203
	v_lshlrev_b32_e32 v246, 16, v207
	v_and_b32_e32 v247, 0xffff0000, v207
	v_max_f32_e32 v246, 0x1e3ce508, v246
	v_max_f32_e32 v247, 0x1e3ce508, v247
	v_rcp_f32_e32 v246, v246
	v_rcp_f32_e32 v247, v247
	v_pk_mul_f32 v[238:239], v[238:239], v[240:241]
	v_pk_mul_f32 v[76:77], v[76:77], v[238:239]
	v_max_f32_e32 v244, 0x1e3ce508, v244
	v_max_f32_e32 v245, 0x1e3ce508, v245
	v_pk_mul_f32 v[244:245], v[244:245], v[246:247]
	v_pk_mul_f32 v[78:79], v[78:79], v[244:245]
	s_waitcnt vmcnt(16)
	v_lshlrev_b32_e32 v238, 16, v214
	v_and_b32_e32 v239, 0xffff0000, v214
	v_lshlrev_b32_e32 v240, 16, v218
	v_and_b32_e32 v241, 0xffff0000, v218
	v_max_f32_e32 v240, 0x1e3ce508, v240
	v_max_f32_e32 v241, 0x1e3ce508, v241
	v_rcp_f32_e32 v240, v240
	v_rcp_f32_e32 v241, v241
	v_max_f32_e32 v238, 0x1e3ce508, v238
	v_max_f32_e32 v239, 0x1e3ce508, v239
	v_lshlrev_b32_e32 v244, 16, v215
	v_and_b32_e32 v245, 0xffff0000, v215
	v_lshlrev_b32_e32 v246, 16, v219
	v_and_b32_e32 v247, 0xffff0000, v219
	v_max_f32_e32 v246, 0x1e3ce508, v246
	v_max_f32_e32 v247, 0x1e3ce508, v247
	v_rcp_f32_e32 v246, v246
	v_rcp_f32_e32 v247, v247
	v_pk_mul_f32 v[238:239], v[238:239], v[240:241]
	v_pk_mul_f32 v[72:73], v[72:73], v[238:239]
	v_max_f32_e32 v244, 0x1e3ce508, v244
	v_max_f32_e32 v245, 0x1e3ce508, v245
	v_lshlrev_b32_e32 v238, 16, v216
	v_and_b32_e32 v239, 0xffff0000, v216
	v_lshlrev_b32_e32 v240, 16, v220
	v_and_b32_e32 v241, 0xffff0000, v220
	v_max_f32_e32 v240, 0x1e3ce508, v240
	v_max_f32_e32 v241, 0x1e3ce508, v241
	v_rcp_f32_e32 v240, v240
	v_rcp_f32_e32 v241, v241
	v_pk_mul_f32 v[244:245], v[244:245], v[246:247]
	v_pk_mul_f32 v[74:75], v[74:75], v[244:245]
	v_max_f32_e32 v238, 0x1e3ce508, v238
	v_max_f32_e32 v239, 0x1e3ce508, v239
	v_lshlrev_b32_e32 v244, 16, v217
	v_and_b32_e32 v245, 0xffff0000, v217
	v_lshlrev_b32_e32 v246, 16, v221
	v_and_b32_e32 v247, 0xffff0000, v221
	v_max_f32_e32 v246, 0x1e3ce508, v246
	v_max_f32_e32 v247, 0x1e3ce508, v247
	v_rcp_f32_e32 v246, v246
	v_rcp_f32_e32 v247, v247
	v_pk_mul_f32 v[238:239], v[238:239], v[240:241]
	v_pk_mul_f32 v[68:69], v[68:69], v[238:239]
	v_max_f32_e32 v244, 0x1e3ce508, v244
	v_max_f32_e32 v245, 0x1e3ce508, v245
	v_pk_mul_f32 v[244:245], v[244:245], v[246:247]
	v_pk_mul_f32 v[70:71], v[70:71], v[244:245]
	s_waitcnt vmcnt(14)
; __device__ __forceinline__ void unpack8(const u32x4 w, f32x4& a, f32x4& b) { a[0] = bf_lo(w.x); a[1] = bf_hi(w.x); a[2] = bf_lo(w.y); a[3] = bf_hi(w.y); b[0] = bf_lo(w.z); b[1] = bf_hi(w.z); b[2] = bf_lo(w.w); b[3] = bf_hi(w.w); }
;     __device__ __forceinline__ void mid(AccT& acc, const Unit& u, int t, int wr, int wc, int fr, int fq) const {
;     ...
;                 for (int bj = 0; bj < 2; ++bj) { const bf16_t* gp = Z + (size_t)(row0 + ai * 128 + m * 16) * ZW + ZG + seg * 2048 + col0 + bj * 128; ga[m][bj] = *(const u32x4*)gp; gb[m][bj] = *(const u32x4*)(gp + 2048); }
; #pragma unroll
;             for (int m = 0; m < 4; ++m)
; #pragma unroll
;                 for (int bj = 0; bj < 2; ++bj) {
;                     f32x4 a0, a1, b0, b1; unpack8(ga[m][bj], a0, a1); unpack8(gb[m][bj], b0, b1);
; #pragma unroll
;                     for (int j = 0; j < 4; ++j) { a0[j] = fmaxf(a0[j], 1e-20f) * __builtin_amdgcn_rcpf(fmaxf(b0[j], 1e-20f)); a1[j] = fmaxf(a1[j], 1e-20f) * __builtin_amdgcn_rcpf(fmaxf(b1[j], 1e-20f)); }
;                     acc[ai][bj][m][0] *= a0; acc[ai][bj][m][1] *= a1;
;                 }
	v_lshlrev_b32_e32 v238, 16, v222
	v_and_b32_e32 v239, 0xffff0000, v222
	v_lshlrev_b32_e32 v240, 16, v226
	v_and_b32_e32 v241, 0xffff0000, v226
	v_max_f32_e32 v240, 0x1e3ce508, v240
	v_max_f32_e32 v241, 0x1e3ce508, v241
	v_rcp_f32_e32 v240, v240
	v_rcp_f32_e32 v241, v241
	v_max_f32_e32 v238, 0x1e3ce508, v238
	v_max_f32_e32 v239, 0x1e3ce508, v239
	v_lshlrev_b32_e32 v244, 16, v223
	v_and_b32_e32 v245, 0xffff0000, v223
	v_lshlrev_b32_e32 v246, 16, v227
	v_and_b32_e32 v247, 0xffff0000, v227
	v_max_f32_e32 v246, 0x1e3ce508, v246
	v_max_f32_e32 v247, 0x1e3ce508, v247
	v_rcp_f32_e32 v246, v246
	v_rcp_f32_e32 v247, v247
	v_pk_mul_f32 v[238:239], v[238:239], v[240:241]
	v_pk_mul_f32 v[64:65], v[64:65], v[238:239]
	v_max_f32_e32 v244, 0x1e3ce508, v244
	v_max_f32_e32 v245, 0x1e3ce508, v245
	v_lshlrev_b32_e32 v238, 16, v224
	v_and_b32_e32 v239, 0xffff0000, v224
	v_lshlrev_b32_e32 v240, 16, v228
	v_and_b32_e32 v241, 0xffff0000, v228
	v_max_f32_e32 v240, 0x1e3ce508, v240
	v_max_f32_e32 v241, 0x1e3ce508, v241
	v_rcp_f32_e32 v240, v240
	v_rcp_f32_e32 v241, v241
	v_pk_mul_f32 v[244:245], v[244:245], v[246:247]
	v_pk_mul_f32 v[66:67], v[66:67], v[244:245]
	v_max_f32_e32 v238, 0x1e3ce508, v238
	v_max_f32_e32 v239, 0x1e3ce508, v239
	v_lshlrev_b32_e32 v244, 16, v225
	v_and_b32_e32 v245, 0xffff0000, v225
	v_lshlrev_b32_e32 v246, 16, v229
	v_and_b32_e32 v247, 0xffff0000, v229
	v_max_f32_e32 v246, 0x1e3ce508, v246
	v_max_f32_e32 v247, 0x1e3ce508, v247
	v_rcp_f32_e32 v246, v246
	v_rcp_f32_e32 v247, v247
	v_pk_mul_f32 v[238:239], v[238:239], v[240:241]
	v_pk_mul_f32 v[60:61], v[60:61], v[238:239]
	v_max_f32_e32 v244, 0x1e3ce508, v244
	v_max_f32_e32 v245, 0x1e3ce508, v245
	v_pk_mul_f32 v[244:245], v[244:245], v[246:247]
	v_pk_mul_f32 v[62:63], v[62:63], v[244:245]
	s_waitcnt vmcnt(12)
	v_lshlrev_b32_e32 v238, 16, v230
	v_and_b32_e32 v239, 0xffff0000, v230
	v_lshlrev_b32_e32 v240, 16, v234
	v_and_b32_e32 v241, 0xffff0000, v234
	v_max_f32_e32 v240, 0x1e3ce508, v240
	v_max_f32_e32 v241, 0x1e3ce508, v241
	v_rcp_f32_e32 v240, v240
	v_rcp_f32_e32 v241, v241
	v_max_f32_e32 v238, 0x1e3ce508, v238
	v_max_f32_e32 v239, 0x1e3ce508, v239
	v_lshlrev_b32_e32 v244, 16, v231
	v_and_b32_e32 v245, 0xffff0000, v231
	v_lshlrev_b32_e32 v246, 16, v235
	v_and_b32_e32 v247, 0xffff0000, v235
	v_max_f32_e32 v246, 0x1e3ce508, v246
	v_max_f32_e32 v247, 0x1e3ce508, v247
	v_rcp_f32_e32 v246, v246
	v_rcp_f32_e32 v247, v247
	v_pk_mul_f32 v[238:239], v[238:239], v[240:241]
	v_pk_mul_f32 v[56:57], v[56:57], v[238:239]
	v_max_f32_e32 v244, 0x1e3ce508, v244
	v_max_f32_e32 v245, 0x1e3ce508, v245
	v_lshlrev_b32_e32 v238, 16, v232
	v_and_b32_e32 v239, 0xffff0000, v232
	v_lshlrev_b32_e32 v240, 16, v236
	v_and_b32_e32 v241, 0xffff0000, v236
	v_max_f32_e32 v240, 0x1e3ce508, v240
	v_max_f32_e32 v241, 0x1e3ce508, v241
	v_rcp_f32_e32 v240, v240
	v_rcp_f32_e32 v241, v241
	v_pk_mul_f32 v[244:245], v[244:245], v[246:247]
	v_pk_mul_f32 v[58:59], v[58:59], v[244:245]
	v_max_f32_e32 v238, 0x1e3ce508, v238
	v_max_f32_e32 v239, 0x1e3ce508, v239
	v_lshlrev_b32_e32 v244, 16, v233
	v_and_b32_e32 v245, 0xffff0000, v233
	v_lshlrev_b32_e32 v246, 16, v237
	v_and_b32_e32 v247, 0xffff0000, v237
	v_max_f32_e32 v246, 0x1e3ce508, v246
	v_max_f32_e32 v247, 0x1e3ce508, v247
	v_rcp_f32_e32 v246, v246
	v_rcp_f32_e32 v247, v247
	v_pk_mul_f32 v[238:239], v[238:239], v[240:241]
	v_pk_mul_f32 v[52:53], v[52:53], v[238:239]
	v_max_f32_e32 v244, 0x1e3ce508, v244
	v_max_f32_e32 v245, 0x1e3ce508, v245
	v_pk_mul_f32 v[244:245], v[244:245], v[246:247]
	v_pk_mul_f32 v[54:55], v[54:55], v[244:245]
	s_waitcnt vmcnt(10)
	v_lshlrev_b32_e32 v238, 16, v132
	v_and_b32_e32 v239, 0xffff0000, v132
	v_lshlrev_b32_e32 v240, 16, v136
	v_and_b32_e32 v241, 0xffff0000, v136
	v_max_f32_e32 v240, 0x1e3ce508, v240
	v_max_f32_e32 v241, 0x1e3ce508, v241
	v_rcp_f32_e32 v240, v240
	v_rcp_f32_e32 v241, v241
	v_max_f32_e32 v238, 0x1e3ce508, v238
	v_max_f32_e32 v239, 0x1e3ce508, v239
	v_lshlrev_b32_e32 v244, 16, v133
	v_and_b32_e32 v245, 0xffff0000, v133
	v_lshlrev_b32_e32 v246, 16, v137
	v_and_b32_e32 v247, 0xffff0000, v137
	v_max_f32_e32 v246, 0x1e3ce508, v246
	v_max_f32_e32 v247, 0x1e3ce508, v247
	v_rcp_f32_e32 v246, v246
	v_rcp_f32_e32 v247, v247
	v_pk_mul_f32 v[238:239], v[238:239], v[240:241]
	v_pk_mul_f32 v[48:49], v[48:49], v[238:239]
	v_max_f32_e32 v244, 0x1e3ce508, v244
	v_max_f32_e32 v245, 0x1e3ce508, v245
	v_lshlrev_b32_e32 v238, 16, v134
	v_and_b32_e32 v239, 0xffff0000, v134
	v_lshlrev_b32_e32 v240, 16, v138
	v_and_b32_e32 v241, 0xffff0000, v138
	v_max_f32_e32 v240, 0x1e3ce508, v240
	v_max_f32_e32 v241, 0x1e3ce508, v241
	v_rcp_f32_e32 v240, v240
	v_rcp_f32_e32 v241, v241
	v_pk_mul_f32 v[244:245], v[244:245], v[246:247]
	v_pk_mul_f32 v[50:51], v[50:51], v[244:245]
	v_max_f32_e32 v238, 0x1e3ce508, v238
	v_max_f32_e32 v239, 0x1e3ce508, v239
	v_lshlrev_b32_e32 v244, 16, v135
	v_and_b32_e32 v245, 0xffff0000, v135
	v_lshlrev_b32_e32 v246, 16, v139
	v_and_b32_e32 v247, 0xffff0000, v139
	v_max_f32_e32 v246, 0x1e3ce508, v246
	v_max_f32_e32 v247, 0x1e3ce508, v247
	v_rcp_f32_e32 v246, v246
	v_rcp_f32_e32 v247, v247
	v_pk_mul_f32 v[238:239], v[238:239], v[240:241]
	v_pk_mul_f32 v[44:45], v[44:45], v[238:239]
	v_max_f32_e32 v244, 0x1e3ce508, v244
	v_max_f32_e32 v245, 0x1e3ce508, v245
	v_pk_mul_f32 v[244:245], v[244:245], v[246:247]
	v_pk_mul_f32 v[46:47], v[46:47], v[244:245]
	s_waitcnt vmcnt(8)
; __device__ __forceinline__ void unpack8(const u32x4 w, f32x4& a, f32x4& b) { a[0] = bf_lo(w.x); a[1] = bf_hi(w.x); a[2] = bf_lo(w.y); a[3] = bf_hi(w.y); b[0] = bf_lo(w.z); b[1] = bf_hi(w.z); b[2] = bf_lo(w.w); b[3] = bf_hi(w.w); }
;     __device__ __forceinline__ void mid(AccT& acc, const Unit& u, int t, int wr, int wc, int fr, int fq) const {
;     ...
;                 for (int bj = 0; bj < 2; ++bj) { const bf16_t* gp = Z + (size_t)(row0 + ai * 128 + m * 16) * ZW + ZG + seg * 2048 + col0 + bj * 128; ga[m][bj] = *(const u32x4*)gp; gb[m][bj] = *(const u32x4*)(gp + 2048); }
; #pragma unroll
;             for (int m = 0; m < 4; ++m)
; #pragma unroll
;                 for (int bj = 0; bj < 2; ++bj) {
;                     f32x4 a0, a1, b0, b1; unpack8(ga[m][bj], a0, a1); unpack8(gb[m][bj], b0, b1);
; #pragma unroll
;                     for (int j = 0; j < 4; ++j) { a0[j] = fmaxf(a0[j], 1e-20f) * __builtin_amdgcn_rcpf(fmaxf(b0[j], 1e-20f)); a1[j] = fmaxf(a1[j], 1e-20f) * __builtin_amdgcn_rcpf(fmaxf(b1[j], 1e-20f)); }
;                     acc[ai][bj][m][0] *= a0; acc[ai][bj][m][1] *= a1;
;                 }
	v_lshlrev_b32_e32 v238, 16, v140
	v_and_b32_e32 v239, 0xffff0000, v140
	v_lshlrev_b32_e32 v240, 16, v144
	v_and_b32_e32 v241, 0xffff0000, v144
	v_max_f32_e32 v240, 0x1e3ce508, v240
	v_max_f32_e32 v241, 0x1e3ce508, v241
	v_rcp_f32_e32 v240, v240
	v_rcp_f32_e32 v241, v241
	v_max_f32_e32 v238, 0x1e3ce508, v238
	v_max_f32_e32 v239, 0x1e3ce508, v239
	v_lshlrev_b32_e32 v244, 16, v141
	v_and_b32_e32 v245, 0xffff0000, v141
	v_lshlrev_b32_e32 v246, 16, v145
	v_and_b32_e32 v247, 0xffff0000, v145
	v_max_f32_e32 v246, 0x1e3ce508, v246
	v_max_f32_e32 v247, 0x1e3ce508, v247
	v_rcp_f32_e32 v246, v246
	v_rcp_f32_e32 v247, v247
	v_pk_mul_f32 v[238:239], v[238:239], v[240:241]
	v_pk_mul_f32 v[40:41], v[40:41], v[238:239]
	v_max_f32_e32 v244, 0x1e3ce508, v244
	v_max_f32_e32 v245, 0x1e3ce508, v245
	v_lshlrev_b32_e32 v238, 16, v142
	v_and_b32_e32 v239, 0xffff0000, v142
	v_lshlrev_b32_e32 v240, 16, v146
	v_and_b32_e32 v241, 0xffff0000, v146
	v_max_f32_e32 v240, 0x1e3ce508, v240
	v_max_f32_e32 v241, 0x1e3ce508, v241
	v_rcp_f32_e32 v240, v240
	v_rcp_f32_e32 v241, v241
	v_pk_mul_f32 v[244:245], v[244:245], v[246:247]
	v_pk_mul_f32 v[42:43], v[42:43], v[244:245]
	v_max_f32_e32 v238, 0x1e3ce508, v238
	v_max_f32_e32 v239, 0x1e3ce508, v239
	v_lshlrev_b32_e32 v244, 16, v143
	v_and_b32_e32 v245, 0xffff0000, v143
	v_lshlrev_b32_e32 v246, 16, v147
	v_and_b32_e32 v247, 0xffff0000, v147
	v_max_f32_e32 v246, 0x1e3ce508, v246
	v_max_f32_e32 v247, 0x1e3ce508, v247
	v_rcp_f32_e32 v246, v246
	v_rcp_f32_e32 v247, v247
	v_pk_mul_f32 v[238:239], v[238:239], v[240:241]
	v_pk_mul_f32 v[36:37], v[36:37], v[238:239]
	v_max_f32_e32 v244, 0x1e3ce508, v244
	v_max_f32_e32 v245, 0x1e3ce508, v245
	v_pk_mul_f32 v[244:245], v[244:245], v[246:247]
	v_pk_mul_f32 v[38:39], v[38:39], v[244:245]
	s_waitcnt vmcnt(6)
	v_lshlrev_b32_e32 v238, 16, v148
	v_and_b32_e32 v239, 0xffff0000, v148
	v_lshlrev_b32_e32 v240, 16, v152
	v_and_b32_e32 v241, 0xffff0000, v152
	v_max_f32_e32 v240, 0x1e3ce508, v240
	v_max_f32_e32 v241, 0x1e3ce508, v241
	v_rcp_f32_e32 v240, v240
	v_rcp_f32_e32 v241, v241
	v_max_f32_e32 v238, 0x1e3ce508, v238
	v_max_f32_e32 v239, 0x1e3ce508, v239
	v_lshlrev_b32_e32 v244, 16, v149
	v_and_b32_e32 v245, 0xffff0000, v149
	v_lshlrev_b32_e32 v246, 16, v153
	v_and_b32_e32 v247, 0xffff0000, v153
	v_max_f32_e32 v246, 0x1e3ce508, v246
	v_max_f32_e32 v247, 0x1e3ce508, v247
	v_rcp_f32_e32 v246, v246
	v_rcp_f32_e32 v247, v247
	v_pk_mul_f32 v[238:239], v[238:239], v[240:241]
	v_pk_mul_f32 v[32:33], v[32:33], v[238:239]
	v_max_f32_e32 v244, 0x1e3ce508, v244
	v_max_f32_e32 v245, 0x1e3ce508, v245
	v_lshlrev_b32_e32 v238, 16, v150
	v_and_b32_e32 v239, 0xffff0000, v150
	v_lshlrev_b32_e32 v240, 16, v154
	v_and_b32_e32 v241, 0xffff0000, v154
	v_max_f32_e32 v240, 0x1e3ce508, v240
	v_max_f32_e32 v241, 0x1e3ce508, v241
	v_rcp_f32_e32 v240, v240
	v_rcp_f32_e32 v241, v241
	v_pk_mul_f32 v[244:245], v[244:245], v[246:247]
	v_pk_mul_f32 v[34:35], v[34:35], v[244:245]
	v_max_f32_e32 v238, 0x1e3ce508, v238
	v_max_f32_e32 v239, 0x1e3ce508, v239
	v_lshlrev_b32_e32 v244, 16, v151
	v_and_b32_e32 v245, 0xffff0000, v151
	v_lshlrev_b32_e32 v246, 16, v155
	v_and_b32_e32 v247, 0xffff0000, v155
	v_max_f32_e32 v246, 0x1e3ce508, v246
	v_max_f32_e32 v247, 0x1e3ce508, v247
	v_rcp_f32_e32 v246, v246
	v_rcp_f32_e32 v247, v247
	v_pk_mul_f32 v[238:239], v[238:239], v[240:241]
	v_pk_mul_f32 v[28:29], v[28:29], v[238:239]
	v_max_f32_e32 v244, 0x1e3ce508, v244
	v_max_f32_e32 v245, 0x1e3ce508, v245
	v_pk_mul_f32 v[244:245], v[244:245], v[246:247]
	v_pk_mul_f32 v[30:31], v[30:31], v[244:245]
	s_waitcnt vmcnt(4)
; __device__ __forceinline__ void unpack8(const u32x4 w, f32x4& a, f32x4& b) { a[0] = bf_lo(w.x); a[1] = bf_hi(w.x); a[2] = bf_lo(w.y); a[3] = bf_hi(w.y); b[0] = bf_lo(w.z); b[1] = bf_hi(w.z); b[2] = bf_lo(w.w); b[3] = bf_hi(w.w); }
;     __device__ __forceinline__ void mid(AccT& acc, const Unit& u, int t, int wr, int wc, int fr, int fq) const {
;     ...
;                 for (int bj = 0; bj < 2; ++bj) { const bf16_t* gp = Z + (size_t)(row0 + ai * 128 + m * 16) * ZW + ZG + seg * 2048 + col0 + bj * 128; ga[m][bj] = *(const u32x4*)gp; gb[m][bj] = *(const u32x4*)(gp + 2048); }
; #pragma unroll
;             for (int m = 0; m < 4; ++m)
; #pragma unroll
;                 for (int bj = 0; bj < 2; ++bj) {
;                     f32x4 a0, a1, b0, b1; unpack8(ga[m][bj], a0, a1); unpack8(gb[m][bj], b0, b1);
; #pragma unroll
;                     for (int j = 0; j < 4; ++j) { a0[j] = fmaxf(a0[j], 1e-20f) * __builtin_amdgcn_rcpf(fmaxf(b0[j], 1e-20f)); a1[j] = fmaxf(a1[j], 1e-20f) * __builtin_amdgcn_rcpf(fmaxf(b1[j], 1e-20f)); }
;                     acc[ai][bj][m][0] *= a0; acc[ai][bj][m][1] *= a1;
;                 }
;             asm volatile("" ::: "memory");
;         }
;     }
	v_lshlrev_b32_e32 v238, 16, v156
	v_and_b32_e32 v239, 0xffff0000, v156
	v_lshlrev_b32_e32 v240, 16, v160
	v_and_b32_e32 v241, 0xffff0000, v160
	v_max_f32_e32 v240, 0x1e3ce508, v240
	v_max_f32_e32 v241, 0x1e3ce508, v241
	v_rcp_f32_e32 v240, v240
	v_rcp_f32_e32 v241, v241
	v_max_f32_e32 v238, 0x1e3ce508, v238
	v_max_f32_e32 v239, 0x1e3ce508, v239
	v_lshlrev_b32_e32 v244, 16, v157
	v_and_b32_e32 v245, 0xffff0000, v157
	v_lshlrev_b32_e32 v246, 16, v161
	v_and_b32_e32 v247, 0xffff0000, v161
	v_max_f32_e32 v246, 0x1e3ce508, v246
	v_max_f32_e32 v247, 0x1e3ce508, v247
	v_rcp_f32_e32 v246, v246
	v_rcp_f32_e32 v247, v247
	v_pk_mul_f32 v[238:239], v[238:239], v[240:241]
	v_pk_mul_f32 v[24:25], v[24:25], v[238:239]
	v_max_f32_e32 v244, 0x1e3ce508, v244
	v_max_f32_e32 v245, 0x1e3ce508, v245
	v_lshlrev_b32_e32 v238, 16, v158
	v_and_b32_e32 v239, 0xffff0000, v158
	v_lshlrev_b32_e32 v240, 16, v162
	v_and_b32_e32 v241, 0xffff0000, v162
	v_max_f32_e32 v240, 0x1e3ce508, v240
	v_max_f32_e32 v241, 0x1e3ce508, v241
	v_rcp_f32_e32 v240, v240
	v_rcp_f32_e32 v241, v241
	v_pk_mul_f32 v[244:245], v[244:245], v[246:247]
	v_pk_mul_f32 v[26:27], v[26:27], v[244:245]
	v_max_f32_e32 v238, 0x1e3ce508, v238
	v_max_f32_e32 v239, 0x1e3ce508, v239
	v_lshlrev_b32_e32 v244, 16, v159
	v_and_b32_e32 v245, 0xffff0000, v159
	v_lshlrev_b32_e32 v246, 16, v163
	v_and_b32_e32 v247, 0xffff0000, v163
	v_max_f32_e32 v246, 0x1e3ce508, v246
	v_max_f32_e32 v247, 0x1e3ce508, v247
	v_rcp_f32_e32 v246, v246
	v_rcp_f32_e32 v247, v247
	v_pk_mul_f32 v[238:239], v[238:239], v[240:241]
	v_pk_mul_f32 v[20:21], v[20:21], v[238:239]
	v_max_f32_e32 v244, 0x1e3ce508, v244
	v_max_f32_e32 v245, 0x1e3ce508, v245
	v_pk_mul_f32 v[244:245], v[244:245], v[246:247]
	v_pk_mul_f32 v[22:23], v[22:23], v[244:245]
	s_waitcnt vmcnt(2)
	v_lshlrev_b32_e32 v238, 16, v164
	v_and_b32_e32 v239, 0xffff0000, v164
	v_lshlrev_b32_e32 v240, 16, v168
	v_and_b32_e32 v241, 0xffff0000, v168
	v_max_f32_e32 v240, 0x1e3ce508, v240
	v_max_f32_e32 v241, 0x1e3ce508, v241
	v_rcp_f32_e32 v240, v240
	v_rcp_f32_e32 v241, v241
	v_max_f32_e32 v238, 0x1e3ce508, v238
	v_max_f32_e32 v239, 0x1e3ce508, v239
	v_lshlrev_b32_e32 v244, 16, v165
	v_and_b32_e32 v245, 0xffff0000, v165
	v_lshlrev_b32_e32 v246, 16, v169
	v_and_b32_e32 v247, 0xffff0000, v169
	v_max_f32_e32 v246, 0x1e3ce508, v246
	v_max_f32_e32 v247, 0x1e3ce508, v247
	v_rcp_f32_e32 v246, v246
	v_rcp_f32_e32 v247, v247
	v_pk_mul_f32 v[238:239], v[238:239], v[240:241]
	v_pk_mul_f32 v[16:17], v[16:17], v[238:239]
	v_max_f32_e32 v244, 0x1e3ce508, v244
	v_max_f32_e32 v245, 0x1e3ce508, v245
	v_lshlrev_b32_e32 v238, 16, v166
	v_and_b32_e32 v239, 0xffff0000, v166
	v_lshlrev_b32_e32 v240, 16, v170
	v_and_b32_e32 v241, 0xffff0000, v170
	v_max_f32_e32 v240, 0x1e3ce508, v240
	v_max_f32_e32 v241, 0x1e3ce508, v241
	v_rcp_f32_e32 v240, v240
	v_rcp_f32_e32 v241, v241
	v_pk_mul_f32 v[244:245], v[244:245], v[246:247]
	v_pk_mul_f32 v[18:19], v[18:19], v[244:245]
	v_max_f32_e32 v238, 0x1e3ce508, v238
	v_max_f32_e32 v239, 0x1e3ce508, v239
	v_lshlrev_b32_e32 v244, 16, v167
	v_and_b32_e32 v245, 0xffff0000, v167
	v_lshlrev_b32_e32 v246, 16, v171
	v_and_b32_e32 v247, 0xffff0000, v171
	v_max_f32_e32 v246, 0x1e3ce508, v246
	v_max_f32_e32 v247, 0x1e3ce508, v247
	v_rcp_f32_e32 v246, v246
	v_rcp_f32_e32 v247, v247
	v_pk_mul_f32 v[238:239], v[238:239], v[240:241]
	v_pk_mul_f32 v[12:13], v[12:13], v[238:239]
	v_max_f32_e32 v244, 0x1e3ce508, v244
	v_max_f32_e32 v245, 0x1e3ce508, v245
	v_pk_mul_f32 v[244:245], v[244:245], v[246:247]
	v_pk_mul_f32 v[14:15], v[14:15], v[244:245]
	s_waitcnt vmcnt(0)
	v_lshlrev_b32_e32 v238, 16, v172
	v_and_b32_e32 v239, 0xffff0000, v172
	v_lshlrev_b32_e32 v240, 16, v176
	v_and_b32_e32 v241, 0xffff0000, v176
	v_max_f32_e32 v240, 0x1e3ce508, v240
	v_max_f32_e32 v241, 0x1e3ce508, v241
	v_rcp_f32_e32 v240, v240
	v_rcp_f32_e32 v241, v241
	v_max_f32_e32 v238, 0x1e3ce508, v238
	v_max_f32_e32 v239, 0x1e3ce508, v239
	v_lshlrev_b32_e32 v244, 16, v173
	v_and_b32_e32 v245, 0xffff0000, v173
	v_lshlrev_b32_e32 v246, 16, v177
	v_and_b32_e32 v247, 0xffff0000, v177
	v_max_f32_e32 v246, 0x1e3ce508, v246
	v_max_f32_e32 v247, 0x1e3ce508, v247
	v_rcp_f32_e32 v246, v246
	v_rcp_f32_e32 v247, v247
	v_pk_mul_f32 v[238:239], v[238:239], v[240:241]
	v_pk_mul_f32 v[8:9], v[8:9], v[238:239]
	v_max_f32_e32 v244, 0x1e3ce508, v244
	v_max_f32_e32 v245, 0x1e3ce508, v245
	v_lshlrev_b32_e32 v238, 16, v174
	v_and_b32_e32 v239, 0xffff0000, v174
	v_lshlrev_b32_e32 v240, 16, v178
	v_and_b32_e32 v241, 0xffff0000, v178
	v_max_f32_e32 v240, 0x1e3ce508, v240
	v_max_f32_e32 v241, 0x1e3ce508, v241
	v_rcp_f32_e32 v240, v240
	v_rcp_f32_e32 v241, v241
	v_pk_mul_f32 v[244:245], v[244:245], v[246:247]
	v_pk_mul_f32 v[10:11], v[10:11], v[244:245]
	v_max_f32_e32 v238, 0x1e3ce508, v238
	v_max_f32_e32 v239, 0x1e3ce508, v239
	v_lshlrev_b32_e32 v244, 16, v175
	v_and_b32_e32 v245, 0xffff0000, v175
	v_lshlrev_b32_e32 v246, 16, v179
	v_and_b32_e32 v247, 0xffff0000, v179
	v_max_f32_e32 v246, 0x1e3ce508, v246
	v_max_f32_e32 v247, 0x1e3ce508, v247
	v_rcp_f32_e32 v246, v246
	v_rcp_f32_e32 v247, v247
	v_pk_mul_f32 v[238:239], v[238:239], v[240:241]
	v_pk_mul_f32 v[4:5], v[4:5], v[238:239]
	v_max_f32_e32 v244, 0x1e3ce508, v244
	v_max_f32_e32 v245, 0x1e3ce508, v245
	v_pk_mul_f32 v[244:245], v[244:245], v[246:247]
	v_pk_mul_f32 v[6:7], v[6:7], v[244:245]

; #define PG8_STAGE(bufoff, gbase, voff) do { _Pragma("unroll") for (int _i = 0; _i < 2; ++_i) \
;         __builtin_amdgcn_global_load_lds((const unsigned*)((const char*)(gbase) + (voff)[_i]), (LAS unsigned*)(lds + (bufoff) + ldsw + _i * 8192), 16, 0, 0); } while (0)
; #define PG8_LDA(dst, b, h) do { _Pragma("unroll") for (int m = 0; m < 4; ++m) _Pragma("unroll") for (int k = 0; k < 2; ++k) dst[m][k] = *(const LAS bf16x8*)(lds + PG8_SA(b, h) + aoff + m * 2048 + k * 1024); } while (0)
; #define PG8_WAIT_V(n) asm volatile("s_waitcnt vmcnt(" #n ")" ::: "memory")
; #define PG8_BAR __builtin_amdgcn_s_barrier()
; template <class Epi, class Sched>
; __device__ __forceinline__ void gemm_phase(LAS unsigned char* lds_in, const int lda, const int ldb, const Sched& S, const Epi& E, const int WID) {
;     ...
;         for (int t = tb; t < te; t += 2) {
;             const bool last = (t == nt - 2);
;             const char* a1 = cA + (size_t)(t + 1) * kstep;
;             const char* a2 = last ? nA : cA + (size_t)(t + 2) * kstep; const char* b2 = last ? nB : cB + (size_t)(t + 2) * kstep;
;             const char* a3 = a2 + kstep; const char* b3 = b2 + kstep;
;             PG8_LDB(B0, 0, 0); PG8_SCHED; PG8_LDA(At, 0, 0); PG8_STAGE(PG8_SA(1, 1), a1 + hstepA, voffA);
;             PG8_WAIT_L(8); PG8_BAR; PG8_WAIT_L(0); PG8_MMA(0, 0, At, B0); PG8_BAR; PG8_SCHED;
;             PG8_LDB(B1, 0, 1); PG8_STAGE(PG8_SB(0, 0), b2, voffB);
;             PG8_BAR; PG8_WAIT_L(0); PG8_MMA(0, 1, At, B1); PG8_BAR;
;             PG8_LDA(At, 0, 1); PG8_STAGE(PG8_SA(0, 0), a2, voffA);
;             PG8_BAR; PG8_WAIT_L(0); PG8_MMA(1, 0, At, B0); PG8_BAR; PG8_SCHED;
;             PG8_STAGE(PG8_SB(0, 1), b2 + hstepB, voffB);
;             PG8_WAIT_V(6); PG8_BAR; PG8_MMA(1, 1, At, B1); PG8_BAR;
;             PG8_LDB(B0, 1, 0); PG8_SCHED; PG8_LDA(At, 1, 0); PG8_STAGE(PG8_SA(0, 1), a2 + hstepA, voffA);
;             PG8_WAIT_L(8); PG8_BAR; PG8_WAIT_L(0); PG8_MMA(0, 0, At, B0); PG8_BAR; PG8_SCHED;
;             PG8_LDB(B1, 1, 1); PG8_STAGE(PG8_SB(1, 0), b3, voffB);
;             PG8_BAR; PG8_WAIT_L(0); PG8_MMA(0, 1, At, B1); PG8_BAR;
;             PG8_LDA(At, 1, 1); PG8_STAGE(PG8_SA(1, 0), a3, voffA);
;             PG8_BAR; PG8_WAIT_L(0); PG8_MMA(1, 0, At, B0); PG8_BAR; PG8_SCHED;
;             PG8_STAGE(PG8_SB(1, 1), b3 + hstepB, voffB);
;             PG8_WAIT_V(6); PG8_BAR; PG8_MMA(1, 1, At, B1); PG8_BAR;
.LBB0_344:
	v_add_u32_e32 v1, s23, v211
	ds_read_b128 v[134:137], v1
	ds_read_b128 v[138:141], v1 offset:1024
	ds_read_b128 v[142:145], v1 offset:2048
	ds_read_b128 v[146:149], v1 offset:3072
	s_add_i32 vcc_lo, vcc_lo, 2
	s_add_u32 s16, s14, s70
	s_addc_u32 s17, s15, 0
	s_add_u32 s66, s12, s70
	s_addc_u32 s67, s13, 0
	s_cmp_eq_u32 s70, s10
	s_cselect_b32 s19, s3, s17
	s_cselect_b32 s18, s2, s16
	s_cselect_b32 s17, s5, s67
	s_cselect_b32 s16, s4, s66
	v_lshl_add_u64 v[178:179], v[132:133], 0, s[70:71]
	s_add_i32 m0, s47, 0xc000
	ds_read_b128 v[150:153], v213
	ds_read_b128 v[154:157], v213 offset:1024
	ds_read_b128 v[158:161], v213 offset:2048
	ds_read_b128 v[162:165], v213 offset:3072
	ds_read_b128 v[166:169], v213 offset:4096
	ds_read_b128 v[170:173], v213 offset:5120
	ds_read_b128 v[174:177], v213 offset:6144
	ds_read_b128 v[200:203], v213 offset:7168
	global_load_lds_dwordx4 v[178:179], off
	v_lshl_add_u64 v[178:179], v[2:3], 0, s[70:71]
	s_add_i32 m0, s47, 0xe000
	s_nop 0
	global_load_lds_dwordx4 v[178:179], off
	s_waitcnt lgkmcnt(8)
	s_barrier
	s_waitcnt lgkmcnt(0)
	s_setprio 1
	s_waitcnt lgkmcnt(0)
	v_mfma_f32_16x16x32_bf16 v[128:131], v[134:137], v[150:153], v[128:131]
	v_mfma_f32_16x16x32_bf16 v[124:127], v[142:145], v[150:153], v[124:127]
	v_mfma_f32_16x16x32_bf16 v[112:115], v[134:137], v[158:161], v[112:115]
	v_mfma_f32_16x16x32_bf16 v[108:111], v[142:145], v[158:161], v[108:111]
	v_mfma_f32_16x16x32_bf16 v[96:99], v[134:137], v[166:169], v[96:99]
	v_mfma_f32_16x16x32_bf16 v[92:95], v[142:145], v[166:169], v[92:95]
	v_mfma_f32_16x16x32_bf16 v[80:83], v[134:137], v[174:177], v[80:83]
	v_mfma_f32_16x16x32_bf16 v[76:79], v[142:145], v[174:177], v[76:79]
	v_mfma_f32_16x16x32_bf16 v[128:131], v[138:141], v[154:157], v[128:131]
	v_mfma_f32_16x16x32_bf16 v[124:127], v[146:149], v[154:157], v[124:127]
	v_mfma_f32_16x16x32_bf16 v[112:115], v[138:141], v[162:165], v[112:115]
	v_mfma_f32_16x16x32_bf16 v[108:111], v[146:149], v[162:165], v[108:111]
	v_mfma_f32_16x16x32_bf16 v[96:99], v[138:141], v[170:173], v[96:99]
	v_mfma_f32_16x16x32_bf16 v[92:95], v[146:149], v[170:173], v[92:95]
	v_mfma_f32_16x16x32_bf16 v[80:83], v[138:141], v[200:203], v[80:83]
	v_mfma_f32_16x16x32_bf16 v[76:79], v[146:149], v[200:203], v[76:79]
	s_setprio 0
	s_barrier
	s_mov_b32 m0, s35
	v_add_u32_e32 v1, s50, v211
	ds_read_b128 v[204:207], v1
	ds_read_b128 v[214:217], v1 offset:1024
	ds_read_b128 v[218:221], v1 offset:2048
	ds_read_b128 v[222:225], v1 offset:3072
	global_load_lds_dwordx4 v186, s[16:17]
	s_mov_b32 m0, s46
	s_nop 0
	global_load_lds_dwordx4 v190, s[16:17]
	s_barrier
	s_waitcnt lgkmcnt(0)
	s_setprio 1
	s_waitcnt lgkmcnt(0)
	v_mfma_f32_16x16x32_bf16 v[120:123], v[204:207], v[150:153], v[120:123]
	v_mfma_f32_16x16x32_bf16 v[116:119], v[218:221], v[150:153], v[116:119]
	v_mfma_f32_16x16x32_bf16 v[104:107], v[204:207], v[158:161], v[104:107]
	v_mfma_f32_16x16x32_bf16 v[100:103], v[218:221], v[158:161], v[100:103]
	v_mfma_f32_16x16x32_bf16 v[88:91], v[204:207], v[166:169], v[88:91]
	v_mfma_f32_16x16x32_bf16 v[84:87], v[218:221], v[166:169], v[84:87]
	v_mfma_f32_16x16x32_bf16 v[72:75], v[204:207], v[174:177], v[72:75]
	v_mfma_f32_16x16x32_bf16 v[68:71], v[218:221], v[174:177], v[68:71]
	v_mfma_f32_16x16x32_bf16 v[120:123], v[214:217], v[154:157], v[120:123]
	v_mfma_f32_16x16x32_bf16 v[116:119], v[222:225], v[154:157], v[116:119]
	v_mfma_f32_16x16x32_bf16 v[104:107], v[214:217], v[162:165], v[104:107]
	v_mfma_f32_16x16x32_bf16 v[100:103], v[222:225], v[162:165], v[100:103]
	v_mfma_f32_16x16x32_bf16 v[88:91], v[214:217], v[170:173], v[88:91]
	v_mfma_f32_16x16x32_bf16 v[84:87], v[222:225], v[170:173], v[84:87]
	v_mfma_f32_16x16x32_bf16 v[72:75], v[214:217], v[200:203], v[72:75]
	v_mfma_f32_16x16x32_bf16 v[68:71], v[222:225], v[200:203], v[68:71]
	s_setprio 0
	s_mov_b32 m0, s47
	s_barrier
	ds_read_b128 v[150:153], v213 offset:16384
	ds_read_b128 v[154:157], v213 offset:17408
	ds_read_b128 v[158:161], v213 offset:18432
	ds_read_b128 v[162:165], v213 offset:19456
	ds_read_b128 v[166:169], v213 offset:20480
	ds_read_b128 v[170:173], v213 offset:21504
	ds_read_b128 v[174:177], v213 offset:22528
	ds_read_b128 v[200:203], v213 offset:23552
	global_load_lds_dwordx4 v184, s[18:19]
	s_mov_b32 m0, s49
	s_nop 0
	global_load_lds_dwordx4 v188, s[18:19]
	s_barrier
	s_waitcnt lgkmcnt(0)
	s_setprio 1
	s_waitcnt lgkmcnt(0)
	v_mfma_f32_16x16x32_bf16 v[64:67], v[134:137], v[150:153], v[64:67]
	v_mfma_f32_16x16x32_bf16 v[60:63], v[142:145], v[150:153], v[60:63]
	v_mfma_f32_16x16x32_bf16 v[48:51], v[134:137], v[158:161], v[48:51]
	v_mfma_f32_16x16x32_bf16 v[44:47], v[142:145], v[158:161], v[44:47]
	v_mfma_f32_16x16x32_bf16 v[32:35], v[134:137], v[166:169], v[32:35]
	v_mfma_f32_16x16x32_bf16 v[28:31], v[142:145], v[166:169], v[28:31]
	v_mfma_f32_16x16x32_bf16 v[16:19], v[134:137], v[174:177], v[16:19]
	v_mfma_f32_16x16x32_bf16 v[12:15], v[142:145], v[174:177], v[12:15]
	v_mfma_f32_16x16x32_bf16 v[64:67], v[138:141], v[154:157], v[64:67]
	v_mfma_f32_16x16x32_bf16 v[60:63], v[146:149], v[154:157], v[60:63]
	v_mfma_f32_16x16x32_bf16 v[48:51], v[138:141], v[162:165], v[48:51]
	v_mfma_f32_16x16x32_bf16 v[44:47], v[146:149], v[162:165], v[44:47]
	v_mfma_f32_16x16x32_bf16 v[32:35], v[138:141], v[170:173], v[32:35]
	v_mfma_f32_16x16x32_bf16 v[28:31], v[146:149], v[170:173], v[28:31]
	v_mfma_f32_16x16x32_bf16 v[16:19], v[138:141], v[200:203], v[16:19]
	v_mfma_f32_16x16x32_bf16 v[12:15], v[146:149], v[200:203], v[12:15]
	s_setprio 0
	s_barrier
	s_add_u32 s66, s16, 0xa0000
	s_addc_u32 s67, s17, 0
	s_mov_b32 m0, s51
	s_nop 0
	global_load_lds_dwordx4 v186, s[66:67]
	s_mov_b32 m0, s65
	s_nop 0
	global_load_lds_dwordx4 v190, s[66:67]
	s_waitcnt vmcnt(6)
	s_barrier
; #define PG8_STAGE(bufoff, gbase, voff) do { _Pragma("unroll") for (int _i = 0; _i < 2; ++_i) \
;         __builtin_amdgcn_global_load_lds((const unsigned*)((const char*)(gbase) + (voff)[_i]), (LAS unsigned*)(lds + (bufoff) + ldsw + _i * 8192), 16, 0, 0); } while (0)
; #define PG8_LDA(dst, b, h) do { _Pragma("unroll") for (int m = 0; m < 4; ++m) _Pragma("unroll") for (int k = 0; k < 2; ++k) dst[m][k] = *(const LAS bf16x8*)(lds + PG8_SA(b, h) + aoff + m * 2048 + k * 1024); } while (0)
; #define PG8_LDB(dst, b, h) do { _Pragma("unroll") for (int n = 0; n < 2; ++n) _Pragma("unroll") for (int k = 0; k < 2; ++k) dst[n][k] = *(const LAS bf16x8*)(lds + PG8_SB(b, h) + boff + n * 2048 + k * 1024); } while (0)
; #define PG8_MMA(ai, bj, At, Bt) do { __builtin_amdgcn_s_setprio(1); _Pragma("unroll") for (int m = 0; m < 4; ++m) _Pragma("unroll") for (int n = 0; n < 2; ++n) _Pragma("unroll") for (int k = 0; k < 2; ++k) \
;         acc[ai][bj][m][n] = __builtin_amdgcn_mfma_f32_16x16x32_bf16(Bt[n][k], At[m][k], acc[ai][bj][m][n], 0, 0, 0); __builtin_amdgcn_s_setprio(0); } while (0)
; #define PG8_WAIT_V(n) asm volatile("s_waitcnt vmcnt(" #n ")" ::: "memory")
; #define PG8_WAIT_L(n) asm volatile("s_waitcnt lgkmcnt(" #n ")" ::: "memory")
; #define PG8_BAR __builtin_amdgcn_s_barrier()
; #define PG8_SCHED __builtin_amdgcn_sched_barrier(0)
; template <class Epi, class Sched>
; __device__ __forceinline__ void gemm_phase(LAS unsigned char* lds_in, const int lda, const int ldb, const Sched& S, const Epi& E, const int WID) {
;     ...
;             PG8_LDB(B0, 1, 0); PG8_SCHED; PG8_LDA(At, 1, 0); PG8_STAGE(PG8_SA(0, 1), a2 + hstepA, voffA);
;             PG8_WAIT_L(8); PG8_BAR; PG8_WAIT_L(0); PG8_MMA(0, 0, At, B0); PG8_BAR; PG8_SCHED;
;             PG8_LDB(B1, 1, 1); PG8_STAGE(PG8_SB(1, 0), b3, voffB);
;             PG8_BAR; PG8_WAIT_L(0); PG8_MMA(0, 1, At, B1); PG8_BAR;
;             PG8_LDA(At, 1, 1); PG8_STAGE(PG8_SA(1, 0), a3, voffA);
;             PG8_BAR; PG8_WAIT_L(0); PG8_MMA(1, 0, At, B0); PG8_BAR; PG8_SCHED;
;             PG8_STAGE(PG8_SB(1, 1), b3 + hstepB, voffB);
;             PG8_WAIT_V(6); PG8_BAR; PG8_MMA(1, 1, At, B1); PG8_BAR;
	s_setprio 1
	v_mfma_f32_16x16x32_bf16 v[56:59], v[204:207], v[150:153], v[56:59]
	v_mfma_f32_16x16x32_bf16 v[52:55], v[218:221], v[150:153], v[52:55]
	v_mfma_f32_16x16x32_bf16 v[40:43], v[204:207], v[158:161], v[40:43]
	v_mfma_f32_16x16x32_bf16 v[36:39], v[218:221], v[158:161], v[36:39]
	v_mfma_f32_16x16x32_bf16 v[24:27], v[204:207], v[166:169], v[24:27]
	v_mfma_f32_16x16x32_bf16 v[20:23], v[218:221], v[166:169], v[20:23]
	v_mfma_f32_16x16x32_bf16 v[8:11], v[204:207], v[174:177], v[8:11]
	v_mfma_f32_16x16x32_bf16 v[4:7], v[218:221], v[174:177], v[4:7]
	v_mfma_f32_16x16x32_bf16 v[56:59], v[214:217], v[154:157], v[56:59]
	v_mfma_f32_16x16x32_bf16 v[52:55], v[222:225], v[154:157], v[52:55]
	v_mfma_f32_16x16x32_bf16 v[40:43], v[214:217], v[162:165], v[40:43]
	v_mfma_f32_16x16x32_bf16 v[36:39], v[222:225], v[162:165], v[36:39]
	v_mfma_f32_16x16x32_bf16 v[24:27], v[214:217], v[170:173], v[24:27]
	v_mfma_f32_16x16x32_bf16 v[20:23], v[222:225], v[170:173], v[20:23]
	v_mfma_f32_16x16x32_bf16 v[8:11], v[214:217], v[200:203], v[8:11]
	v_mfma_f32_16x16x32_bf16 v[4:7], v[222:225], v[200:203], v[4:7]
	s_setprio 0
	v_add_u32_e32 v1, s90, v211
	s_barrier
	ds_read_b128 v[134:137], v1
	ds_read_b128 v[138:141], v1 offset:1024
	ds_read_b128 v[142:145], v1 offset:2048
	ds_read_b128 v[146:149], v1 offset:3072
	s_add_u32 s18, s18, 0xa0000
	s_addc_u32 s19, s19, 0
	s_mov_b32 m0, s78
	ds_read_b128 v[150:153], v213 offset:32768
	ds_read_b128 v[154:157], v213 offset:33792
	ds_read_b128 v[158:161], v213 offset:34816
	ds_read_b128 v[162:165], v213 offset:35840
	ds_read_b128 v[166:169], v213 offset:36864
	ds_read_b128 v[170:173], v213 offset:37888
	ds_read_b128 v[174:177], v213 offset:38912
	ds_read_b128 v[200:203], v213 offset:39936
	global_load_lds_dwordx4 v184, s[18:19]
	s_mov_b32 m0, s79
	s_nop 0
	global_load_lds_dwordx4 v188, s[18:19]
	s_waitcnt lgkmcnt(8)
	s_barrier
	s_waitcnt lgkmcnt(0)
	s_setprio 1
	s_waitcnt lgkmcnt(0)
	v_mfma_f32_16x16x32_bf16 v[128:131], v[134:137], v[150:153], v[128:131]
	v_mfma_f32_16x16x32_bf16 v[124:127], v[142:145], v[150:153], v[124:127]
	v_mfma_f32_16x16x32_bf16 v[112:115], v[134:137], v[158:161], v[112:115]
	v_mfma_f32_16x16x32_bf16 v[108:111], v[142:145], v[158:161], v[108:111]
	v_mfma_f32_16x16x32_bf16 v[96:99], v[134:137], v[166:169], v[96:99]
	v_mfma_f32_16x16x32_bf16 v[92:95], v[142:145], v[166:169], v[92:95]
	v_mfma_f32_16x16x32_bf16 v[80:83], v[134:137], v[174:177], v[80:83]
	v_mfma_f32_16x16x32_bf16 v[76:79], v[142:145], v[174:177], v[76:79]
	v_mfma_f32_16x16x32_bf16 v[128:131], v[138:141], v[154:157], v[128:131]
	v_mfma_f32_16x16x32_bf16 v[124:127], v[146:149], v[154:157], v[124:127]
	v_mfma_f32_16x16x32_bf16 v[112:115], v[138:141], v[162:165], v[112:115]
	v_mfma_f32_16x16x32_bf16 v[108:111], v[146:149], v[162:165], v[108:111]
	v_mfma_f32_16x16x32_bf16 v[96:99], v[138:141], v[170:173], v[96:99]
	v_mfma_f32_16x16x32_bf16 v[92:95], v[146:149], v[170:173], v[92:95]
	v_mfma_f32_16x16x32_bf16 v[80:83], v[138:141], v[200:203], v[80:83]
	v_mfma_f32_16x16x32_bf16 v[76:79], v[146:149], v[200:203], v[76:79]
	s_setprio 0
	s_barrier
	s_mov_b32 m0, s91
	v_add_u32_e32 v1, s21, v211
	s_add_u32 s100, s16, 0x80
	s_addc_u32 s101, s17, 0
	ds_read_b128 v[204:207], v1
	ds_read_b128 v[214:217], v1 offset:1024
	ds_read_b128 v[218:221], v1 offset:2048
	ds_read_b128 v[222:225], v1 offset:3072
	global_load_lds_dwordx4 v186, s[100:101]
	s_add_u32 s100, s16, 0x80
	s_addc_u32 s101, s17, 0
	s_mov_b32 m0, s92
	s_nop 0
	global_load_lds_dwordx4 v190, s[100:101]
	s_barrier
; #define PG8_STAGE(bufoff, gbase, voff) do { _Pragma("unroll") for (int _i = 0; _i < 2; ++_i) \
;         __builtin_amdgcn_global_load_lds((const unsigned*)((const char*)(gbase) + (voff)[_i]), (LAS unsigned*)(lds + (bufoff) + ldsw + _i * 8192), 16, 0, 0); } while (0)
; #define PG8_LDA(dst, b, h) do { _Pragma("unroll") for (int m = 0; m < 4; ++m) _Pragma("unroll") for (int k = 0; k < 2; ++k) dst[m][k] = *(const LAS bf16x8*)(lds + PG8_SA(b, h) + aoff + m * 2048 + k * 1024); } while (0)
; #define PG8_LDB(dst, b, h) do { _Pragma("unroll") for (int n = 0; n < 2; ++n) _Pragma("unroll") for (int k = 0; k < 2; ++k) dst[n][k] = *(const LAS bf16x8*)(lds + PG8_SB(b, h) + boff + n * 2048 + k * 1024); } while (0)
; #define PG8_MMA(ai, bj, At, Bt) do { __builtin_amdgcn_s_setprio(1); _Pragma("unroll") for (int m = 0; m < 4; ++m) _Pragma("unroll") for (int n = 0; n < 2; ++n) _Pragma("unroll") for (int k = 0; k < 2; ++k) \
;         acc[ai][bj][m][n] = __builtin_amdgcn_mfma_f32_16x16x32_bf16(Bt[n][k], At[m][k], acc[ai][bj][m][n], 0, 0, 0); __builtin_amdgcn_s_setprio(0); } while (0)
; #define PG8_WAIT_V(n) asm volatile("s_waitcnt vmcnt(" #n ")" ::: "memory")
; #define PG8_BAR __builtin_amdgcn_s_barrier()
; template <class Epi, class Sched>
; __device__ __forceinline__ void gemm_phase(LAS unsigned char* lds_in, const int lda, const int ldb, const Sched& S, const Epi& E, const int WID) {
;     ...
;         for (int sg = 0; sg < (Epi::HAS_MID ? 3 : 1); ++sg) {
;         const int tb = Epi::HAS_MID ? (sg == 0 ? 0 : (sg == 1 ? 16 : 24)) : 0, te = Epi::HAS_MID ? (sg == 0 ? 16 : (sg == 1 ? 24 : nt)) : nt;
;         if constexpr (Epi::HAS_MID) { if (sg > 0) { PG8_SCHED; E.mid(acc, cur, tb, wr, wc, fr, fq); PG8_SCHED; } }
;         for (int t = tb; t < te; t += 2) {
;     ...
;             PG8_LDB(B0, 1, 0); PG8_SCHED; PG8_LDA(At, 1, 0); PG8_STAGE(PG8_SA(0, 1), a2 + hstepA, voffA);
;             PG8_WAIT_L(8); PG8_BAR; PG8_WAIT_L(0); PG8_MMA(0, 0, At, B0); PG8_BAR; PG8_SCHED;
;             PG8_LDB(B1, 1, 1); PG8_STAGE(PG8_SB(1, 0), b3, voffB);
;             PG8_BAR; PG8_WAIT_L(0); PG8_MMA(0, 1, At, B1); PG8_BAR;
;             PG8_LDA(At, 1, 1); PG8_STAGE(PG8_SA(1, 0), a3, voffA);
;             PG8_BAR; PG8_WAIT_L(0); PG8_MMA(1, 0, At, B0); PG8_BAR; PG8_SCHED;
;             PG8_STAGE(PG8_SB(1, 1), b3 + hstepB, voffB);
;             PG8_WAIT_V(6); PG8_BAR; PG8_MMA(1, 1, At, B1); PG8_BAR;
	s_waitcnt lgkmcnt(0)
	s_setprio 1
	s_waitcnt lgkmcnt(0)
	v_mfma_f32_16x16x32_bf16 v[120:123], v[204:207], v[150:153], v[120:123]
	v_mfma_f32_16x16x32_bf16 v[116:119], v[218:221], v[150:153], v[116:119]
	v_mfma_f32_16x16x32_bf16 v[104:107], v[204:207], v[158:161], v[104:107]
	v_mfma_f32_16x16x32_bf16 v[100:103], v[218:221], v[158:161], v[100:103]
	v_mfma_f32_16x16x32_bf16 v[88:91], v[204:207], v[166:169], v[88:91]
	v_mfma_f32_16x16x32_bf16 v[84:87], v[218:221], v[166:169], v[84:87]
	v_mfma_f32_16x16x32_bf16 v[72:75], v[204:207], v[174:177], v[72:75]
	v_mfma_f32_16x16x32_bf16 v[68:71], v[218:221], v[174:177], v[68:71]
	v_mfma_f32_16x16x32_bf16 v[120:123], v[214:217], v[154:157], v[120:123]
	v_mfma_f32_16x16x32_bf16 v[116:119], v[222:225], v[154:157], v[116:119]
	v_mfma_f32_16x16x32_bf16 v[104:107], v[214:217], v[162:165], v[104:107]
	v_mfma_f32_16x16x32_bf16 v[100:103], v[222:225], v[162:165], v[100:103]
	v_mfma_f32_16x16x32_bf16 v[88:91], v[214:217], v[170:173], v[88:91]
	v_mfma_f32_16x16x32_bf16 v[84:87], v[222:225], v[170:173], v[84:87]
	v_mfma_f32_16x16x32_bf16 v[72:75], v[214:217], v[200:203], v[72:75]
	v_mfma_f32_16x16x32_bf16 v[68:71], v[222:225], v[200:203], v[68:71]
	s_setprio 0
	s_mov_b32 m0, s93
	s_add_u32 s100, s18, 0xfff60080
	s_addc_u32 s101, s19, -1
	s_barrier
	ds_read_b128 v[150:153], v213 offset:49152
	ds_read_b128 v[154:157], v213 offset:50176
	ds_read_b128 v[158:161], v213 offset:51200
	ds_read_b128 v[162:165], v213 offset:52224
	ds_read_b128 v[166:169], v213 offset:53248
	ds_read_b128 v[170:173], v213 offset:54272
	ds_read_b128 v[174:177], v213 offset:55296
	ds_read_b128 v[200:203], v213 offset:56320
	global_load_lds_dwordx4 v184, s[100:101]
	s_add_u32 s100, s18, 0xfff60080
	s_addc_u32 s101, s19, -1
	s_mov_b32 m0, s20
	s_nop 0
	global_load_lds_dwordx4 v188, s[100:101]
	s_barrier
	s_waitcnt lgkmcnt(0)
	s_setprio 1
	s_waitcnt lgkmcnt(0)
	v_mfma_f32_16x16x32_bf16 v[64:67], v[134:137], v[150:153], v[64:67]
	v_mfma_f32_16x16x32_bf16 v[60:63], v[142:145], v[150:153], v[60:63]
	v_mfma_f32_16x16x32_bf16 v[48:51], v[134:137], v[158:161], v[48:51]
	v_mfma_f32_16x16x32_bf16 v[44:47], v[142:145], v[158:161], v[44:47]
	v_mfma_f32_16x16x32_bf16 v[32:35], v[134:137], v[166:169], v[32:35]
	v_mfma_f32_16x16x32_bf16 v[28:31], v[142:145], v[166:169], v[28:31]
	v_mfma_f32_16x16x32_bf16 v[16:19], v[134:137], v[174:177], v[16:19]
	v_mfma_f32_16x16x32_bf16 v[12:15], v[142:145], v[174:177], v[12:15]
	v_mfma_f32_16x16x32_bf16 v[64:67], v[138:141], v[154:157], v[64:67]
	v_mfma_f32_16x16x32_bf16 v[60:63], v[146:149], v[154:157], v[60:63]
	v_mfma_f32_16x16x32_bf16 v[48:51], v[138:141], v[162:165], v[48:51]
	v_mfma_f32_16x16x32_bf16 v[44:47], v[146:149], v[162:165], v[44:47]
	v_mfma_f32_16x16x32_bf16 v[32:35], v[138:141], v[170:173], v[32:35]
	v_mfma_f32_16x16x32_bf16 v[28:31], v[146:149], v[170:173], v[28:31]
	v_mfma_f32_16x16x32_bf16 v[16:19], v[138:141], v[200:203], v[16:19]
	v_mfma_f32_16x16x32_bf16 v[12:15], v[146:149], v[200:203], v[12:15]
	s_setprio 0
	s_barrier
	s_add_u32 s16, s16, 0xa0080
	s_addc_u32 s17, s17, 0
	s_mov_b32 m0, s48
	s_nop 0
	global_load_lds_dwordx4 v186, s[16:17]
	s_mov_b32 m0, s22
	s_nop 0
	global_load_lds_dwordx4 v190, s[16:17]
	s_waitcnt vmcnt(6)
	s_barrier
	s_setprio 1
	v_mfma_f32_16x16x32_bf16 v[56:59], v[204:207], v[150:153], v[56:59]
	v_mfma_f32_16x16x32_bf16 v[52:55], v[218:221], v[150:153], v[52:55]
	v_mfma_f32_16x16x32_bf16 v[40:43], v[204:207], v[158:161], v[40:43]
	v_mfma_f32_16x16x32_bf16 v[36:39], v[218:221], v[158:161], v[36:39]
	v_mfma_f32_16x16x32_bf16 v[24:27], v[204:207], v[166:169], v[24:27]
	v_mfma_f32_16x16x32_bf16 v[20:23], v[218:221], v[166:169], v[20:23]
	v_mfma_f32_16x16x32_bf16 v[8:11], v[204:207], v[174:177], v[8:11]
	v_mfma_f32_16x16x32_bf16 v[4:7], v[218:221], v[174:177], v[4:7]
	v_mfma_f32_16x16x32_bf16 v[56:59], v[214:217], v[154:157], v[56:59]
	v_mfma_f32_16x16x32_bf16 v[52:55], v[222:225], v[154:157], v[52:55]
	v_mfma_f32_16x16x32_bf16 v[40:43], v[214:217], v[162:165], v[40:43]
	v_mfma_f32_16x16x32_bf16 v[36:39], v[222:225], v[162:165], v[36:39]
	v_mfma_f32_16x16x32_bf16 v[24:27], v[214:217], v[170:173], v[24:27]
	v_mfma_f32_16x16x32_bf16 v[20:23], v[222:225], v[170:173], v[20:23]
	v_mfma_f32_16x16x32_bf16 v[8:11], v[214:217], v[200:203], v[8:11]
	v_mfma_f32_16x16x32_bf16 v[4:7], v[222:225], v[200:203], v[4:7]
	s_setprio 0
	s_add_u32 s14, s14, 0x100
	s_addc_u32 s15, s15, 0
	s_add_u32 s12, s12, 0x100
	s_addc_u32 s13, s13, 0
	s_add_u32 s10, s10, 0xffffff00
	s_addc_u32 s11, s11, -1
	v_lshl_add_u64 v[132:133], v[132:133], 0, s[74:75]
	s_cmp_ge_u32 vcc_lo, vcc_hi
	v_lshl_add_u64 v[2:3], v[2:3], 0, s[74:75]
	s_barrier
	s_cbranch_scc0 .LBB0_344
	s_branch .LBB0_339

; #define PG8_STAGE(bufoff, gbase, voff) do { _Pragma("unroll") for (int _i = 0; _i < 2; ++_i) \
;         __builtin_amdgcn_global_load_lds((const unsigned*)((const char*)(gbase) + (voff)[_i]), (LAS unsigned*)(lds + (bufoff) + ldsw + _i * 8192), 16, 0, 0); } while (0)
; #define PG8_LDA(dst, b, h) do { _Pragma("unroll") for (int m = 0; m < 4; ++m) _Pragma("unroll") for (int k = 0; k < 2; ++k) dst[m][k] = *(const LAS bf16x8*)(lds + PG8_SA(b, h) + aoff + m * 2048 + k * 1024); } while (0)
; #define PG8_LDB(dst, b, h) do { _Pragma("unroll") for (int n = 0; n < 2; ++n) _Pragma("unroll") for (int k = 0; k < 2; ++k) dst[n][k] = *(const LAS bf16x8*)(lds + PG8_SB(b, h) + boff + n * 2048 + k * 1024); } while (0)
; #define PG8_MMA(ai, bj, At, Bt) do { __builtin_amdgcn_s_setprio(1); _Pragma("unroll") for (int m = 0; m < 4; ++m) _Pragma("unroll") for (int n = 0; n < 2; ++n) _Pragma("unroll") for (int k = 0; k < 2; ++k) \
;         acc[ai][bj][m][n] = __builtin_amdgcn_mfma_f32_16x16x32_bf16(Bt[n][k], At[m][k], acc[ai][bj][m][n], 0, 0, 0); __builtin_amdgcn_s_setprio(0); } while (0)
; #define PG8_WAIT_V(n) asm volatile("s_waitcnt vmcnt(" #n ")" ::: "memory")
; #define PG8_WAIT_L(n) asm volatile("s_waitcnt lgkmcnt(" #n ")" ::: "memory")
; #define PG8_BAR __builtin_amdgcn_s_barrier()
; #define PG8_SCHED __builtin_amdgcn_sched_barrier(0)
; template <class Epi, class Sched>
; __device__ __forceinline__ void gemm_phase(LAS unsigned char* lds_in, const int lda, const int ldb, const Sched& S, const Epi& E, const int WID) {
;     ...
;             PG8_LDB(B0, 0, 0); PG8_SCHED; PG8_LDA(At, 0, 0); PG8_STAGE(PG8_SA(1, 1), a1 + hstepA, voffA);
;             PG8_WAIT_L(8); PG8_BAR; PG8_WAIT_L(0); PG8_MMA(0, 0, At, B0); PG8_BAR; PG8_SCHED;
;             PG8_LDB(B1, 0, 1); PG8_STAGE(PG8_SB(0, 0), b2, voffB);
;             PG8_BAR; PG8_WAIT_L(0); PG8_MMA(0, 1, At, B1); PG8_BAR;
;             PG8_LDA(At, 0, 1); PG8_STAGE(PG8_SA(0, 0), a2, voffA);
;             PG8_BAR; PG8_WAIT_L(0); PG8_MMA(1, 0, At, B0); PG8_BAR; PG8_SCHED;
;             PG8_STAGE(PG8_SB(0, 1), b2 + hstepB, voffB);
;             PG8_WAIT_V(6); PG8_BAR; PG8_MMA(1, 1, At, B1); PG8_BAR;
.LBB0_922:
	v_add_u32_e32 v153, s3, v150
	ds_read_b128 v[142:145], v153
	ds_read_b128 v[146:149], v153 offset:1024
	ds_read_b128 v[154:157], v153 offset:2048
	ds_read_b128 v[158:161], v153 offset:3072
	s_add_u32 s16, s14, 0xfff80080
	s_addc_u32 s17, s15, -1
	s_cmp_eq_u32 vcc_lo, 28
	s_cselect_b32 s19, s9, s17
	s_cselect_b32 s18, s8, s16
	s_cselect_b32 s17, s11, s13
	s_cselect_b32 s16, s10, s7
	s_add_i32 m0, s22, 0xc000
	ds_read_b128 v[162:165], v152
	ds_read_b128 v[166:169], v152 offset:1024
	ds_read_b128 v[170:173], v152 offset:2048
	ds_read_b128 v[174:177], v152 offset:3072
	ds_read_b128 v[178:181], v152 offset:4096
	ds_read_b128 v[182:185], v152 offset:5120
	ds_read_b128 v[186:189], v152 offset:6144
	ds_read_b128 v[190:193], v152 offset:7168
	global_load_lds_dwordx4 v138, s[14:15]
	s_add_i32 m0, s22, 0xe000
	s_nop 0
	global_load_lds_dwordx4 v140, s[14:15]
	s_waitcnt lgkmcnt(8)
	s_barrier
	s_waitcnt lgkmcnt(0)
	s_setprio 1
	s_waitcnt lgkmcnt(0)
	v_mfma_f32_16x16x32_bf16 v[126:129], v[142:145], v[162:165], v[126:129]
	v_mfma_f32_16x16x32_bf16 v[122:125], v[154:157], v[162:165], v[122:125]
	v_mfma_f32_16x16x32_bf16 v[118:121], v[142:145], v[170:173], v[118:121]
	v_mfma_f32_16x16x32_bf16 v[114:117], v[154:157], v[170:173], v[114:117]
	v_mfma_f32_16x16x32_bf16 v[110:113], v[142:145], v[178:181], v[110:113]
	v_mfma_f32_16x16x32_bf16 v[106:109], v[154:157], v[178:181], v[106:109]
	v_mfma_f32_16x16x32_bf16 v[102:105], v[142:145], v[186:189], v[102:105]
	v_mfma_f32_16x16x32_bf16 v[98:101], v[154:157], v[186:189], v[98:101]
	v_mfma_f32_16x16x32_bf16 v[126:129], v[146:149], v[166:169], v[126:129]
	v_mfma_f32_16x16x32_bf16 v[122:125], v[158:161], v[166:169], v[122:125]
	v_mfma_f32_16x16x32_bf16 v[118:121], v[146:149], v[174:177], v[118:121]
	v_mfma_f32_16x16x32_bf16 v[114:117], v[158:161], v[174:177], v[114:117]
	v_mfma_f32_16x16x32_bf16 v[110:113], v[146:149], v[182:185], v[110:113]
	v_mfma_f32_16x16x32_bf16 v[106:109], v[158:161], v[182:185], v[106:109]
	v_mfma_f32_16x16x32_bf16 v[102:105], v[146:149], v[190:193], v[102:105]
	v_mfma_f32_16x16x32_bf16 v[98:101], v[158:161], v[190:193], v[98:101]
	s_setprio 0
	s_barrier
	s_mov_b32 m0, s20
	v_add_u32_e32 v153, s35, v150
	ds_read_b128 v[194:197], v153
	ds_read_b128 v[198:201], v153 offset:1024
	ds_read_b128 v[202:205], v153 offset:2048
	ds_read_b128 v[206:209], v153 offset:3072
	global_load_lds_dwordx4 v132, s[16:17]
	s_mov_b32 m0, s21
	s_nop 0
	global_load_lds_dwordx4 v136, s[16:17]
	s_barrier
	s_waitcnt lgkmcnt(0)
	s_setprio 1
	s_waitcnt lgkmcnt(0)
	v_mfma_f32_16x16x32_bf16 v[70:73], v[194:197], v[162:165], v[70:73]
	v_mfma_f32_16x16x32_bf16 v[62:65], v[202:205], v[162:165], v[62:65]
	v_mfma_f32_16x16x32_bf16 v[54:57], v[194:197], v[170:173], v[54:57]
	v_mfma_f32_16x16x32_bf16 v[50:53], v[202:205], v[170:173], v[50:53]
	v_mfma_f32_16x16x32_bf16 v[46:49], v[194:197], v[178:181], v[46:49]
	v_mfma_f32_16x16x32_bf16 v[42:45], v[202:205], v[178:181], v[42:45]
	v_mfma_f32_16x16x32_bf16 v[38:41], v[194:197], v[186:189], v[38:41]
	v_mfma_f32_16x16x32_bf16 v[34:37], v[202:205], v[186:189], v[34:37]
	v_mfma_f32_16x16x32_bf16 v[70:73], v[198:201], v[166:169], v[70:73]
	v_mfma_f32_16x16x32_bf16 v[62:65], v[206:209], v[166:169], v[62:65]
	v_mfma_f32_16x16x32_bf16 v[54:57], v[198:201], v[174:177], v[54:57]
	v_mfma_f32_16x16x32_bf16 v[50:53], v[206:209], v[174:177], v[50:53]
	v_mfma_f32_16x16x32_bf16 v[46:49], v[198:201], v[182:185], v[46:49]
	v_mfma_f32_16x16x32_bf16 v[42:45], v[206:209], v[182:185], v[42:45]
	v_mfma_f32_16x16x32_bf16 v[38:41], v[198:201], v[190:193], v[38:41]
	v_mfma_f32_16x16x32_bf16 v[34:37], v[206:209], v[190:193], v[34:37]
	s_setprio 0
	s_mov_b32 m0, s22
	s_barrier
	ds_read_b128 v[162:165], v152 offset:16384
	ds_read_b128 v[166:169], v152 offset:17408
	ds_read_b128 v[170:173], v152 offset:18432
	ds_read_b128 v[174:177], v152 offset:19456
	ds_read_b128 v[178:181], v152 offset:20480
	ds_read_b128 v[182:185], v152 offset:21504
	ds_read_b128 v[186:189], v152 offset:22528
	ds_read_b128 v[190:193], v152 offset:23552
	global_load_lds_dwordx4 v130, s[18:19]
	s_mov_b32 m0, s23
	s_nop 0
	global_load_lds_dwordx4 v134, s[18:19]
	s_barrier
	s_waitcnt lgkmcnt(0)
	s_setprio 1
	s_waitcnt lgkmcnt(0)
	v_mfma_f32_16x16x32_bf16 v[94:97], v[142:145], v[162:165], v[94:97]
	v_mfma_f32_16x16x32_bf16 v[90:93], v[154:157], v[162:165], v[90:93]
	v_mfma_f32_16x16x32_bf16 v[86:89], v[142:145], v[170:173], v[86:89]
	v_mfma_f32_16x16x32_bf16 v[82:85], v[154:157], v[170:173], v[82:85]
	v_mfma_f32_16x16x32_bf16 v[78:81], v[142:145], v[178:181], v[78:81]
	v_mfma_f32_16x16x32_bf16 v[74:77], v[154:157], v[178:181], v[74:77]
	v_mfma_f32_16x16x32_bf16 v[66:69], v[142:145], v[186:189], v[66:69]
	v_mfma_f32_16x16x32_bf16 v[58:61], v[154:157], v[186:189], v[58:61]
	v_mfma_f32_16x16x32_bf16 v[94:97], v[146:149], v[166:169], v[94:97]
	v_mfma_f32_16x16x32_bf16 v[90:93], v[158:161], v[166:169], v[90:93]
	v_mfma_f32_16x16x32_bf16 v[86:89], v[146:149], v[174:177], v[86:89]
	v_mfma_f32_16x16x32_bf16 v[82:85], v[158:161], v[174:177], v[82:85]
	v_mfma_f32_16x16x32_bf16 v[78:81], v[146:149], v[182:185], v[78:81]
	v_mfma_f32_16x16x32_bf16 v[74:77], v[158:161], v[182:185], v[74:77]
	v_mfma_f32_16x16x32_bf16 v[66:69], v[146:149], v[190:193], v[66:69]
	v_mfma_f32_16x16x32_bf16 v[58:61], v[158:161], v[190:193], v[58:61]
	s_setprio 0
	s_barrier
	s_add_u32 s66, s16, 0x400000
	s_addc_u32 s67, s17, 0
	s_mov_b32 m0, s46
	s_nop 0
	global_load_lds_dwordx4 v132, s[66:67]
	s_mov_b32 m0, s47
	s_nop 0
	global_load_lds_dwordx4 v136, s[66:67]
	s_waitcnt vmcnt(6)
	s_barrier
; #define PG8_STAGE(bufoff, gbase, voff) do { _Pragma("unroll") for (int _i = 0; _i < 2; ++_i) \
;         __builtin_amdgcn_global_load_lds((const unsigned*)((const char*)(gbase) + (voff)[_i]), (LAS unsigned*)(lds + (bufoff) + ldsw + _i * 8192), 16, 0, 0); } while (0)
; #define PG8_LDA(dst, b, h) do { _Pragma("unroll") for (int m = 0; m < 4; ++m) _Pragma("unroll") for (int k = 0; k < 2; ++k) dst[m][k] = *(const LAS bf16x8*)(lds + PG8_SA(b, h) + aoff + m * 2048 + k * 1024); } while (0)
; #define PG8_LDB(dst, b, h) do { _Pragma("unroll") for (int n = 0; n < 2; ++n) _Pragma("unroll") for (int k = 0; k < 2; ++k) dst[n][k] = *(const LAS bf16x8*)(lds + PG8_SB(b, h) + boff + n * 2048 + k * 1024); } while (0)
; #define PG8_MMA(ai, bj, At, Bt) do { __builtin_amdgcn_s_setprio(1); _Pragma("unroll") for (int m = 0; m < 4; ++m) _Pragma("unroll") for (int n = 0; n < 2; ++n) _Pragma("unroll") for (int k = 0; k < 2; ++k) \
;         acc[ai][bj][m][n] = __builtin_amdgcn_mfma_f32_16x16x32_bf16(Bt[n][k], At[m][k], acc[ai][bj][m][n], 0, 0, 0); __builtin_amdgcn_s_setprio(0); } while (0)
; #define PG8_WAIT_V(n) asm volatile("s_waitcnt vmcnt(" #n ")" ::: "memory")
; #define PG8_WAIT_L(n) asm volatile("s_waitcnt lgkmcnt(" #n ")" ::: "memory")
; #define PG8_BAR __builtin_amdgcn_s_barrier()
; #define PG8_SCHED __builtin_amdgcn_sched_barrier(0)
; template <class Epi, class Sched>
; __device__ __forceinline__ void gemm_phase(LAS unsigned char* lds_in, const int lda, const int ldb, const Sched& S, const Epi& E, const int WID) {
;     ...
;             PG8_WAIT_V(6); PG8_BAR; PG8_MMA(1, 1, At, B1); PG8_BAR;
;             PG8_LDB(B0, 1, 0); PG8_SCHED; PG8_LDA(At, 1, 0); PG8_STAGE(PG8_SA(0, 1), a2 + hstepA, voffA);
;             PG8_WAIT_L(8); PG8_BAR; PG8_WAIT_L(0); PG8_MMA(0, 0, At, B0); PG8_BAR; PG8_SCHED;
;             PG8_LDB(B1, 1, 1); PG8_STAGE(PG8_SB(1, 0), b3, voffB);
;             PG8_BAR; PG8_WAIT_L(0); PG8_MMA(0, 1, At, B1); PG8_BAR;
;             PG8_LDA(At, 1, 1); PG8_STAGE(PG8_SA(1, 0), a3, voffA);
;             PG8_BAR; PG8_WAIT_L(0); PG8_MMA(1, 0, At, B0); PG8_BAR; PG8_SCHED;
	s_setprio 1
	v_mfma_f32_16x16x32_bf16 v[30:33], v[194:197], v[162:165], v[30:33]
	v_mfma_f32_16x16x32_bf16 v[26:29], v[202:205], v[162:165], v[26:29]
	v_mfma_f32_16x16x32_bf16 v[22:25], v[194:197], v[170:173], v[22:25]
	v_mfma_f32_16x16x32_bf16 v[18:21], v[202:205], v[170:173], v[18:21]
	v_mfma_f32_16x16x32_bf16 v[14:17], v[194:197], v[178:181], v[14:17]
	v_mfma_f32_16x16x32_bf16 v[10:13], v[202:205], v[178:181], v[10:13]
	v_mfma_f32_16x16x32_bf16 v[6:9], v[194:197], v[186:189], v[6:9]
	v_mfma_f32_16x16x32_bf16 v[2:5], v[202:205], v[186:189], v[2:5]
	v_mfma_f32_16x16x32_bf16 v[30:33], v[198:201], v[166:169], v[30:33]
	v_mfma_f32_16x16x32_bf16 v[26:29], v[206:209], v[166:169], v[26:29]
	v_mfma_f32_16x16x32_bf16 v[22:25], v[198:201], v[174:177], v[22:25]
	v_mfma_f32_16x16x32_bf16 v[18:21], v[206:209], v[174:177], v[18:21]
	v_mfma_f32_16x16x32_bf16 v[14:17], v[198:201], v[182:185], v[14:17]
	v_mfma_f32_16x16x32_bf16 v[10:13], v[206:209], v[182:185], v[10:13]
	v_mfma_f32_16x16x32_bf16 v[6:9], v[198:201], v[190:193], v[6:9]
	v_mfma_f32_16x16x32_bf16 v[2:5], v[206:209], v[190:193], v[2:5]
	s_setprio 0
	v_add_u32_e32 v153, s50, v150
	s_barrier
	ds_read_b128 v[142:145], v153
	ds_read_b128 v[146:149], v153 offset:1024
	ds_read_b128 v[154:157], v153 offset:2048
	ds_read_b128 v[158:161], v153 offset:3072
	s_add_u32 s18, s18, 0x80000
	s_addc_u32 s19, s19, 0
	s_mov_b32 m0, s48
	ds_read_b128 v[162:165], v152 offset:32768
	ds_read_b128 v[166:169], v152 offset:33792
	ds_read_b128 v[170:173], v152 offset:34816
	ds_read_b128 v[174:177], v152 offset:35840
	ds_read_b128 v[178:181], v152 offset:36864
	ds_read_b128 v[182:185], v152 offset:37888
	ds_read_b128 v[186:189], v152 offset:38912
	ds_read_b128 v[190:193], v152 offset:39936
	global_load_lds_dwordx4 v130, s[18:19]
	s_mov_b32 m0, s49
	s_nop 0
	global_load_lds_dwordx4 v134, s[18:19]
	s_waitcnt lgkmcnt(8)
	s_barrier
	s_waitcnt lgkmcnt(0)
	s_setprio 1
	s_waitcnt lgkmcnt(0)
	v_mfma_f32_16x16x32_bf16 v[126:129], v[142:145], v[162:165], v[126:129]
	v_mfma_f32_16x16x32_bf16 v[122:125], v[154:157], v[162:165], v[122:125]
	v_mfma_f32_16x16x32_bf16 v[118:121], v[142:145], v[170:173], v[118:121]
	v_mfma_f32_16x16x32_bf16 v[114:117], v[154:157], v[170:173], v[114:117]
	v_mfma_f32_16x16x32_bf16 v[110:113], v[142:145], v[178:181], v[110:113]
	v_mfma_f32_16x16x32_bf16 v[106:109], v[154:157], v[178:181], v[106:109]
	v_mfma_f32_16x16x32_bf16 v[102:105], v[142:145], v[186:189], v[102:105]
	v_mfma_f32_16x16x32_bf16 v[98:101], v[154:157], v[186:189], v[98:101]
	v_mfma_f32_16x16x32_bf16 v[126:129], v[146:149], v[166:169], v[126:129]
	v_mfma_f32_16x16x32_bf16 v[122:125], v[158:161], v[166:169], v[122:125]
	v_mfma_f32_16x16x32_bf16 v[118:121], v[146:149], v[174:177], v[118:121]
	v_mfma_f32_16x16x32_bf16 v[114:117], v[158:161], v[174:177], v[114:117]
	v_mfma_f32_16x16x32_bf16 v[110:113], v[146:149], v[182:185], v[110:113]
	v_mfma_f32_16x16x32_bf16 v[106:109], v[158:161], v[182:185], v[106:109]
	v_mfma_f32_16x16x32_bf16 v[102:105], v[146:149], v[190:193], v[102:105]
	v_mfma_f32_16x16x32_bf16 v[98:101], v[158:161], v[190:193], v[98:101]
	s_setprio 0
	s_barrier
	s_mov_b32 m0, s51
	v_add_u32_e32 v153, s90, v150
	s_add_u32 s100, s16, 0x80
	s_addc_u32 s101, s17, 0
	ds_read_b128 v[194:197], v153
	ds_read_b128 v[198:201], v153 offset:1024
	ds_read_b128 v[202:205], v153 offset:2048
	ds_read_b128 v[206:209], v153 offset:3072
	global_load_lds_dwordx4 v132, s[100:101]
	s_add_u32 s100, s16, 0x80
	s_addc_u32 s101, s17, 0
	s_mov_b32 m0, s65
	s_nop 0
	global_load_lds_dwordx4 v136, s[100:101]
	s_barrier
	s_waitcnt lgkmcnt(0)
	s_setprio 1
	s_waitcnt lgkmcnt(0)
	v_mfma_f32_16x16x32_bf16 v[70:73], v[194:197], v[162:165], v[70:73]
	v_mfma_f32_16x16x32_bf16 v[62:65], v[202:205], v[162:165], v[62:65]
	v_mfma_f32_16x16x32_bf16 v[54:57], v[194:197], v[170:173], v[54:57]
	v_mfma_f32_16x16x32_bf16 v[50:53], v[202:205], v[170:173], v[50:53]
	v_mfma_f32_16x16x32_bf16 v[46:49], v[194:197], v[178:181], v[46:49]
	v_mfma_f32_16x16x32_bf16 v[42:45], v[202:205], v[178:181], v[42:45]
	v_mfma_f32_16x16x32_bf16 v[38:41], v[194:197], v[186:189], v[38:41]
	v_mfma_f32_16x16x32_bf16 v[34:37], v[202:205], v[186:189], v[34:37]
	v_mfma_f32_16x16x32_bf16 v[70:73], v[198:201], v[166:169], v[70:73]
	v_mfma_f32_16x16x32_bf16 v[62:65], v[206:209], v[166:169], v[62:65]
	v_mfma_f32_16x16x32_bf16 v[54:57], v[198:201], v[174:177], v[54:57]
	v_mfma_f32_16x16x32_bf16 v[50:53], v[206:209], v[174:177], v[50:53]
	v_mfma_f32_16x16x32_bf16 v[46:49], v[198:201], v[182:185], v[46:49]
	v_mfma_f32_16x16x32_bf16 v[42:45], v[206:209], v[182:185], v[42:45]
	v_mfma_f32_16x16x32_bf16 v[38:41], v[198:201], v[190:193], v[38:41]
	v_mfma_f32_16x16x32_bf16 v[34:37], v[206:209], v[190:193], v[34:37]
	s_setprio 0
	s_mov_b32 m0, s78
	s_add_u32 s100, s18, 0xfff80080
	s_addc_u32 s101, s19, -1
	s_barrier
; #define PG8_STAGE(bufoff, gbase, voff) do { _Pragma("unroll") for (int _i = 0; _i < 2; ++_i) \
;         __builtin_amdgcn_global_load_lds((const unsigned*)((const char*)(gbase) + (voff)[_i]), (LAS unsigned*)(lds + (bufoff) + ldsw + _i * 8192), 16, 0, 0); } while (0)
; #define PG8_LDA(dst, b, h) do { _Pragma("unroll") for (int m = 0; m < 4; ++m) _Pragma("unroll") for (int k = 0; k < 2; ++k) dst[m][k] = *(const LAS bf16x8*)(lds + PG8_SA(b, h) + aoff + m * 2048 + k * 1024); } while (0)
; #define PG8_MMA(ai, bj, At, Bt) do { __builtin_amdgcn_s_setprio(1); _Pragma("unroll") for (int m = 0; m < 4; ++m) _Pragma("unroll") for (int n = 0; n < 2; ++n) _Pragma("unroll") for (int k = 0; k < 2; ++k) \
;         acc[ai][bj][m][n] = __builtin_amdgcn_mfma_f32_16x16x32_bf16(Bt[n][k], At[m][k], acc[ai][bj][m][n], 0, 0, 0); __builtin_amdgcn_s_setprio(0); } while (0)
; #define PG8_WAIT_V(n) asm volatile("s_waitcnt vmcnt(" #n ")" ::: "memory")
; #define PG8_WAIT_L(n) asm volatile("s_waitcnt lgkmcnt(" #n ")" ::: "memory")
; #define PG8_BAR __builtin_amdgcn_s_barrier()
; #define PG8_SCHED __builtin_amdgcn_sched_barrier(0)
; template <class Epi, class Sched>
; __device__ __forceinline__ void gemm_phase(LAS unsigned char* lds_in, const int lda, const int ldb, const Sched& S, const Epi& E, const int WID) {
;     ...
;             PG8_LDA(At, 1, 1); PG8_STAGE(PG8_SA(1, 0), a3, voffA);
;             PG8_BAR; PG8_WAIT_L(0); PG8_MMA(1, 0, At, B0); PG8_BAR; PG8_SCHED;
;             PG8_STAGE(PG8_SB(1, 1), b3 + hstepB, voffB);
;             PG8_WAIT_V(6); PG8_BAR; PG8_MMA(1, 1, At, B1); PG8_BAR;
;     __device__ __forceinline__ void operator()(const AccT& acc, const Unit& u, int wr, int wc, int fr, int fq) const {
;         const int part = u.pm >> 3, s0 = (u.pm & 7) * 256 + wr * 64 + fr, pb = u.aux;
; #pragma unroll
;         for (int bj = 0; bj < 2; ++bj) {
;             const int dcol = (u.pn * 2 + bj) * 256 + part * 128 + wc * 32 + 8 * fq;
; #pragma unroll
;             for (int ai = 0; ai < 2; ++ai)
; #pragma unroll
;                 for (int m = 0; m < 4; ++m) {
;                     const size_t tok = (size_t)pb * 2048 + s0 + ai * 128 + m * 16;
;                     bf16_t* dst = sample ? (E + tok * 1024 + dcol) : (X + tok * XW + dcol);
	ds_read_b128 v[162:165], v152 offset:49152
	ds_read_b128 v[166:169], v152 offset:50176
	ds_read_b128 v[170:173], v152 offset:51200
	ds_read_b128 v[174:177], v152 offset:52224
	ds_read_b128 v[178:181], v152 offset:53248
	ds_read_b128 v[182:185], v152 offset:54272
	ds_read_b128 v[186:189], v152 offset:55296
	ds_read_b128 v[190:193], v152 offset:56320
	global_load_lds_dwordx4 v130, s[100:101]
	s_add_u32 s100, s18, 0xfff80080
	s_addc_u32 s101, s19, -1
	s_mov_b32 m0, s79
	s_nop 0
	global_load_lds_dwordx4 v134, s[100:101]
	s_barrier
	s_waitcnt lgkmcnt(0)
	s_setprio 1
	s_waitcnt lgkmcnt(0)
	v_mfma_f32_16x16x32_bf16 v[94:97], v[142:145], v[162:165], v[94:97]
	v_mfma_f32_16x16x32_bf16 v[90:93], v[154:157], v[162:165], v[90:93]
	v_mfma_f32_16x16x32_bf16 v[86:89], v[142:145], v[170:173], v[86:89]
	v_mfma_f32_16x16x32_bf16 v[82:85], v[154:157], v[170:173], v[82:85]
	v_mfma_f32_16x16x32_bf16 v[78:81], v[142:145], v[178:181], v[78:81]
	v_mfma_f32_16x16x32_bf16 v[74:77], v[154:157], v[178:181], v[74:77]
	v_mfma_f32_16x16x32_bf16 v[66:69], v[142:145], v[186:189], v[66:69]
	v_mfma_f32_16x16x32_bf16 v[58:61], v[154:157], v[186:189], v[58:61]
	v_mfma_f32_16x16x32_bf16 v[94:97], v[146:149], v[166:169], v[94:97]
	v_mfma_f32_16x16x32_bf16 v[90:93], v[158:161], v[166:169], v[90:93]
	v_mfma_f32_16x16x32_bf16 v[86:89], v[146:149], v[174:177], v[86:89]
	v_mfma_f32_16x16x32_bf16 v[82:85], v[158:161], v[174:177], v[82:85]
	v_mfma_f32_16x16x32_bf16 v[78:81], v[146:149], v[182:185], v[78:81]
	v_mfma_f32_16x16x32_bf16 v[74:77], v[158:161], v[182:185], v[74:77]
	v_mfma_f32_16x16x32_bf16 v[66:69], v[146:149], v[190:193], v[66:69]
	v_mfma_f32_16x16x32_bf16 v[58:61], v[158:161], v[190:193], v[58:61]
	s_setprio 0
	s_barrier
	s_add_u32 s16, s16, 0x400080
	s_addc_u32 s17, s17, 0
	s_mov_b32 m0, s91
	s_nop 0
	global_load_lds_dwordx4 v132, s[16:17]
	s_mov_b32 m0, s92
	s_nop 0
	global_load_lds_dwordx4 v136, s[16:17]
	s_waitcnt vmcnt(6)
	s_barrier
	s_setprio 1
	v_mfma_f32_16x16x32_bf16 v[30:33], v[194:197], v[162:165], v[30:33]
	v_mfma_f32_16x16x32_bf16 v[26:29], v[202:205], v[162:165], v[26:29]
	v_mfma_f32_16x16x32_bf16 v[22:25], v[194:197], v[170:173], v[22:25]
	v_mfma_f32_16x16x32_bf16 v[18:21], v[202:205], v[170:173], v[18:21]
	v_mfma_f32_16x16x32_bf16 v[14:17], v[194:197], v[178:181], v[14:17]
	v_mfma_f32_16x16x32_bf16 v[10:13], v[202:205], v[178:181], v[10:13]
	v_mfma_f32_16x16x32_bf16 v[6:9], v[194:197], v[186:189], v[6:9]
	v_mfma_f32_16x16x32_bf16 v[2:5], v[202:205], v[186:189], v[2:5]
	v_mfma_f32_16x16x32_bf16 v[30:33], v[198:201], v[166:169], v[30:33]
	v_mfma_f32_16x16x32_bf16 v[26:29], v[206:209], v[166:169], v[26:29]
	v_mfma_f32_16x16x32_bf16 v[22:25], v[198:201], v[174:177], v[22:25]
	v_mfma_f32_16x16x32_bf16 v[18:21], v[206:209], v[174:177], v[18:21]
	v_mfma_f32_16x16x32_bf16 v[14:17], v[198:201], v[182:185], v[14:17]
	v_mfma_f32_16x16x32_bf16 v[10:13], v[206:209], v[182:185], v[10:13]
	v_mfma_f32_16x16x32_bf16 v[6:9], v[198:201], v[190:193], v[6:9]
	v_mfma_f32_16x16x32_bf16 v[2:5], v[206:209], v[190:193], v[2:5]
	s_setprio 0
	s_add_i32 vcc_lo, vcc_lo, 2
	s_add_u32 s14, s14, 0x100
	s_addc_u32 s15, s15, 0
	s_add_u32 s7, s7, 0x100
	s_addc_u32 s13, s13, 0
	s_cmp_gt_u32 vcc_lo, 29
	s_barrier
	s_cbranch_scc0 .LBB0_922
	s_lshl_b32 s7, s97, 8
	s_and_b32 s7, s7, 0x700
	v_add_u32_e32 v142, s7, v1
	s_ashr_i32 s13, s12, 31
	s_lshl_b64 s[12:13], s[12:13], 11
	v_ashrrev_i32_e32 v143, 31, v142
	v_lshl_add_u64 v[144:145], s[12:13], 0, v[142:143]
	s_mov_b64 s[12:13], -1
	s_and_b64 vcc, exec, s[4:5]
	s_cbranch_vccz .LBB0_925
	v_mov_b64_e32 v[142:143], s[42:43]
	v_mad_u64_u32 v[148:149], s[12:13], v144, s57, v[142:143]
	v_mad_i32_i24 v149, v145, s57, v149
	s_mov_b64 s[12:13], 0

; #define PG8_STAGE(bufoff, gbase, voff) do { _Pragma("unroll") for (int _i = 0; _i < 2; ++_i) \
;         __builtin_amdgcn_global_load_lds((const unsigned*)((const char*)(gbase) + (voff)[_i]), (LAS unsigned*)(lds + (bufoff) + ldsw + _i * 8192), 16, 0, 0); } while (0)
; #define PG8_LDA(dst, b, h) do { _Pragma("unroll") for (int m = 0; m < 4; ++m) _Pragma("unroll") for (int k = 0; k < 2; ++k) dst[m][k] = *(const LAS bf16x8*)(lds + PG8_SA(b, h) + aoff + m * 2048 + k * 1024); } while (0)
; #define PG8_LDB(dst, b, h) do { _Pragma("unroll") for (int n = 0; n < 2; ++n) _Pragma("unroll") for (int k = 0; k < 2; ++k) dst[n][k] = *(const LAS bf16x8*)(lds + PG8_SB(b, h) + boff + n * 2048 + k * 1024); } while (0)
; #define PG8_MMA(ai, bj, At, Bt) do { __builtin_amdgcn_s_setprio(1); _Pragma("unroll") for (int m = 0; m < 4; ++m) _Pragma("unroll") for (int n = 0; n < 2; ++n) _Pragma("unroll") for (int k = 0; k < 2; ++k) \
;         acc[ai][bj][m][n] = __builtin_amdgcn_mfma_f32_16x16x32_bf16(Bt[n][k], At[m][k], acc[ai][bj][m][n], 0, 0, 0); __builtin_amdgcn_s_setprio(0); } while (0)
; #define PG8_WAIT_V(n) asm volatile("s_waitcnt vmcnt(" #n ")" ::: "memory")
; #define PG8_WAIT_L(n) asm volatile("s_waitcnt lgkmcnt(" #n ")" ::: "memory")
; #define PG8_BAR __builtin_amdgcn_s_barrier()
; #define PG8_SCHED __builtin_amdgcn_sched_barrier(0)
; template <class Epi, class Sched>
; __device__ __forceinline__ void gemm_phase(LAS unsigned char* lds_in, const int lda, const int ldb, const Sched& S, const Epi& E, const int WID) {
;     ...
;             PG8_LDB(B0, 0, 0); PG8_SCHED; PG8_LDA(At, 0, 0); PG8_STAGE(PG8_SA(1, 1), a1 + hstepA, voffA);
;             PG8_WAIT_L(8); PG8_BAR; PG8_WAIT_L(0); PG8_MMA(0, 0, At, B0); PG8_BAR; PG8_SCHED;
;             PG8_LDB(B1, 0, 1); PG8_STAGE(PG8_SB(0, 0), b2, voffB);
;             PG8_BAR; PG8_WAIT_L(0); PG8_MMA(0, 1, At, B1); PG8_BAR;
;             PG8_LDA(At, 0, 1); PG8_STAGE(PG8_SA(0, 0), a2, voffA);
;             PG8_BAR; PG8_WAIT_L(0); PG8_MMA(1, 0, At, B0); PG8_BAR; PG8_SCHED;
;             PG8_STAGE(PG8_SB(0, 1), b2 + hstepB, voffB);
;             PG8_WAIT_V(6); PG8_BAR; PG8_MMA(1, 1, At, B1); PG8_BAR;
.LBB0_1040:
	v_add_u32_e32 v142, s3, v174
	ds_read_b128 v[130:133], v142
	ds_read_b128 v[134:137], v142 offset:1024
	ds_read_b128 v[138:141], v142 offset:2048
	ds_read_b128 v[142:145], v142 offset:3072
	s_add_u32 s20, s18, 0xfff80080
	s_addc_u32 s21, s19, -1
	s_cmp_eq_u32 s70, 28
	s_cselect_b32 s23, s13, s21
	s_cselect_b32 s22, s12, s20
	s_cselect_b32 s21, s15, s11
	s_cselect_b32 s20, s14, s1
	s_add_i32 m0, s46, 0xc000
	ds_read_b128 v[158:161], v176
	ds_read_b128 v[162:165], v176 offset:1024
	ds_read_b128 v[166:169], v176 offset:2048
	ds_read_b128 v[170:173], v176 offset:3072
	ds_read_b128 v[178:181], v176 offset:4096
	ds_read_b128 v[182:185], v176 offset:5120
	ds_read_b128 v[186:189], v176 offset:6144
	ds_read_b128 v[190:193], v176 offset:7168
	global_load_lds_dwordx4 v154, s[18:19]
	s_add_i32 m0, s46, 0xe000
	s_nop 0
	global_load_lds_dwordx4 v156, s[18:19]
	s_waitcnt lgkmcnt(8)
	s_barrier
	s_waitcnt lgkmcnt(0)
	s_setprio 1
	s_waitcnt lgkmcnt(0)
	v_mfma_f32_16x16x32_bf16 v[126:129], v[130:133], v[158:161], v[126:129]
	v_mfma_f32_16x16x32_bf16 v[122:125], v[138:141], v[158:161], v[122:125]
	v_mfma_f32_16x16x32_bf16 v[118:121], v[130:133], v[166:169], v[118:121]
	v_mfma_f32_16x16x32_bf16 v[114:117], v[138:141], v[166:169], v[114:117]
	v_mfma_f32_16x16x32_bf16 v[110:113], v[130:133], v[178:181], v[110:113]
	v_mfma_f32_16x16x32_bf16 v[106:109], v[138:141], v[178:181], v[106:109]
	v_mfma_f32_16x16x32_bf16 v[102:105], v[130:133], v[186:189], v[102:105]
	v_mfma_f32_16x16x32_bf16 v[98:101], v[138:141], v[186:189], v[98:101]
	v_mfma_f32_16x16x32_bf16 v[126:129], v[134:137], v[162:165], v[126:129]
	v_mfma_f32_16x16x32_bf16 v[122:125], v[142:145], v[162:165], v[122:125]
	v_mfma_f32_16x16x32_bf16 v[118:121], v[134:137], v[170:173], v[118:121]
	v_mfma_f32_16x16x32_bf16 v[114:117], v[142:145], v[170:173], v[114:117]
	v_mfma_f32_16x16x32_bf16 v[110:113], v[134:137], v[182:185], v[110:113]
	v_mfma_f32_16x16x32_bf16 v[106:109], v[142:145], v[182:185], v[106:109]
	v_mfma_f32_16x16x32_bf16 v[102:105], v[134:137], v[190:193], v[102:105]
	v_mfma_f32_16x16x32_bf16 v[98:101], v[142:145], v[190:193], v[98:101]
	s_setprio 0
	s_barrier
	s_mov_b32 m0, s17
	v_add_u32_e32 v177, s48, v174
	ds_read_b128 v[194:197], v177
	ds_read_b128 v[198:201], v177 offset:1024
	ds_read_b128 v[202:205], v177 offset:2048
	ds_read_b128 v[206:209], v177 offset:3072
	global_load_lds_dwordx4 v148, s[20:21]
	s_mov_b32 m0, s35
	s_nop 0
	global_load_lds_dwordx4 v152, s[20:21]
	s_barrier
	s_waitcnt lgkmcnt(0)
	s_setprio 1
	s_waitcnt lgkmcnt(0)
	v_mfma_f32_16x16x32_bf16 v[62:65], v[194:197], v[158:161], v[62:65]
	v_mfma_f32_16x16x32_bf16 v[58:61], v[202:205], v[158:161], v[58:61]
	v_mfma_f32_16x16x32_bf16 v[54:57], v[194:197], v[166:169], v[54:57]
	v_mfma_f32_16x16x32_bf16 v[50:53], v[202:205], v[166:169], v[50:53]
	v_mfma_f32_16x16x32_bf16 v[46:49], v[194:197], v[178:181], v[46:49]
	v_mfma_f32_16x16x32_bf16 v[42:45], v[202:205], v[178:181], v[42:45]
	v_mfma_f32_16x16x32_bf16 v[38:41], v[194:197], v[186:189], v[38:41]
	v_mfma_f32_16x16x32_bf16 v[34:37], v[202:205], v[186:189], v[34:37]
	v_mfma_f32_16x16x32_bf16 v[62:65], v[198:201], v[162:165], v[62:65]
	v_mfma_f32_16x16x32_bf16 v[58:61], v[206:209], v[162:165], v[58:61]
	v_mfma_f32_16x16x32_bf16 v[54:57], v[198:201], v[170:173], v[54:57]
	v_mfma_f32_16x16x32_bf16 v[50:53], v[206:209], v[170:173], v[50:53]
	v_mfma_f32_16x16x32_bf16 v[46:49], v[198:201], v[182:185], v[46:49]
	v_mfma_f32_16x16x32_bf16 v[42:45], v[206:209], v[182:185], v[42:45]
	v_mfma_f32_16x16x32_bf16 v[38:41], v[198:201], v[190:193], v[38:41]
	v_mfma_f32_16x16x32_bf16 v[34:37], v[206:209], v[190:193], v[34:37]
	s_setprio 0
	s_mov_b32 m0, s46
	s_barrier
	ds_read_b128 v[158:161], v176 offset:16384
	ds_read_b128 v[162:165], v176 offset:17408
	ds_read_b128 v[166:169], v176 offset:18432
	ds_read_b128 v[170:173], v176 offset:19456
	ds_read_b128 v[178:181], v176 offset:20480
	ds_read_b128 v[182:185], v176 offset:21504
	ds_read_b128 v[186:189], v176 offset:22528
	ds_read_b128 v[190:193], v176 offset:23552
	global_load_lds_dwordx4 v146, s[22:23]
	s_mov_b32 m0, s47
	s_nop 0
	global_load_lds_dwordx4 v150, s[22:23]
	s_barrier
	s_waitcnt lgkmcnt(0)
	s_setprio 1
	s_waitcnt lgkmcnt(0)
	v_mfma_f32_16x16x32_bf16 v[94:97], v[130:133], v[158:161], v[94:97]
	v_mfma_f32_16x16x32_bf16 v[90:93], v[138:141], v[158:161], v[90:93]
	v_mfma_f32_16x16x32_bf16 v[86:89], v[130:133], v[166:169], v[86:89]
	v_mfma_f32_16x16x32_bf16 v[82:85], v[138:141], v[166:169], v[82:85]
	v_mfma_f32_16x16x32_bf16 v[78:81], v[130:133], v[178:181], v[78:81]
	v_mfma_f32_16x16x32_bf16 v[74:77], v[138:141], v[178:181], v[74:77]
	v_mfma_f32_16x16x32_bf16 v[70:73], v[130:133], v[186:189], v[70:73]
	v_mfma_f32_16x16x32_bf16 v[66:69], v[138:141], v[186:189], v[66:69]
	v_mfma_f32_16x16x32_bf16 v[94:97], v[134:137], v[162:165], v[94:97]
	v_mfma_f32_16x16x32_bf16 v[90:93], v[142:145], v[162:165], v[90:93]
	v_mfma_f32_16x16x32_bf16 v[86:89], v[134:137], v[170:173], v[86:89]
	v_mfma_f32_16x16x32_bf16 v[82:85], v[142:145], v[170:173], v[82:85]
	v_mfma_f32_16x16x32_bf16 v[78:81], v[134:137], v[182:185], v[78:81]
	v_mfma_f32_16x16x32_bf16 v[74:77], v[142:145], v[182:185], v[74:77]
	v_mfma_f32_16x16x32_bf16 v[70:73], v[134:137], v[190:193], v[70:73]
	v_mfma_f32_16x16x32_bf16 v[66:69], v[142:145], v[190:193], v[66:69]
	s_setprio 0
	s_barrier
	s_add_u32 s96, s20, 0x80000
	s_addc_u32 s97, s21, 0
	s_mov_b32 m0, s49
	s_nop 0
	global_load_lds_dwordx4 v148, s[96:97]
	s_mov_b32 m0, s50
	s_nop 0
	global_load_lds_dwordx4 v152, s[96:97]
	s_waitcnt vmcnt(6)
	s_barrier
; #define PG8_STAGE(bufoff, gbase, voff) do { _Pragma("unroll") for (int _i = 0; _i < 2; ++_i) \
;         __builtin_amdgcn_global_load_lds((const unsigned*)((const char*)(gbase) + (voff)[_i]), (LAS unsigned*)(lds + (bufoff) + ldsw + _i * 8192), 16, 0, 0); } while (0)
; #define PG8_LDA(dst, b, h) do { _Pragma("unroll") for (int m = 0; m < 4; ++m) _Pragma("unroll") for (int k = 0; k < 2; ++k) dst[m][k] = *(const LAS bf16x8*)(lds + PG8_SA(b, h) + aoff + m * 2048 + k * 1024); } while (0)
; #define PG8_LDB(dst, b, h) do { _Pragma("unroll") for (int n = 0; n < 2; ++n) _Pragma("unroll") for (int k = 0; k < 2; ++k) dst[n][k] = *(const LAS bf16x8*)(lds + PG8_SB(b, h) + boff + n * 2048 + k * 1024); } while (0)
; #define PG8_MMA(ai, bj, At, Bt) do { __builtin_amdgcn_s_setprio(1); _Pragma("unroll") for (int m = 0; m < 4; ++m) _Pragma("unroll") for (int n = 0; n < 2; ++n) _Pragma("unroll") for (int k = 0; k < 2; ++k) \
;         acc[ai][bj][m][n] = __builtin_amdgcn_mfma_f32_16x16x32_bf16(Bt[n][k], At[m][k], acc[ai][bj][m][n], 0, 0, 0); __builtin_amdgcn_s_setprio(0); } while (0)
; #define PG8_WAIT_V(n) asm volatile("s_waitcnt vmcnt(" #n ")" ::: "memory")
; #define PG8_WAIT_L(n) asm volatile("s_waitcnt lgkmcnt(" #n ")" ::: "memory")
; #define PG8_BAR __builtin_amdgcn_s_barrier()
; #define PG8_SCHED __builtin_amdgcn_sched_barrier(0)
; template <class Epi, class Sched>
; __device__ __forceinline__ void gemm_phase(LAS unsigned char* lds_in, const int lda, const int ldb, const Sched& S, const Epi& E, const int WID) {
;     ...
;             PG8_WAIT_V(6); PG8_BAR; PG8_MMA(1, 1, At, B1); PG8_BAR;
;             PG8_LDB(B0, 1, 0); PG8_SCHED; PG8_LDA(At, 1, 0); PG8_STAGE(PG8_SA(0, 1), a2 + hstepA, voffA);
;             PG8_WAIT_L(8); PG8_BAR; PG8_WAIT_L(0); PG8_MMA(0, 0, At, B0); PG8_BAR; PG8_SCHED;
;             PG8_LDB(B1, 1, 1); PG8_STAGE(PG8_SB(1, 0), b3, voffB);
;             PG8_BAR; PG8_WAIT_L(0); PG8_MMA(0, 1, At, B1); PG8_BAR;
;             PG8_LDA(At, 1, 1); PG8_STAGE(PG8_SA(1, 0), a3, voffA);
;             PG8_BAR; PG8_WAIT_L(0); PG8_MMA(1, 0, At, B0); PG8_BAR; PG8_SCHED;
	s_setprio 1
	v_mfma_f32_16x16x32_bf16 v[30:33], v[194:197], v[158:161], v[30:33]
	v_mfma_f32_16x16x32_bf16 v[26:29], v[202:205], v[158:161], v[26:29]
	v_mfma_f32_16x16x32_bf16 v[22:25], v[194:197], v[166:169], v[22:25]
	v_mfma_f32_16x16x32_bf16 v[18:21], v[202:205], v[166:169], v[18:21]
	v_mfma_f32_16x16x32_bf16 v[14:17], v[194:197], v[178:181], v[14:17]
	v_mfma_f32_16x16x32_bf16 v[10:13], v[202:205], v[178:181], v[10:13]
	v_mfma_f32_16x16x32_bf16 v[6:9], v[194:197], v[186:189], v[6:9]
	v_mfma_f32_16x16x32_bf16 v[2:5], v[202:205], v[186:189], v[2:5]
	v_mfma_f32_16x16x32_bf16 v[30:33], v[198:201], v[162:165], v[30:33]
	v_mfma_f32_16x16x32_bf16 v[26:29], v[206:209], v[162:165], v[26:29]
	v_mfma_f32_16x16x32_bf16 v[22:25], v[198:201], v[170:173], v[22:25]
	v_mfma_f32_16x16x32_bf16 v[18:21], v[206:209], v[170:173], v[18:21]
	v_mfma_f32_16x16x32_bf16 v[14:17], v[198:201], v[182:185], v[14:17]
	v_mfma_f32_16x16x32_bf16 v[10:13], v[206:209], v[182:185], v[10:13]
	v_mfma_f32_16x16x32_bf16 v[6:9], v[198:201], v[190:193], v[6:9]
	v_mfma_f32_16x16x32_bf16 v[2:5], v[206:209], v[190:193], v[2:5]
	s_setprio 0
	v_add_u32_e32 v142, s78, v174
	s_barrier
	ds_read_b128 v[130:133], v142
	ds_read_b128 v[134:137], v142 offset:1024
	ds_read_b128 v[138:141], v142 offset:2048
	ds_read_b128 v[142:145], v142 offset:3072
	s_add_u32 s22, s22, 0x80000
	s_addc_u32 s23, s23, 0
	s_mov_b32 m0, s51
	ds_read_b128 v[158:161], v176 offset:32768
	ds_read_b128 v[162:165], v176 offset:33792
	ds_read_b128 v[166:169], v176 offset:34816
	ds_read_b128 v[170:173], v176 offset:35840
	ds_read_b128 v[178:181], v176 offset:36864
	ds_read_b128 v[182:185], v176 offset:37888
	ds_read_b128 v[186:189], v176 offset:38912
	ds_read_b128 v[190:193], v176 offset:39936
	global_load_lds_dwordx4 v146, s[22:23]
	s_mov_b32 m0, s65
	s_nop 0
	global_load_lds_dwordx4 v150, s[22:23]
	s_waitcnt lgkmcnt(8)
	s_barrier
	s_waitcnt lgkmcnt(0)
	s_setprio 1
	s_waitcnt lgkmcnt(0)
	v_mfma_f32_16x16x32_bf16 v[126:129], v[130:133], v[158:161], v[126:129]
	v_mfma_f32_16x16x32_bf16 v[122:125], v[138:141], v[158:161], v[122:125]
	v_mfma_f32_16x16x32_bf16 v[118:121], v[130:133], v[166:169], v[118:121]
	v_mfma_f32_16x16x32_bf16 v[114:117], v[138:141], v[166:169], v[114:117]
	v_mfma_f32_16x16x32_bf16 v[110:113], v[130:133], v[178:181], v[110:113]
	v_mfma_f32_16x16x32_bf16 v[106:109], v[138:141], v[178:181], v[106:109]
	v_mfma_f32_16x16x32_bf16 v[102:105], v[130:133], v[186:189], v[102:105]
	v_mfma_f32_16x16x32_bf16 v[98:101], v[138:141], v[186:189], v[98:101]
	v_mfma_f32_16x16x32_bf16 v[126:129], v[134:137], v[162:165], v[126:129]
	v_mfma_f32_16x16x32_bf16 v[122:125], v[142:145], v[162:165], v[122:125]
	v_mfma_f32_16x16x32_bf16 v[118:121], v[134:137], v[170:173], v[118:121]
	v_mfma_f32_16x16x32_bf16 v[114:117], v[142:145], v[170:173], v[114:117]
	v_mfma_f32_16x16x32_bf16 v[110:113], v[134:137], v[182:185], v[110:113]
	v_mfma_f32_16x16x32_bf16 v[106:109], v[142:145], v[182:185], v[106:109]
	v_mfma_f32_16x16x32_bf16 v[102:105], v[134:137], v[190:193], v[102:105]
	v_mfma_f32_16x16x32_bf16 v[98:101], v[142:145], v[190:193], v[98:101]
	s_setprio 0
	s_barrier
	s_mov_b32 m0, s79
	v_add_u32_e32 v177, s90, v174
	s_add_u32 s100, s20, 0x80
	s_addc_u32 s101, s21, 0
	ds_read_b128 v[194:197], v177
	ds_read_b128 v[198:201], v177 offset:1024
	ds_read_b128 v[202:205], v177 offset:2048
	ds_read_b128 v[206:209], v177 offset:3072
	global_load_lds_dwordx4 v148, s[100:101]
	s_add_u32 s100, s20, 0x80
	s_addc_u32 s101, s21, 0
	s_mov_b32 m0, s2
	s_nop 0
	global_load_lds_dwordx4 v152, s[100:101]
	s_barrier
	s_waitcnt lgkmcnt(0)
	s_setprio 1
	s_waitcnt lgkmcnt(0)
	v_mfma_f32_16x16x32_bf16 v[62:65], v[194:197], v[158:161], v[62:65]
	v_mfma_f32_16x16x32_bf16 v[58:61], v[202:205], v[158:161], v[58:61]
	v_mfma_f32_16x16x32_bf16 v[54:57], v[194:197], v[166:169], v[54:57]
	v_mfma_f32_16x16x32_bf16 v[50:53], v[202:205], v[166:169], v[50:53]
	v_mfma_f32_16x16x32_bf16 v[46:49], v[194:197], v[178:181], v[46:49]
	v_mfma_f32_16x16x32_bf16 v[42:45], v[202:205], v[178:181], v[42:45]
	v_mfma_f32_16x16x32_bf16 v[38:41], v[194:197], v[186:189], v[38:41]
	v_mfma_f32_16x16x32_bf16 v[34:37], v[202:205], v[186:189], v[34:37]
	v_mfma_f32_16x16x32_bf16 v[62:65], v[198:201], v[162:165], v[62:65]
	v_mfma_f32_16x16x32_bf16 v[58:61], v[206:209], v[162:165], v[58:61]
	v_mfma_f32_16x16x32_bf16 v[54:57], v[198:201], v[170:173], v[54:57]
	v_mfma_f32_16x16x32_bf16 v[50:53], v[206:209], v[170:173], v[50:53]
	v_mfma_f32_16x16x32_bf16 v[46:49], v[198:201], v[182:185], v[46:49]
	v_mfma_f32_16x16x32_bf16 v[42:45], v[206:209], v[182:185], v[42:45]
	v_mfma_f32_16x16x32_bf16 v[38:41], v[198:201], v[190:193], v[38:41]
	v_mfma_f32_16x16x32_bf16 v[34:37], v[206:209], v[190:193], v[34:37]
	s_setprio 0
	s_mov_b32 m0, s4
	s_add_u32 s100, s22, 0xfff80080
	s_addc_u32 s101, s23, -1
	s_barrier
	ds_read_b128 v[158:161], v176 offset:49152
	ds_read_b128 v[162:165], v176 offset:50176
	ds_read_b128 v[166:169], v176 offset:51200
	ds_read_b128 v[170:173], v176 offset:52224
	ds_read_b128 v[178:181], v176 offset:53248
	ds_read_b128 v[182:185], v176 offset:54272
	ds_read_b128 v[186:189], v176 offset:55296
	ds_read_b128 v[190:193], v176 offset:56320
	global_load_lds_dwordx4 v146, s[100:101]
	s_add_u32 s100, s22, 0xfff80080
	s_addc_u32 s101, s23, -1
	s_mov_b32 m0, s5
	s_nop 0
	global_load_lds_dwordx4 v150, s[100:101]
	s_barrier
; __device__ __forceinline__ float rstd_of(float ss) { return rsqrtf(ss * (1.0f / DM) + EPS); }
; __device__ __forceinline__ u32x4 pack8(const f32x4 a, const f32x4 b) { u32x4 w; w.x = cvt_pk_bf16(a[0], a[1]); w.y = cvt_pk_bf16(a[2], a[3]); w.z = cvt_pk_bf16(b[0], b[1]); w.w = cvt_pk_bf16(b[2], b[3]); return w; }
; #define PG8_STAGE(bufoff, gbase, voff) do { _Pragma("unroll") for (int _i = 0; _i < 2; ++_i) \
;         __builtin_amdgcn_global_load_lds((const unsigned*)((const char*)(gbase) + (voff)[_i]), (LAS unsigned*)(lds + (bufoff) + ldsw + _i * 8192), 16, 0, 0); } while (0)
; #define PG8_MMA(ai, bj, At, Bt) do { __builtin_amdgcn_s_setprio(1); _Pragma("unroll") for (int m = 0; m < 4; ++m) _Pragma("unroll") for (int n = 0; n < 2; ++n) _Pragma("unroll") for (int k = 0; k < 2; ++k) \
;         acc[ai][bj][m][n] = __builtin_amdgcn_mfma_f32_16x16x32_bf16(Bt[n][k], At[m][k], acc[ai][bj][m][n], 0, 0, 0); __builtin_amdgcn_s_setprio(0); } while (0)
; template <class Epi, class Sched>
; __device__ __forceinline__ void gemm_phase(LAS unsigned char* lds_in, const int lda, const int ldb, const Sched& S, const Epi& E, const int WID) {
;     ...
;             PG8_BAR; PG8_WAIT_L(0); PG8_MMA(1, 0, At, B0); PG8_BAR; PG8_SCHED;
;             PG8_STAGE(PG8_SB(1, 1), b3 + hstepB, voffB);
;             PG8_WAIT_V(6); PG8_BAR; PG8_MMA(1, 1, At, B1); PG8_BAR;
;     __device__ __forceinline__ void operator()(const AccT& acc, const Unit& u, int wr, int wc, int fr, int fq) const {
;     ...
;             const bool scat = sample && u.pm < 2;
;             f32x4 rs0[2], rs1[2];
; #pragma unroll
;             for (int bj = 0; bj < 2; ++bj) { const f32x4 a = *(const f32x4*)(SS + col0 + bj * 128), b = *(const f32x4*)(SS + col0 + bj * 128 + 4);
; #pragma unroll
;                 for (int j = 0; j < 4; ++j) { rs0[bj][j] = rstd_of(a[j]); rs1[bj][j] = rstd_of(b[j]); } }
; #pragma unroll
;             for (int ai = 0; ai < 2; ++ai)
; #pragma unroll
;                 for (int m = 0; m < 4; ++m) {
;                     bf16_t* rp = TT + (size_t)(row0 + ai * 128 + m * 16) * CH;
; #pragma unroll
;                     for (int bj = 0; bj < 2; ++bj) {
;                         const u32x4 w = pack8(acc[ai][bj][m][0] * rs0[bj], acc[ai][bj][m][1] * rs1[bj]);
;                         const int tok = col0 + bj * 128;
;                         if (!scat) *(u32x4*)(rp + tok) = w;
	s_waitcnt lgkmcnt(0)
	s_setprio 1
	s_waitcnt lgkmcnt(0)
	v_mfma_f32_16x16x32_bf16 v[94:97], v[130:133], v[158:161], v[94:97]
	v_mfma_f32_16x16x32_bf16 v[90:93], v[138:141], v[158:161], v[90:93]
	v_mfma_f32_16x16x32_bf16 v[86:89], v[130:133], v[166:169], v[86:89]
	v_mfma_f32_16x16x32_bf16 v[82:85], v[138:141], v[166:169], v[82:85]
	v_mfma_f32_16x16x32_bf16 v[78:81], v[130:133], v[178:181], v[78:81]
	v_mfma_f32_16x16x32_bf16 v[74:77], v[138:141], v[178:181], v[74:77]
	v_mfma_f32_16x16x32_bf16 v[70:73], v[130:133], v[186:189], v[70:73]
	v_mfma_f32_16x16x32_bf16 v[66:69], v[138:141], v[186:189], v[66:69]
	v_mfma_f32_16x16x32_bf16 v[94:97], v[134:137], v[162:165], v[94:97]
	v_mfma_f32_16x16x32_bf16 v[90:93], v[142:145], v[162:165], v[90:93]
	v_mfma_f32_16x16x32_bf16 v[86:89], v[134:137], v[170:173], v[86:89]
	v_mfma_f32_16x16x32_bf16 v[82:85], v[142:145], v[170:173], v[82:85]
	v_mfma_f32_16x16x32_bf16 v[78:81], v[134:137], v[182:185], v[78:81]
	v_mfma_f32_16x16x32_bf16 v[74:77], v[142:145], v[182:185], v[74:77]
	v_mfma_f32_16x16x32_bf16 v[70:73], v[134:137], v[190:193], v[70:73]
	v_mfma_f32_16x16x32_bf16 v[66:69], v[142:145], v[190:193], v[66:69]
	s_setprio 0
	s_barrier
	s_add_u32 s20, s20, 0x80080
	s_addc_u32 s21, s21, 0
	s_mov_b32 m0, s91
	s_nop 0
	global_load_lds_dwordx4 v148, s[20:21]
	s_mov_b32 m0, s92
	s_nop 0
	global_load_lds_dwordx4 v152, s[20:21]
	s_waitcnt vmcnt(6)
	s_barrier
	s_setprio 1
	v_mfma_f32_16x16x32_bf16 v[30:33], v[194:197], v[158:161], v[30:33]
	v_mfma_f32_16x16x32_bf16 v[26:29], v[202:205], v[158:161], v[26:29]
	v_mfma_f32_16x16x32_bf16 v[22:25], v[194:197], v[166:169], v[22:25]
	v_mfma_f32_16x16x32_bf16 v[18:21], v[202:205], v[166:169], v[18:21]
	v_mfma_f32_16x16x32_bf16 v[14:17], v[194:197], v[178:181], v[14:17]
	v_mfma_f32_16x16x32_bf16 v[10:13], v[202:205], v[178:181], v[10:13]
	v_mfma_f32_16x16x32_bf16 v[6:9], v[194:197], v[186:189], v[6:9]
	v_mfma_f32_16x16x32_bf16 v[2:5], v[202:205], v[186:189], v[2:5]
	v_mfma_f32_16x16x32_bf16 v[30:33], v[198:201], v[162:165], v[30:33]
	v_mfma_f32_16x16x32_bf16 v[26:29], v[206:209], v[162:165], v[26:29]
	v_mfma_f32_16x16x32_bf16 v[22:25], v[198:201], v[170:173], v[22:25]
	v_mfma_f32_16x16x32_bf16 v[18:21], v[206:209], v[170:173], v[18:21]
	v_mfma_f32_16x16x32_bf16 v[14:17], v[198:201], v[182:185], v[14:17]
	v_mfma_f32_16x16x32_bf16 v[10:13], v[206:209], v[182:185], v[10:13]
	v_mfma_f32_16x16x32_bf16 v[6:9], v[198:201], v[190:193], v[6:9]
	v_mfma_f32_16x16x32_bf16 v[2:5], v[206:209], v[190:193], v[2:5]
	s_setprio 0
	s_add_i32 s70, s70, 2
	s_add_u32 s18, s18, 0x100
	s_addc_u32 s19, s19, 0
	s_add_u32 s1, s1, 0x100
	s_addc_u32 s11, s11, 0
	s_cmp_gt_u32 s70, 29
	s_barrier
	s_cbranch_scc0 .LBB0_1040
	s_lshl_b32 s11, s16, 8
	v_lshl_add_u32 v160, s0, 8, v1
	v_or_b32_e32 v158, s11, v175
	s_cmp_lg_u32 s94, 0
	v_ashrrev_i32_e32 v159, 31, v158
	v_ashrrev_i32_e32 v161, 31, v160
	s_cbranch_scc0 .LBB0_1107
	v_lshl_add_u64 v[134:135], v[158:159], 2, s[76:77]
	global_load_dwordx4 v[130:133], v[134:135], off offset:16
	global_load_dwordx4 v[136:139], v[134:135], off
	s_cmp_lt_i32 s0, 2
	s_mov_b32 s0, 0x358637bd
	v_mov_b64_e32 v[140:141], s[0:1]
	s_cselect_b64 s[18:19], -1, 0
	s_mov_b64 s[20:21], -1
	s_waitcnt vmcnt(0)
	v_pk_fma_f32 v[130:131], v[130:131], s[84:85], v[140:141] op_sel_hi:[1,0,0]
	v_pk_fma_f32 v[136:137], v[136:137], s[84:85], v[140:141] op_sel_hi:[1,0,0]
	s_nop 0
	v_mul_f32_e32 v142, 0x4b800000, v136
	v_cmp_gt_f32_e64 s[0:1], s38, v136
	v_cmp_gt_f32_e32 vcc, s38, v137
	s_nop 0
	v_cndmask_b32_e64 v136, v136, v142, s[0:1]
	v_mul_f32_e32 v142, 0x4b800000, v137
	v_cndmask_b32_e32 v137, v137, v142, vcc
	v_rsq_f32_e32 v136, v136
	v_rsq_f32_e32 v137, v137
	s_nop 0
	v_pk_mul_f32 v[142:143], v[136:137], s[88:89] op_sel_hi:[1,0]
	s_nop 0
	v_cndmask_b32_e64 v142, v136, v142, s[0:1]
	v_mul_f32_e32 v136, 0x4b800000, v130
	v_cmp_gt_f32_e64 s[0:1], s38, v130
	v_cndmask_b32_e32 v143, v137, v143, vcc
	v_cmp_gt_f32_e32 vcc, s38, v131
	v_cndmask_b32_e64 v130, v130, v136, s[0:1]
	v_mul_f32_e32 v136, 0x4b800000, v131
	v_cndmask_b32_e32 v131, v131, v136, vcc
	v_rsq_f32_e32 v130, v130
	v_rsq_f32_e32 v131, v131
	s_nop 0
	v_pk_mul_f32 v[136:137], v[130:131], s[88:89] op_sel_hi:[1,0]
	s_nop 0
	v_cndmask_b32_e32 v145, v131, v137, vcc
	v_cndmask_b32_e64 v144, v130, v136, s[0:1]
	v_pk_fma_f32 v[130:131], v[138:139], s[84:85], v[140:141] op_sel_hi:[1,0,0]
	v_lshlrev_b64 v[138:139], 15, v[160:161]
	v_mul_f32_e32 v136, 0x4b800000, v130
	v_cmp_gt_f32_e64 s[0:1], s38, v130
	v_cmp_gt_f32_e32 vcc, s38, v131
	v_lshl_add_u64 v[166:167], s[86:87], 0, v[138:139]
	v_cndmask_b32_e64 v130, v130, v136, s[0:1]
	v_mul_f32_e32 v136, 0x4b800000, v131
	v_cndmask_b32_e32 v131, v131, v136, vcc
	v_rsq_f32_e32 v130, v130
	v_rsq_f32_e32 v131, v131
	v_pk_mul_f32 v[138:139], v[126:127], v[142:143]
	v_pk_mul_f32 v[168:169], v[122:123], v[144:145]
	v_cvt_pk_bf16_f32 v138, v138, v139
	v_pk_mul_f32 v[136:137], v[130:131], s[88:89] op_sel_hi:[1,0]
	s_nop 0
	v_cndmask_b32_e32 v163, v131, v137, vcc
	v_cndmask_b32_e64 v162, v130, v136, s[0:1]
	v_pk_fma_f32 v[130:131], v[132:133], s[84:85], v[140:141] op_sel_hi:[1,0,0]
	v_pk_mul_f32 v[140:141], v[128:129], v[162:163]
	v_mul_f32_e32 v132, 0x4b800000, v130
	v_cmp_gt_f32_e64 s[0:1], s38, v130
	v_cmp_gt_f32_e32 vcc, s38, v131
	v_cvt_pk_bf16_f32 v139, v140, v141
	v_cvt_pk_bf16_f32 v140, v168, v169
	v_lshl_add_u64 v[168:169], v[158:159], 1, v[166:167]
	v_cndmask_b32_e64 v130, v130, v132, s[0:1]
	v_mul_f32_e32 v132, 0x4b800000, v131
	v_cndmask_b32_e32 v131, v131, v132, vcc
	v_rsq_f32_e32 v130, v130
	v_rsq_f32_e32 v131, v131
	s_nop 0
	v_pk_mul_f32 v[132:133], v[130:131], s[88:89] op_sel_hi:[1,0]
	s_nop 0
	v_cndmask_b32_e32 v165, v131, v133, vcc
	v_cndmask_b32_e64 v164, v130, v132, s[0:1]
	global_load_dwordx4 v[130:133], v[134:135], off offset:528
	s_nop 0
	global_load_dwordx4 v[134:137], v[134:135], off offset:512
	v_readlane_b32 s0, v255, 10
	v_readlane_b32 s1, v255, 11
	s_and_b64 s[0:1], s[0:1], s[18:19]
	s_and_b64 vcc, exec, s[0:1]
	v_pk_mul_f32 v[170:171], v[124:125], v[164:165]
	s_nop 0
	v_cvt_pk_bf16_f32 v141, v170, v171
	s_cbranch_vccnz .LBB0_1044
	s_mov_b64 s[20:21], 0
	global_store_dwordx4 v[168:169], v[138:141], off

; __global__ void __launch_bounds__(NTHREADS, 2) fwd_kernel(Params p) {
	.amdhsa_kernel _Z10fwd_kernel6Params
		.amdhsa_group_segment_fixed_size 0
		.amdhsa_private_segment_fixed_size 0
		.amdhsa_kernarg_size 432
		.amdhsa_user_sgpr_count 2
		.amdhsa_user_sgpr_dispatch_ptr 0
		.amdhsa_user_sgpr_queue_ptr 0
		.amdhsa_user_sgpr_kernarg_segment_ptr 1
		.amdhsa_user_sgpr_dispatch_id 0
		.amdhsa_user_sgpr_kernarg_preload_length 0
		.amdhsa_user_sgpr_kernarg_preload_offset 0
		.amdhsa_user_sgpr_private_segment_size 0
		.amdhsa_uses_dynamic_stack 0
		.amdhsa_enable_private_segment 0
		.amdhsa_system_sgpr_workgroup_id_x 1
		.amdhsa_system_sgpr_workgroup_id_y 0
		.amdhsa_system_sgpr_workgroup_id_z 0
		.amdhsa_system_sgpr_workgroup_info 0
		.amdhsa_system_vgpr_workitem_id 2
		.amdhsa_next_free_vgpr 256
		.amdhsa_next_free_sgpr 102
		.amdhsa_accum_offset 256
		.amdhsa_reserve_vcc 1
		.amdhsa_float_round_mode_32 0
		.amdhsa_float_round_mode_16_64 0
		.amdhsa_float_denorm_mode_32 3
		.amdhsa_float_denorm_mode_16_64 3
		.amdhsa_dx10_clamp 1
		.amdhsa_ieee_mode 1
		.amdhsa_fp16_overflow 0
		.amdhsa_tg_split 0
		.amdhsa_exception_fp_ieee_invalid_op 0
		.amdhsa_exception_fp_denorm_src 0
		.amdhsa_exception_fp_ieee_div_zero 0
		.amdhsa_exception_fp_ieee_overflow 0
		.amdhsa_exception_fp_ieee_underflow 0
		.amdhsa_exception_fp_ieee_inexact 0
		.amdhsa_exception_int_div_zero 0
	.end_amdhsa_kernel

; __global__ void __launch_bounds__(NTHREADS, 2) fwd_kernel(Params p) {
.Lfunc_end0:
	.size	_Z10fwd_kernel6Params, .Lfunc_end0-_Z10fwd_kernel6Params
	.set _Z10fwd_kernel6Params.num_vgpr, 256
	.set _Z10fwd_kernel6Params.num_agpr, 0
	.set _Z10fwd_kernel6Params.numbered_sgpr, 102
	.set _Z10fwd_kernel6Params.num_named_barrier, 0
	.set _Z10fwd_kernel6Params.private_seg_size, 0
	.set _Z10fwd_kernel6Params.uses_vcc, 1
	.set _Z10fwd_kernel6Params.uses_flat_scratch, 0
	.set _Z10fwd_kernel6Params.has_dyn_sized_stack, 0
	.set _Z10fwd_kernel6Params.has_recursion, 0
	.set _Z10fwd_kernel6Params.has_indirect_call, 0

; __global__ void __launch_bounds__(NTHREADS, 2) fwd_kernel(Params p) {
amdhsa.kernels:
  - .agpr_count:     0
    .args:
      - .offset:         0
        .size:           176
        .value_kind:     by_value
      - .offset:         176
        .size:           4
        .value_kind:     hidden_block_count_x
      - .offset:         180
        .size:           4
        .value_kind:     hidden_block_count_y
      - .offset:         184
        .size:           4
        .value_kind:     hidden_block_count_z
      - .offset:         188
        .size:           2
        .value_kind:     hidden_group_size_x
      - .offset:         190
        .size:           2
        .value_kind:     hidden_group_size_y
      - .offset:         192
        .size:           2
        .value_kind:     hidden_group_size_z
      - .offset:         194
        .size:           2
        .value_kind:     hidden_remainder_x
      - .offset:         196
        .size:           2
        .value_kind:     hidden_remainder_y
      - .offset:         198
        .size:           2
        .value_kind:     hidden_remainder_z
      - .offset:         216
        .size:           8
        .value_kind:     hidden_global_offset_x
      - .offset:         224
        .size:           8
        .value_kind:     hidden_global_offset_y
      - .offset:         232
        .size:           8
        .value_kind:     hidden_global_offset_z
      - .offset:         240
        .size:           2
        .value_kind:     hidden_grid_dims
      - .offset:         264
        .size:           8
        .value_kind:     hidden_multigrid_sync_arg
      - .offset:         296
        .size:           4
        .value_kind:     hidden_dynamic_lds_size
    .group_segment_fixed_size: 0
    .kernarg_segment_align: 8
    .kernarg_segment_size: 432
    .language:       OpenCL C
    .language_version:
      - 2
      - 0
    .max_flat_workgroup_size: 512
    .name:           _Z10fwd_kernel6Params
    .private_segment_fixed_size: 0
    .sgpr_count:     108
    .sgpr_spill_count: 77
    .symbol:         _Z10fwd_kernel6Params.kd
    .uniform_work_group_size: 1
    .uses_dynamic_stack: false
    .vgpr_count:     256
    .vgpr_spill_count: 0
    .wavefront_size: 64
